# v77 + K-loops: M0 written straight from literal + wave LDS offset (scratch SGPR chains and duplicate base adds removed)
# baseline (speedup 1.0000x reference)
.LBB0_266:
	s_xor_b64 s[2:3], s[2:3], -1
	s_mov_b32 s34, s74
	s_add_i32 s74, s74, 1
	s_cmp_lt_u32 s34, 5
	s_mov_b64 s[4:5], s[10:11]
	s_mov_b32 s10, s75
	s_cselect_b64 s[14:15], -1, 0
	s_add_i32 s75, s74, s16
	s_mov_b64 s[12:13], s[8:9]
	s_and_b64 s[8:9], s[14:15], exec
	s_cselect_b32 s8, s75, s10
	s_cselect_b32 s10, s6, s6
	s_ashr_i32 s11, s10, 31
	s_lshl_b64 s[10:11], s[10:11], 19
	s_add_u32 s10, s80, s10
	s_addc_u32 s11, s81, s11
	s_and_b64 s[44:45], s[14:15], exec
	s_cselect_b32 s44, s11, s5
	s_cselect_b32 s45, s10, s4
	s_ashr_i32 s9, s8, 31
	s_lshl_b64 s[8:9], s[8:9], 19
	v_readlane_b32 s47, v255, 14
	s_add_u32 s8, s47, s8
	v_readlane_b32 s47, v255, 15
	s_addc_u32 s9, s47, s9
	s_and_b64 s[14:15], s[14:15], exec
	s_cselect_b32 s47, s9, s13
	s_cselect_b32 s55, s8, s12
	s_add_u32 s4, s4, 0x40080
	s_addc_u32 s5, s5, 0
	s_add_u32 s78, s12, 0x100
	s_addc_u32 s79, s13, 0
	s_mov_b32 s85, -2
	s_waitcnt lgkmcnt(0)
	s_add_i32 s86, 0, 0x10000
	v_add_u32_e32 v0, s86, v150
	v_add_u32_e32 v189, 0x10000, v150
	ds_read_b128 v[142:145], v0
	ds_read_b128 v[146:149], v0 offset:1024
	ds_read_b128 v[152:155], v0 offset:2048
	ds_read_b128 v[156:159], v0 offset:3072
	s_add_u32 s12, s4, 0xfffc0080
	s_addc_u32 s13, s5, -1
	s_cmp_eq_u32 s85, 12
	s_cselect_b32 s15, s44, s13
	s_cselect_b32 s14, s45, s12
	s_cselect_b32 s13, s47, s79
	s_cselect_b32 s12, s55, s78
	s_add_i32 m0, s7, 0xc000
	ds_read_b128 v[160:163], v151
	ds_read_b128 v[164:167], v151 offset:1024
	ds_read_b128 v[168:171], v151 offset:2048
	ds_read_b128 v[172:175], v151 offset:3072
	ds_read_b128 v[176:179], v151 offset:4096
	ds_read_b128 v[180:183], v151 offset:5120
	ds_read_b128 v[184:187], v151 offset:6144
	ds_read_b128 v[190:193], v151 offset:7168
	global_load_lds_dwordx4 v138, s[4:5]
	s_add_i32 m0, s7, 0xe000
	s_nop 0
	global_load_lds_dwordx4 v140, s[4:5]
	s_waitcnt lgkmcnt(8)
	s_barrier
	s_waitcnt lgkmcnt(0)
	v_mfma_f32_16x16x32_bf16 v[126:129], v[142:145], v[160:163], 0
	v_mfma_f32_16x16x32_bf16 v[122:125], v[152:155], v[160:163], 0
	v_mfma_f32_16x16x32_bf16 v[110:113], v[142:145], v[168:171], 0
	v_mfma_f32_16x16x32_bf16 v[106:109], v[152:155], v[168:171], 0
	v_mfma_f32_16x16x32_bf16 v[94:97], v[142:145], v[176:179], 0
	v_mfma_f32_16x16x32_bf16 v[90:93], v[152:155], v[176:179], 0
	v_mfma_f32_16x16x32_bf16 v[78:81], v[142:145], v[184:187], 0
	v_mfma_f32_16x16x32_bf16 v[74:77], v[152:155], v[184:187], 0
	v_mfma_f32_16x16x32_bf16 v[126:129], v[146:149], v[164:167], v[126:129]
	v_mfma_f32_16x16x32_bf16 v[122:125], v[156:159], v[164:167], v[122:125]
	v_mfma_f32_16x16x32_bf16 v[110:113], v[146:149], v[172:175], v[110:113]
	v_mfma_f32_16x16x32_bf16 v[106:109], v[156:159], v[172:175], v[106:109]
	v_mfma_f32_16x16x32_bf16 v[94:97], v[146:149], v[180:183], v[94:97]
	v_mfma_f32_16x16x32_bf16 v[90:93], v[156:159], v[180:183], v[90:93]
	v_mfma_f32_16x16x32_bf16 v[78:81], v[146:149], v[190:193], v[78:81]
	v_mfma_f32_16x16x32_bf16 v[74:77], v[156:159], v[190:193], v[74:77]
	s_barrier
	s_add_i32 m0, s22, 0x10000
	ds_read_b128 v[194:197], v189 offset:16384
	ds_read_b128 v[198:201], v189 offset:17408
	ds_read_b128 v[202:205], v189 offset:18432
	ds_read_b128 v[206:209], v189 offset:19456
	global_load_lds_dwordx4 v134, s[12:13]
	s_add_i32 m0, s22, 0x12000
	s_nop 0
	global_load_lds_dwordx4 v130, s[12:13]
	s_barrier
	s_waitcnt lgkmcnt(0)
	v_mfma_f32_16x16x32_bf16 v[118:121], v[194:197], v[160:163], 0
	v_mfma_f32_16x16x32_bf16 v[114:117], v[202:205], v[160:163], 0
	v_mfma_f32_16x16x32_bf16 v[102:105], v[194:197], v[168:171], 0
	v_mfma_f32_16x16x32_bf16 v[98:101], v[202:205], v[168:171], 0
	v_mfma_f32_16x16x32_bf16 v[86:89], v[194:197], v[176:179], 0
	v_mfma_f32_16x16x32_bf16 v[82:85], v[202:205], v[176:179], 0
	v_mfma_f32_16x16x32_bf16 v[70:73], v[194:197], v[184:187], 0
	v_mfma_f32_16x16x32_bf16 v[66:69], v[202:205], v[184:187], 0
	v_mfma_f32_16x16x32_bf16 v[118:121], v[198:201], v[164:167], v[118:121]
	v_mfma_f32_16x16x32_bf16 v[114:117], v[206:209], v[164:167], v[114:117]
	v_mfma_f32_16x16x32_bf16 v[102:105], v[198:201], v[172:175], v[102:105]
	v_mfma_f32_16x16x32_bf16 v[98:101], v[206:209], v[172:175], v[98:101]
	v_mfma_f32_16x16x32_bf16 v[86:89], v[198:201], v[180:183], v[86:89]
	v_mfma_f32_16x16x32_bf16 v[82:85], v[206:209], v[180:183], v[82:85]
	v_mfma_f32_16x16x32_bf16 v[70:73], v[198:201], v[190:193], v[70:73]
	v_mfma_f32_16x16x32_bf16 v[66:69], v[206:209], v[190:193], v[66:69]
	s_mov_b32 m0, s7
	s_mov_b64 s[100:101], s[14:15]
	s_barrier
	ds_read_b128 v[160:163], v151 offset:16384
	ds_read_b128 v[164:167], v151 offset:17408
	ds_read_b128 v[168:171], v151 offset:18432
	ds_read_b128 v[172:175], v151 offset:19456
	ds_read_b128 v[176:179], v151 offset:20480
	ds_read_b128 v[180:183], v151 offset:21504
	ds_read_b128 v[184:187], v151 offset:22528
	ds_read_b128 v[190:193], v151 offset:23552
	global_load_lds_dwordx4 v136, s[100:101]
	s_mov_b32 m0, s23
	s_nop 0
	global_load_lds_dwordx4 v132, s[100:101]
	s_waitcnt vmcnt(10)
	s_barrier
	s_waitcnt lgkmcnt(0)
	v_mfma_f32_16x16x32_bf16 v[62:65], v[142:145], v[160:163], 0
	v_mfma_f32_16x16x32_bf16 v[58:61], v[152:155], v[160:163], 0
	v_mfma_f32_16x16x32_bf16 v[46:49], v[142:145], v[168:171], 0
	v_mfma_f32_16x16x32_bf16 v[42:45], v[152:155], v[168:171], 0
	v_mfma_f32_16x16x32_bf16 v[30:33], v[142:145], v[176:179], 0
	v_mfma_f32_16x16x32_bf16 v[26:29], v[152:155], v[176:179], 0
	v_mfma_f32_16x16x32_bf16 v[14:17], v[142:145], v[184:187], 0
	v_mfma_f32_16x16x32_bf16 v[10:13], v[152:155], v[184:187], 0
	v_mfma_f32_16x16x32_bf16 v[62:65], v[146:149], v[164:167], v[62:65]
	v_mfma_f32_16x16x32_bf16 v[58:61], v[156:159], v[164:167], v[58:61]
	v_mfma_f32_16x16x32_bf16 v[46:49], v[146:149], v[172:175], v[46:49]
	v_mfma_f32_16x16x32_bf16 v[42:45], v[156:159], v[172:175], v[42:45]
	v_mfma_f32_16x16x32_bf16 v[30:33], v[146:149], v[180:183], v[30:33]
	v_mfma_f32_16x16x32_bf16 v[26:29], v[156:159], v[180:183], v[26:29]
	v_mfma_f32_16x16x32_bf16 v[14:17], v[146:149], v[190:193], v[14:17]
	v_mfma_f32_16x16x32_bf16 v[10:13], v[156:159], v[190:193], v[10:13]
	s_barrier
	s_add_u32 s86, s12, 0x40000
	s_addc_u32 s87, s13, 0
	s_add_i32 m0, s22, 0x14000
	s_nop 0
	global_load_lds_dwordx4 v134, s[86:87]
	s_add_i32 m0, s22, 0x16000
	s_nop 0
	global_load_lds_dwordx4 v130, s[86:87]
	ds_read_b128 v[142:145], v189 offset:32768
	ds_read_b128 v[146:149], v189 offset:33792
	ds_read_b128 v[152:155], v189 offset:34816
	ds_read_b128 v[156:159], v189 offset:35840
	s_waitcnt vmcnt(6)
	s_barrier
	v_mfma_f32_16x16x32_bf16 v[54:57], v[194:197], v[160:163], 0
	v_mfma_f32_16x16x32_bf16 v[50:53], v[202:205], v[160:163], 0
	v_mfma_f32_16x16x32_bf16 v[38:41], v[194:197], v[168:171], 0
	v_mfma_f32_16x16x32_bf16 v[34:37], v[202:205], v[168:171], 0
	v_mfma_f32_16x16x32_bf16 v[22:25], v[194:197], v[176:179], 0
	v_mfma_f32_16x16x32_bf16 v[18:21], v[202:205], v[176:179], 0
	v_mfma_f32_16x16x32_bf16 v[6:9], v[194:197], v[184:187], 0
	v_mfma_f32_16x16x32_bf16 v[2:5], v[202:205], v[184:187], 0
	v_mfma_f32_16x16x32_bf16 v[54:57], v[198:201], v[164:167], v[54:57]
	v_mfma_f32_16x16x32_bf16 v[50:53], v[206:209], v[164:167], v[50:53]
	v_mfma_f32_16x16x32_bf16 v[38:41], v[198:201], v[172:175], v[38:41]
	v_mfma_f32_16x16x32_bf16 v[34:37], v[206:209], v[172:175], v[34:37]
	v_mfma_f32_16x16x32_bf16 v[22:25], v[198:201], v[180:183], v[22:25]
	v_mfma_f32_16x16x32_bf16 v[18:21], v[206:209], v[180:183], v[18:21]
	v_mfma_f32_16x16x32_bf16 v[6:9], v[198:201], v[190:193], v[6:9]
	v_mfma_f32_16x16x32_bf16 v[2:5], v[206:209], v[190:193], v[2:5]
	s_barrier
	s_add_u32 s14, s14, 0x40000
	s_addc_u32 s15, s15, 0
	s_mov_b32 m0, s28
	ds_read_b128 v[160:163], v151 offset:32768
	ds_read_b128 v[164:167], v151 offset:33792
	ds_read_b128 v[168:171], v151 offset:34816
	ds_read_b128 v[172:175], v151 offset:35840
	ds_read_b128 v[176:179], v151 offset:36864
	ds_read_b128 v[180:183], v151 offset:37888
	ds_read_b128 v[184:187], v151 offset:38912
	ds_read_b128 v[190:193], v151 offset:39936
	global_load_lds_dwordx4 v136, s[14:15]
	s_mov_b32 m0, s29
	s_nop 0
	global_load_lds_dwordx4 v132, s[14:15]
	s_waitcnt lgkmcnt(8)
	s_barrier
	s_waitcnt lgkmcnt(0)
	v_mfma_f32_16x16x32_bf16 v[126:129], v[142:145], v[160:163], v[126:129]
	v_mfma_f32_16x16x32_bf16 v[122:125], v[152:155], v[160:163], v[122:125]
	v_mfma_f32_16x16x32_bf16 v[110:113], v[142:145], v[168:171], v[110:113]
	v_mfma_f32_16x16x32_bf16 v[106:109], v[152:155], v[168:171], v[106:109]
	v_mfma_f32_16x16x32_bf16 v[94:97], v[142:145], v[176:179], v[94:97]
	v_mfma_f32_16x16x32_bf16 v[90:93], v[152:155], v[176:179], v[90:93]
	v_mfma_f32_16x16x32_bf16 v[78:81], v[142:145], v[184:187], v[78:81]
	v_mfma_f32_16x16x32_bf16 v[74:77], v[152:155], v[184:187], v[74:77]
	v_mfma_f32_16x16x32_bf16 v[126:129], v[146:149], v[164:167], v[126:129]
	v_mfma_f32_16x16x32_bf16 v[122:125], v[156:159], v[164:167], v[122:125]
	v_mfma_f32_16x16x32_bf16 v[110:113], v[146:149], v[172:175], v[110:113]
	v_mfma_f32_16x16x32_bf16 v[106:109], v[156:159], v[172:175], v[106:109]
	v_mfma_f32_16x16x32_bf16 v[94:97], v[146:149], v[180:183], v[94:97]
	v_mfma_f32_16x16x32_bf16 v[90:93], v[156:159], v[180:183], v[90:93]
	v_mfma_f32_16x16x32_bf16 v[78:81], v[146:149], v[190:193], v[78:81]
	v_mfma_f32_16x16x32_bf16 v[74:77], v[156:159], v[190:193], v[74:77]
	s_barrier
	s_add_i32 m0, s22, 0x18000
	ds_read_b128 v[194:197], v189 offset:49152
	ds_read_b128 v[198:201], v189 offset:50176
	ds_read_b128 v[202:205], v189 offset:51200
	ds_read_b128 v[206:209], v189 offset:52224
	s_add_u32 s98, s12, s40
	s_addc_u32 s99, s13, s41
	global_load_lds_dwordx4 v134, s[98:99]
	s_add_i32 m0, s22, 0x1a000
	s_nop 0
	global_load_lds_dwordx4 v130, s[98:99]
	s_barrier
	s_waitcnt lgkmcnt(0)
	v_mfma_f32_16x16x32_bf16 v[118:121], v[194:197], v[160:163], v[118:121]
	v_mfma_f32_16x16x32_bf16 v[114:117], v[202:205], v[160:163], v[114:117]
	v_mfma_f32_16x16x32_bf16 v[102:105], v[194:197], v[168:171], v[102:105]
	v_mfma_f32_16x16x32_bf16 v[98:101], v[202:205], v[168:171], v[98:101]
	v_mfma_f32_16x16x32_bf16 v[86:89], v[194:197], v[176:179], v[86:89]
	v_mfma_f32_16x16x32_bf16 v[82:85], v[202:205], v[176:179], v[82:85]
	v_mfma_f32_16x16x32_bf16 v[70:73], v[194:197], v[184:187], v[70:73]
	v_mfma_f32_16x16x32_bf16 v[66:69], v[202:205], v[184:187], v[66:69]
	v_mfma_f32_16x16x32_bf16 v[118:121], v[198:201], v[164:167], v[118:121]
	v_mfma_f32_16x16x32_bf16 v[114:117], v[206:209], v[164:167], v[114:117]
	v_mfma_f32_16x16x32_bf16 v[102:105], v[198:201], v[172:175], v[102:105]
	v_mfma_f32_16x16x32_bf16 v[98:101], v[206:209], v[172:175], v[98:101]
	v_mfma_f32_16x16x32_bf16 v[86:89], v[198:201], v[180:183], v[86:89]
	v_mfma_f32_16x16x32_bf16 v[82:85], v[206:209], v[180:183], v[82:85]
	v_mfma_f32_16x16x32_bf16 v[70:73], v[198:201], v[190:193], v[70:73]
	v_mfma_f32_16x16x32_bf16 v[66:69], v[206:209], v[190:193], v[66:69]
	s_mov_b32 m0, s38
	s_barrier
	ds_read_b128 v[160:163], v151 offset:49152
	ds_read_b128 v[164:167], v151 offset:50176
	ds_read_b128 v[168:171], v151 offset:51200
	ds_read_b128 v[172:175], v151 offset:52224
	ds_read_b128 v[176:179], v151 offset:53248
	ds_read_b128 v[180:183], v151 offset:54272
	ds_read_b128 v[184:187], v151 offset:55296
	ds_read_b128 v[190:193], v151 offset:56320
	s_add_u32 s98, s100, s40
	s_addc_u32 s99, s101, s41
	global_load_lds_dwordx4 v136, s[98:99]
	s_mov_b32 m0, s39
	s_nop 0
	global_load_lds_dwordx4 v132, s[98:99]
	s_waitcnt vmcnt(10)
	s_barrier
	s_waitcnt lgkmcnt(0)
	v_mfma_f32_16x16x32_bf16 v[62:65], v[142:145], v[160:163], v[62:65]
	v_mfma_f32_16x16x32_bf16 v[58:61], v[152:155], v[160:163], v[58:61]
	v_mfma_f32_16x16x32_bf16 v[46:49], v[142:145], v[168:171], v[46:49]
	v_mfma_f32_16x16x32_bf16 v[42:45], v[152:155], v[168:171], v[42:45]
	v_mfma_f32_16x16x32_bf16 v[30:33], v[142:145], v[176:179], v[30:33]
	v_mfma_f32_16x16x32_bf16 v[26:29], v[152:155], v[176:179], v[26:29]
	v_mfma_f32_16x16x32_bf16 v[14:17], v[142:145], v[184:187], v[14:17]
	v_mfma_f32_16x16x32_bf16 v[10:13], v[152:155], v[184:187], v[10:13]
	v_mfma_f32_16x16x32_bf16 v[62:65], v[146:149], v[164:167], v[62:65]
	v_mfma_f32_16x16x32_bf16 v[58:61], v[156:159], v[164:167], v[58:61]
	v_mfma_f32_16x16x32_bf16 v[46:49], v[146:149], v[172:175], v[46:49]
	v_mfma_f32_16x16x32_bf16 v[42:45], v[156:159], v[172:175], v[42:45]
	v_mfma_f32_16x16x32_bf16 v[30:33], v[146:149], v[180:183], v[30:33]
	v_mfma_f32_16x16x32_bf16 v[26:29], v[156:159], v[180:183], v[26:29]
	v_mfma_f32_16x16x32_bf16 v[14:17], v[146:149], v[190:193], v[14:17]
	v_mfma_f32_16x16x32_bf16 v[10:13], v[156:159], v[190:193], v[10:13]
	s_barrier
	s_add_u32 s12, s12, 0x40080
	s_addc_u32 s13, s13, 0
	s_add_i32 m0, s22, 0x1c000
	s_nop 0
	global_load_lds_dwordx4 v134, s[12:13]
	s_add_i32 m0, s22, 0x1e000
	s_nop 0
	global_load_lds_dwordx4 v130, s[12:13]
	ds_read_b128 v[142:145], v189
	ds_read_b128 v[146:149], v189 offset:1024
	ds_read_b128 v[152:155], v189 offset:2048
	ds_read_b128 v[156:159], v189 offset:3072
	s_waitcnt vmcnt(6)
	s_barrier
	v_mfma_f32_16x16x32_bf16 v[54:57], v[194:197], v[160:163], v[54:57]
	v_mfma_f32_16x16x32_bf16 v[50:53], v[202:205], v[160:163], v[50:53]
	v_mfma_f32_16x16x32_bf16 v[38:41], v[194:197], v[168:171], v[38:41]
	v_mfma_f32_16x16x32_bf16 v[34:37], v[202:205], v[168:171], v[34:37]
	v_mfma_f32_16x16x32_bf16 v[22:25], v[194:197], v[176:179], v[22:25]
	v_mfma_f32_16x16x32_bf16 v[18:21], v[202:205], v[176:179], v[18:21]
	v_mfma_f32_16x16x32_bf16 v[6:9], v[194:197], v[184:187], v[6:9]
	v_mfma_f32_16x16x32_bf16 v[2:5], v[202:205], v[184:187], v[2:5]
	v_mfma_f32_16x16x32_bf16 v[54:57], v[198:201], v[164:167], v[54:57]
	v_mfma_f32_16x16x32_bf16 v[50:53], v[206:209], v[164:167], v[50:53]
	v_mfma_f32_16x16x32_bf16 v[38:41], v[198:201], v[172:175], v[38:41]
	v_mfma_f32_16x16x32_bf16 v[34:37], v[206:209], v[172:175], v[34:37]
	v_mfma_f32_16x16x32_bf16 v[22:25], v[198:201], v[180:183], v[22:25]
	v_mfma_f32_16x16x32_bf16 v[18:21], v[206:209], v[180:183], v[18:21]
	v_mfma_f32_16x16x32_bf16 v[6:9], v[198:201], v[190:193], v[6:9]
	v_mfma_f32_16x16x32_bf16 v[2:5], v[206:209], v[190:193], v[2:5]
	s_add_i32 s85, s85, 2
	s_add_u32 s4, s4, 0x100
	s_addc_u32 s5, s5, 0
	s_add_u32 s78, s78, 0x100
	s_addc_u32 s79, s79, 0
	s_add_u32 s12, s4, 0xfffc0080
	s_addc_u32 s13, s5, -1
	s_cmp_eq_u32 s85, 12
	s_cselect_b32 s15, s44, s13
	s_cselect_b32 s14, s45, s12
	s_cselect_b32 s13, s47, s79
	s_cselect_b32 s12, s55, s78
	s_cmp_gt_u32 s85, 13
	s_barrier
.LBB0_267:
	s_add_i32 m0, s7, 0xc000
	ds_read_b128 v[160:163], v151
	ds_read_b128 v[164:167], v151 offset:1024
	ds_read_b128 v[168:171], v151 offset:2048
	ds_read_b128 v[172:175], v151 offset:3072
	ds_read_b128 v[176:179], v151 offset:4096
	ds_read_b128 v[180:183], v151 offset:5120
	ds_read_b128 v[184:187], v151 offset:6144
	ds_read_b128 v[190:193], v151 offset:7168
	global_load_lds_dwordx4 v138, s[4:5]
	s_add_i32 m0, s7, 0xe000
	s_nop 0
	global_load_lds_dwordx4 v140, s[4:5]
	s_waitcnt lgkmcnt(8)
	s_barrier
	s_waitcnt lgkmcnt(0)
	v_mfma_f32_16x16x32_bf16 v[126:129], v[142:145], v[160:163], v[126:129]
	v_mfma_f32_16x16x32_bf16 v[122:125], v[152:155], v[160:163], v[122:125]
	v_mfma_f32_16x16x32_bf16 v[110:113], v[142:145], v[168:171], v[110:113]
	v_mfma_f32_16x16x32_bf16 v[106:109], v[152:155], v[168:171], v[106:109]
	v_mfma_f32_16x16x32_bf16 v[94:97], v[142:145], v[176:179], v[94:97]
	v_mfma_f32_16x16x32_bf16 v[90:93], v[152:155], v[176:179], v[90:93]
	v_mfma_f32_16x16x32_bf16 v[78:81], v[142:145], v[184:187], v[78:81]
	v_mfma_f32_16x16x32_bf16 v[74:77], v[152:155], v[184:187], v[74:77]
	v_mfma_f32_16x16x32_bf16 v[126:129], v[146:149], v[164:167], v[126:129]
	v_mfma_f32_16x16x32_bf16 v[122:125], v[156:159], v[164:167], v[122:125]
	v_mfma_f32_16x16x32_bf16 v[110:113], v[146:149], v[172:175], v[110:113]
	v_mfma_f32_16x16x32_bf16 v[106:109], v[156:159], v[172:175], v[106:109]
	v_mfma_f32_16x16x32_bf16 v[94:97], v[146:149], v[180:183], v[94:97]
	v_mfma_f32_16x16x32_bf16 v[90:93], v[156:159], v[180:183], v[90:93]
	v_mfma_f32_16x16x32_bf16 v[78:81], v[146:149], v[190:193], v[78:81]
	v_mfma_f32_16x16x32_bf16 v[74:77], v[156:159], v[190:193], v[74:77]
	s_barrier
	s_add_i32 m0, s22, 0x10000
	ds_read_b128 v[194:197], v189 offset:16384
	ds_read_b128 v[198:201], v189 offset:17408
	ds_read_b128 v[202:205], v189 offset:18432
	ds_read_b128 v[206:209], v189 offset:19456
	global_load_lds_dwordx4 v134, s[12:13]
	s_add_i32 m0, s22, 0x12000
	s_nop 0
	global_load_lds_dwordx4 v130, s[12:13]
	s_barrier
	s_waitcnt lgkmcnt(0)
	v_mfma_f32_16x16x32_bf16 v[118:121], v[194:197], v[160:163], v[118:121]
	v_mfma_f32_16x16x32_bf16 v[114:117], v[202:205], v[160:163], v[114:117]
	v_mfma_f32_16x16x32_bf16 v[102:105], v[194:197], v[168:171], v[102:105]
	v_mfma_f32_16x16x32_bf16 v[98:101], v[202:205], v[168:171], v[98:101]
	v_mfma_f32_16x16x32_bf16 v[86:89], v[194:197], v[176:179], v[86:89]
	v_mfma_f32_16x16x32_bf16 v[82:85], v[202:205], v[176:179], v[82:85]
	v_mfma_f32_16x16x32_bf16 v[70:73], v[194:197], v[184:187], v[70:73]
	v_mfma_f32_16x16x32_bf16 v[66:69], v[202:205], v[184:187], v[66:69]
	v_mfma_f32_16x16x32_bf16 v[118:121], v[198:201], v[164:167], v[118:121]
	v_mfma_f32_16x16x32_bf16 v[114:117], v[206:209], v[164:167], v[114:117]
	v_mfma_f32_16x16x32_bf16 v[102:105], v[198:201], v[172:175], v[102:105]
	v_mfma_f32_16x16x32_bf16 v[98:101], v[206:209], v[172:175], v[98:101]
	v_mfma_f32_16x16x32_bf16 v[86:89], v[198:201], v[180:183], v[86:89]
	v_mfma_f32_16x16x32_bf16 v[82:85], v[206:209], v[180:183], v[82:85]
	v_mfma_f32_16x16x32_bf16 v[70:73], v[198:201], v[190:193], v[70:73]
	v_mfma_f32_16x16x32_bf16 v[66:69], v[206:209], v[190:193], v[66:69]
	s_mov_b32 m0, s7
	s_mov_b64 s[100:101], s[14:15]
	s_barrier
	ds_read_b128 v[160:163], v151 offset:16384
	ds_read_b128 v[164:167], v151 offset:17408
	ds_read_b128 v[168:171], v151 offset:18432
	ds_read_b128 v[172:175], v151 offset:19456
	ds_read_b128 v[176:179], v151 offset:20480
	ds_read_b128 v[180:183], v151 offset:21504
	ds_read_b128 v[184:187], v151 offset:22528
	ds_read_b128 v[190:193], v151 offset:23552
	global_load_lds_dwordx4 v136, s[100:101]
	s_mov_b32 m0, s23
	s_nop 0
	global_load_lds_dwordx4 v132, s[100:101]
	s_waitcnt vmcnt(10)
	s_barrier
	s_waitcnt lgkmcnt(0)
	v_mfma_f32_16x16x32_bf16 v[62:65], v[142:145], v[160:163], v[62:65]
	v_mfma_f32_16x16x32_bf16 v[58:61], v[152:155], v[160:163], v[58:61]
	v_mfma_f32_16x16x32_bf16 v[46:49], v[142:145], v[168:171], v[46:49]
	v_mfma_f32_16x16x32_bf16 v[42:45], v[152:155], v[168:171], v[42:45]
	v_mfma_f32_16x16x32_bf16 v[30:33], v[142:145], v[176:179], v[30:33]
	v_mfma_f32_16x16x32_bf16 v[26:29], v[152:155], v[176:179], v[26:29]
	v_mfma_f32_16x16x32_bf16 v[14:17], v[142:145], v[184:187], v[14:17]
	v_mfma_f32_16x16x32_bf16 v[10:13], v[152:155], v[184:187], v[10:13]
	v_mfma_f32_16x16x32_bf16 v[62:65], v[146:149], v[164:167], v[62:65]
	v_mfma_f32_16x16x32_bf16 v[58:61], v[156:159], v[164:167], v[58:61]
	v_mfma_f32_16x16x32_bf16 v[46:49], v[146:149], v[172:175], v[46:49]
	v_mfma_f32_16x16x32_bf16 v[42:45], v[156:159], v[172:175], v[42:45]
	v_mfma_f32_16x16x32_bf16 v[30:33], v[146:149], v[180:183], v[30:33]
	v_mfma_f32_16x16x32_bf16 v[26:29], v[156:159], v[180:183], v[26:29]
	v_mfma_f32_16x16x32_bf16 v[14:17], v[146:149], v[190:193], v[14:17]
	v_mfma_f32_16x16x32_bf16 v[10:13], v[156:159], v[190:193], v[10:13]
	s_barrier
	s_add_u32 s86, s12, 0x40000
	s_addc_u32 s87, s13, 0
	s_add_i32 m0, s22, 0x14000
	s_nop 0
	global_load_lds_dwordx4 v134, s[86:87]
	s_add_i32 m0, s22, 0x16000
	s_nop 0
	global_load_lds_dwordx4 v130, s[86:87]
	ds_read_b128 v[142:145], v189 offset:32768
	ds_read_b128 v[146:149], v189 offset:33792
	ds_read_b128 v[152:155], v189 offset:34816
	ds_read_b128 v[156:159], v189 offset:35840
	s_waitcnt vmcnt(6)
	s_barrier
	v_mfma_f32_16x16x32_bf16 v[54:57], v[194:197], v[160:163], v[54:57]
	v_mfma_f32_16x16x32_bf16 v[50:53], v[202:205], v[160:163], v[50:53]
	v_mfma_f32_16x16x32_bf16 v[38:41], v[194:197], v[168:171], v[38:41]
	v_mfma_f32_16x16x32_bf16 v[34:37], v[202:205], v[168:171], v[34:37]
	v_mfma_f32_16x16x32_bf16 v[22:25], v[194:197], v[176:179], v[22:25]
	v_mfma_f32_16x16x32_bf16 v[18:21], v[202:205], v[176:179], v[18:21]
	v_mfma_f32_16x16x32_bf16 v[6:9], v[194:197], v[184:187], v[6:9]
	v_mfma_f32_16x16x32_bf16 v[2:5], v[202:205], v[184:187], v[2:5]
	v_mfma_f32_16x16x32_bf16 v[54:57], v[198:201], v[164:167], v[54:57]
	v_mfma_f32_16x16x32_bf16 v[50:53], v[206:209], v[164:167], v[50:53]
	v_mfma_f32_16x16x32_bf16 v[38:41], v[198:201], v[172:175], v[38:41]
	v_mfma_f32_16x16x32_bf16 v[34:37], v[206:209], v[172:175], v[34:37]
	v_mfma_f32_16x16x32_bf16 v[22:25], v[198:201], v[180:183], v[22:25]
	v_mfma_f32_16x16x32_bf16 v[18:21], v[206:209], v[180:183], v[18:21]
	v_mfma_f32_16x16x32_bf16 v[6:9], v[198:201], v[190:193], v[6:9]
	v_mfma_f32_16x16x32_bf16 v[2:5], v[206:209], v[190:193], v[2:5]
	s_barrier
	s_add_u32 s14, s14, 0x40000
	s_addc_u32 s15, s15, 0
	s_mov_b32 m0, s28
	ds_read_b128 v[160:163], v151 offset:32768
	ds_read_b128 v[164:167], v151 offset:33792
	ds_read_b128 v[168:171], v151 offset:34816
	ds_read_b128 v[172:175], v151 offset:35840
	ds_read_b128 v[176:179], v151 offset:36864
	ds_read_b128 v[180:183], v151 offset:37888
	ds_read_b128 v[184:187], v151 offset:38912
	ds_read_b128 v[190:193], v151 offset:39936
	global_load_lds_dwordx4 v136, s[14:15]
	s_mov_b32 m0, s29
	s_nop 0
	global_load_lds_dwordx4 v132, s[14:15]
	s_waitcnt lgkmcnt(8)
	s_barrier
	s_waitcnt lgkmcnt(0)
	v_mfma_f32_16x16x32_bf16 v[126:129], v[142:145], v[160:163], v[126:129]
	v_mfma_f32_16x16x32_bf16 v[122:125], v[152:155], v[160:163], v[122:125]
	v_mfma_f32_16x16x32_bf16 v[110:113], v[142:145], v[168:171], v[110:113]
	v_mfma_f32_16x16x32_bf16 v[106:109], v[152:155], v[168:171], v[106:109]
	v_mfma_f32_16x16x32_bf16 v[94:97], v[142:145], v[176:179], v[94:97]
	v_mfma_f32_16x16x32_bf16 v[90:93], v[152:155], v[176:179], v[90:93]
	v_mfma_f32_16x16x32_bf16 v[78:81], v[142:145], v[184:187], v[78:81]
	v_mfma_f32_16x16x32_bf16 v[74:77], v[152:155], v[184:187], v[74:77]
	v_mfma_f32_16x16x32_bf16 v[126:129], v[146:149], v[164:167], v[126:129]
	v_mfma_f32_16x16x32_bf16 v[122:125], v[156:159], v[164:167], v[122:125]
	v_mfma_f32_16x16x32_bf16 v[110:113], v[146:149], v[172:175], v[110:113]
	v_mfma_f32_16x16x32_bf16 v[106:109], v[156:159], v[172:175], v[106:109]
	v_mfma_f32_16x16x32_bf16 v[94:97], v[146:149], v[180:183], v[94:97]
	v_mfma_f32_16x16x32_bf16 v[90:93], v[156:159], v[180:183], v[90:93]
	v_mfma_f32_16x16x32_bf16 v[78:81], v[146:149], v[190:193], v[78:81]
	v_mfma_f32_16x16x32_bf16 v[74:77], v[156:159], v[190:193], v[74:77]
	s_barrier
	s_add_i32 m0, s22, 0x18000
	ds_read_b128 v[194:197], v189 offset:49152
	ds_read_b128 v[198:201], v189 offset:50176
	ds_read_b128 v[202:205], v189 offset:51200
	ds_read_b128 v[206:209], v189 offset:52224
	s_add_u32 s98, s12, s40
	s_addc_u32 s99, s13, s41
	global_load_lds_dwordx4 v134, s[98:99]
	s_add_i32 m0, s22, 0x1a000
	s_nop 0
	global_load_lds_dwordx4 v130, s[98:99]
	s_barrier
	s_waitcnt lgkmcnt(0)
	v_mfma_f32_16x16x32_bf16 v[118:121], v[194:197], v[160:163], v[118:121]
	v_mfma_f32_16x16x32_bf16 v[114:117], v[202:205], v[160:163], v[114:117]
	v_mfma_f32_16x16x32_bf16 v[102:105], v[194:197], v[168:171], v[102:105]
	v_mfma_f32_16x16x32_bf16 v[98:101], v[202:205], v[168:171], v[98:101]
	v_mfma_f32_16x16x32_bf16 v[86:89], v[194:197], v[176:179], v[86:89]
	v_mfma_f32_16x16x32_bf16 v[82:85], v[202:205], v[176:179], v[82:85]
	v_mfma_f32_16x16x32_bf16 v[70:73], v[194:197], v[184:187], v[70:73]
	v_mfma_f32_16x16x32_bf16 v[66:69], v[202:205], v[184:187], v[66:69]
	v_mfma_f32_16x16x32_bf16 v[118:121], v[198:201], v[164:167], v[118:121]
	v_mfma_f32_16x16x32_bf16 v[114:117], v[206:209], v[164:167], v[114:117]
	v_mfma_f32_16x16x32_bf16 v[102:105], v[198:201], v[172:175], v[102:105]
	v_mfma_f32_16x16x32_bf16 v[98:101], v[206:209], v[172:175], v[98:101]
	v_mfma_f32_16x16x32_bf16 v[86:89], v[198:201], v[180:183], v[86:89]
	v_mfma_f32_16x16x32_bf16 v[82:85], v[206:209], v[180:183], v[82:85]
	v_mfma_f32_16x16x32_bf16 v[70:73], v[198:201], v[190:193], v[70:73]
	v_mfma_f32_16x16x32_bf16 v[66:69], v[206:209], v[190:193], v[66:69]
	s_mov_b32 m0, s38
	s_barrier
	ds_read_b128 v[160:163], v151 offset:49152
	ds_read_b128 v[164:167], v151 offset:50176
	ds_read_b128 v[168:171], v151 offset:51200
	ds_read_b128 v[172:175], v151 offset:52224
	ds_read_b128 v[176:179], v151 offset:53248
	ds_read_b128 v[180:183], v151 offset:54272
	ds_read_b128 v[184:187], v151 offset:55296
	ds_read_b128 v[190:193], v151 offset:56320
	s_add_u32 s98, s100, s40
	s_addc_u32 s99, s101, s41
	global_load_lds_dwordx4 v136, s[98:99]
	s_mov_b32 m0, s39
	s_nop 0
	global_load_lds_dwordx4 v132, s[98:99]
	s_waitcnt vmcnt(10)
	s_barrier
	s_waitcnt lgkmcnt(0)
	v_mfma_f32_16x16x32_bf16 v[62:65], v[142:145], v[160:163], v[62:65]
	v_mfma_f32_16x16x32_bf16 v[58:61], v[152:155], v[160:163], v[58:61]
	v_mfma_f32_16x16x32_bf16 v[46:49], v[142:145], v[168:171], v[46:49]
	v_mfma_f32_16x16x32_bf16 v[42:45], v[152:155], v[168:171], v[42:45]
	v_mfma_f32_16x16x32_bf16 v[30:33], v[142:145], v[176:179], v[30:33]
	v_mfma_f32_16x16x32_bf16 v[26:29], v[152:155], v[176:179], v[26:29]
	v_mfma_f32_16x16x32_bf16 v[14:17], v[142:145], v[184:187], v[14:17]
	v_mfma_f32_16x16x32_bf16 v[10:13], v[152:155], v[184:187], v[10:13]
	v_mfma_f32_16x16x32_bf16 v[62:65], v[146:149], v[164:167], v[62:65]
	v_mfma_f32_16x16x32_bf16 v[58:61], v[156:159], v[164:167], v[58:61]
	v_mfma_f32_16x16x32_bf16 v[46:49], v[146:149], v[172:175], v[46:49]
	v_mfma_f32_16x16x32_bf16 v[42:45], v[156:159], v[172:175], v[42:45]
	v_mfma_f32_16x16x32_bf16 v[30:33], v[146:149], v[180:183], v[30:33]
	v_mfma_f32_16x16x32_bf16 v[26:29], v[156:159], v[180:183], v[26:29]
	v_mfma_f32_16x16x32_bf16 v[14:17], v[146:149], v[190:193], v[14:17]
	v_mfma_f32_16x16x32_bf16 v[10:13], v[156:159], v[190:193], v[10:13]
	s_barrier
	s_add_u32 s12, s12, 0x40080
	s_addc_u32 s13, s13, 0
	s_add_i32 m0, s22, 0x1c000
	s_nop 0
	global_load_lds_dwordx4 v134, s[12:13]
	s_add_i32 m0, s22, 0x1e000
	s_nop 0
	global_load_lds_dwordx4 v130, s[12:13]
	ds_read_b128 v[142:145], v189
	ds_read_b128 v[146:149], v189 offset:1024
	ds_read_b128 v[152:155], v189 offset:2048
	ds_read_b128 v[156:159], v189 offset:3072
	s_waitcnt vmcnt(6)
	s_barrier
	v_mfma_f32_16x16x32_bf16 v[54:57], v[194:197], v[160:163], v[54:57]
	v_mfma_f32_16x16x32_bf16 v[50:53], v[202:205], v[160:163], v[50:53]
	v_mfma_f32_16x16x32_bf16 v[38:41], v[194:197], v[168:171], v[38:41]
	v_mfma_f32_16x16x32_bf16 v[34:37], v[202:205], v[168:171], v[34:37]
	v_mfma_f32_16x16x32_bf16 v[22:25], v[194:197], v[176:179], v[22:25]
	v_mfma_f32_16x16x32_bf16 v[18:21], v[202:205], v[176:179], v[18:21]
	v_mfma_f32_16x16x32_bf16 v[6:9], v[194:197], v[184:187], v[6:9]
	v_mfma_f32_16x16x32_bf16 v[2:5], v[202:205], v[184:187], v[2:5]
	v_mfma_f32_16x16x32_bf16 v[54:57], v[198:201], v[164:167], v[54:57]
	v_mfma_f32_16x16x32_bf16 v[50:53], v[206:209], v[164:167], v[50:53]
	v_mfma_f32_16x16x32_bf16 v[38:41], v[198:201], v[172:175], v[38:41]
	v_mfma_f32_16x16x32_bf16 v[34:37], v[206:209], v[172:175], v[34:37]
	v_mfma_f32_16x16x32_bf16 v[22:25], v[198:201], v[180:183], v[22:25]
	v_mfma_f32_16x16x32_bf16 v[18:21], v[206:209], v[180:183], v[18:21]
	v_mfma_f32_16x16x32_bf16 v[6:9], v[198:201], v[190:193], v[6:9]
	v_mfma_f32_16x16x32_bf16 v[2:5], v[206:209], v[190:193], v[2:5]
	s_add_i32 s85, s85, 2
	s_add_u32 s4, s4, 0x100
	s_addc_u32 s5, s5, 0
	s_add_u32 s78, s78, 0x100
	s_addc_u32 s79, s79, 0
	s_add_u32 s12, s4, 0xfffc0080
	s_addc_u32 s13, s5, -1
	s_cmp_eq_u32 s85, 12
	s_cselect_b32 s15, s44, s13
	s_cselect_b32 s14, s45, s12
	s_cselect_b32 s13, s47, s79
	s_cselect_b32 s12, s55, s78
	s_cmp_gt_u32 s85, 13
	s_barrier
	s_cbranch_scc0 .LBB0_267
	s_waitcnt lgkmcnt(0)
	v_mov_b32_e32 v156, v252
	s_mov_b64 s[4:5], -1
	v_and_b32_e32 v154, 63, v156
	s_andn2_b64 vcc, exec, s[2:3]
	v_lshlrev_b32_e32 v142, 2, v154
	s_cbranch_vccnz .LBB0_270
	v_lshlrev_b32_e32 v155, 2, v154
	s_mov_b64 s[4:5], 0

.LBB0_837:
	s_ashr_i32 s15, s14, 31
	s_lshl_b64 s[78:79], s[14:15], 19
	s_add_u32 s84, s36, s78
	s_addc_u32 s85, s37, s79
	s_and_b64 s[4:5], s[4:5], exec
	s_cselect_b32 s15, s85, s91
	s_cselect_b32 s23, s84, s90
	s_add_u32 s34, s90, 0x100
	s_addc_u32 s75, s91, 0
	s_mov_b32 s78, -2
	s_waitcnt lgkmcnt(0)
	s_add_i32 s79, 0, 0x10000
	v_add_u32_e32 v142, s79, v212
	v_add_u32_e32 v189, 0x10000, v212
	ds_read_b128 v[130:133], v142
	ds_read_b128 v[134:137], v142 offset:1024
	ds_read_b128 v[138:141], v142 offset:2048
	ds_read_b128 v[142:145], v142 offset:3072
	s_add_u32 s4, s88, 0x100
	s_addc_u32 s5, s89, 0
	s_cmp_eq_u32 s78, 12
	s_cselect_b32 s93, s17, s5
	s_cselect_b32 s92, s16, s4
	s_cselect_b32 s91, s15, s75
	s_cselect_b32 s90, s23, s34
	v_lshl_add_u64 v[178:179], s[88:89], 0, v[196:197]
	s_add_i32 m0, s39, 0xc000
	ds_read_b128 v[146:149], v213
	ds_read_b128 v[150:153], v213 offset:1024
	ds_read_b128 v[154:157], v213 offset:2048
	ds_read_b128 v[158:161], v213 offset:3072
	ds_read_b128 v[162:165], v213 offset:4096
	ds_read_b128 v[166:169], v213 offset:5120
	ds_read_b128 v[170:173], v213 offset:6144
	ds_read_b128 v[174:177], v213 offset:7168
	global_load_lds_dwordx4 v[178:179], off
	s_add_i32 m0, s39, 0xe000
	v_lshl_add_u64 v[178:179], s[88:89], 0, v[198:199]
	global_load_lds_dwordx4 v[178:179], off
	s_waitcnt lgkmcnt(8)
	s_barrier
	s_waitcnt lgkmcnt(0)
	v_mfma_f32_16x16x32_bf16 v[126:129], v[130:133], v[146:149], 0
	v_mfma_f32_16x16x32_bf16 v[122:125], v[138:141], v[146:149], 0
	v_mfma_f32_16x16x32_bf16 v[110:113], v[130:133], v[154:157], 0
	v_mfma_f32_16x16x32_bf16 v[106:109], v[138:141], v[154:157], 0
	v_mfma_f32_16x16x32_bf16 v[94:97], v[130:133], v[162:165], 0
	v_mfma_f32_16x16x32_bf16 v[90:93], v[138:141], v[162:165], 0
	v_mfma_f32_16x16x32_bf16 v[78:81], v[130:133], v[170:173], 0
	v_mfma_f32_16x16x32_bf16 v[74:77], v[138:141], v[170:173], 0
	v_mfma_f32_16x16x32_bf16 v[126:129], v[134:137], v[150:153], v[126:129]
	v_mfma_f32_16x16x32_bf16 v[122:125], v[142:145], v[150:153], v[122:125]
	v_mfma_f32_16x16x32_bf16 v[110:113], v[134:137], v[158:161], v[110:113]
	v_mfma_f32_16x16x32_bf16 v[106:109], v[142:145], v[158:161], v[106:109]
	v_mfma_f32_16x16x32_bf16 v[94:97], v[134:137], v[166:169], v[94:97]
	v_mfma_f32_16x16x32_bf16 v[90:93], v[142:145], v[166:169], v[90:93]
	v_mfma_f32_16x16x32_bf16 v[78:81], v[134:137], v[174:177], v[78:81]
	v_mfma_f32_16x16x32_bf16 v[74:77], v[142:145], v[174:177], v[74:77]
	s_barrier
	ds_read_b128 v[178:181], v189 offset:16384
	ds_read_b128 v[182:185], v189 offset:17408
	ds_read_b128 v[200:203], v189 offset:18432
	ds_read_b128 v[204:207], v189 offset:19456
	s_add_i32 m0, s38, 0x10000
	global_load_lds_dwordx4 v0, s[90:91]
	s_add_i32 m0, s38, 0x12000
	s_nop 0
	global_load_lds_dwordx4 v194, s[90:91]
	s_barrier
	s_waitcnt lgkmcnt(0)
	v_mfma_f32_16x16x32_bf16 v[118:121], v[178:181], v[146:149], 0
	v_mfma_f32_16x16x32_bf16 v[114:117], v[200:203], v[146:149], 0
	v_mfma_f32_16x16x32_bf16 v[102:105], v[178:181], v[154:157], 0
	v_mfma_f32_16x16x32_bf16 v[98:101], v[200:203], v[154:157], 0
	v_mfma_f32_16x16x32_bf16 v[86:89], v[178:181], v[162:165], 0
	v_mfma_f32_16x16x32_bf16 v[82:85], v[200:203], v[162:165], 0
	v_mfma_f32_16x16x32_bf16 v[70:73], v[178:181], v[170:173], 0
	v_mfma_f32_16x16x32_bf16 v[66:69], v[200:203], v[170:173], 0
	v_mfma_f32_16x16x32_bf16 v[118:121], v[182:185], v[150:153], v[118:121]
	v_mfma_f32_16x16x32_bf16 v[114:117], v[204:207], v[150:153], v[114:117]
	v_mfma_f32_16x16x32_bf16 v[102:105], v[182:185], v[158:161], v[102:105]
	v_mfma_f32_16x16x32_bf16 v[98:101], v[204:207], v[158:161], v[98:101]
	v_mfma_f32_16x16x32_bf16 v[86:89], v[182:185], v[166:169], v[86:89]
	v_mfma_f32_16x16x32_bf16 v[82:85], v[204:207], v[166:169], v[82:85]
	v_mfma_f32_16x16x32_bf16 v[70:73], v[182:185], v[174:177], v[70:73]
	v_mfma_f32_16x16x32_bf16 v[66:69], v[204:207], v[174:177], v[66:69]
	s_mov_b32 m0, s39
	s_barrier
	ds_read_b128 v[146:149], v213 offset:16384
	ds_read_b128 v[150:153], v213 offset:17408
	ds_read_b128 v[154:157], v213 offset:18432
	ds_read_b128 v[158:161], v213 offset:19456
	ds_read_b128 v[162:165], v213 offset:20480
	ds_read_b128 v[166:169], v213 offset:21504
	ds_read_b128 v[170:173], v213 offset:22528
	ds_read_b128 v[174:177], v213 offset:23552
	global_load_lds_dwordx4 v190, s[92:93]
	s_mov_b32 m0, s42
	s_nop 0
	global_load_lds_dwordx4 v192, s[92:93]
	s_waitcnt vmcnt(10)
	s_barrier
	s_waitcnt lgkmcnt(0)
	v_mfma_f32_16x16x32_bf16 v[62:65], v[130:133], v[146:149], 0
	v_mfma_f32_16x16x32_bf16 v[58:61], v[138:141], v[146:149], 0
	v_mfma_f32_16x16x32_bf16 v[46:49], v[130:133], v[154:157], 0
	v_mfma_f32_16x16x32_bf16 v[42:45], v[138:141], v[154:157], 0
	v_mfma_f32_16x16x32_bf16 v[30:33], v[130:133], v[162:165], 0
	v_mfma_f32_16x16x32_bf16 v[26:29], v[138:141], v[162:165], 0
	v_mfma_f32_16x16x32_bf16 v[14:17], v[130:133], v[170:173], 0
	v_mfma_f32_16x16x32_bf16 v[10:13], v[138:141], v[170:173], 0
	v_mfma_f32_16x16x32_bf16 v[62:65], v[134:137], v[150:153], v[62:65]
	v_mfma_f32_16x16x32_bf16 v[58:61], v[142:145], v[150:153], v[58:61]
	v_mfma_f32_16x16x32_bf16 v[46:49], v[134:137], v[158:161], v[46:49]
	v_mfma_f32_16x16x32_bf16 v[42:45], v[142:145], v[158:161], v[42:45]
	v_mfma_f32_16x16x32_bf16 v[30:33], v[134:137], v[166:169], v[30:33]
	v_mfma_f32_16x16x32_bf16 v[26:29], v[142:145], v[166:169], v[26:29]
	v_mfma_f32_16x16x32_bf16 v[14:17], v[134:137], v[174:177], v[14:17]
	v_mfma_f32_16x16x32_bf16 v[10:13], v[142:145], v[174:177], v[10:13]
	s_barrier
	s_add_u32 s88, s90, 0x40000
	s_addc_u32 s89, s91, 0
	s_add_i32 m0, s38, 0x14000
	s_nop 0
	global_load_lds_dwordx4 v0, s[88:89]
	s_add_i32 m0, s38, 0x16000
	s_nop 0
	global_load_lds_dwordx4 v194, s[88:89]
	s_add_i32 s79, 0, 0x18000
	v_add_u32_e32 v142, s79, v212
	ds_read_b128 v[130:133], v142
	ds_read_b128 v[134:137], v142 offset:1024
	ds_read_b128 v[138:141], v142 offset:2048
	ds_read_b128 v[142:145], v142 offset:3072
	s_waitcnt vmcnt(6)
	s_barrier
	v_mfma_f32_16x16x32_bf16 v[54:57], v[178:181], v[146:149], 0
	v_mfma_f32_16x16x32_bf16 v[50:53], v[200:203], v[146:149], 0
	v_mfma_f32_16x16x32_bf16 v[38:41], v[178:181], v[154:157], 0
	v_mfma_f32_16x16x32_bf16 v[34:37], v[200:203], v[154:157], 0
	v_mfma_f32_16x16x32_bf16 v[22:25], v[178:181], v[162:165], 0
	v_mfma_f32_16x16x32_bf16 v[18:21], v[200:203], v[162:165], 0
	v_mfma_f32_16x16x32_bf16 v[6:9], v[178:181], v[170:173], 0
	v_mfma_f32_16x16x32_bf16 v[2:5], v[200:203], v[170:173], 0
	v_mfma_f32_16x16x32_bf16 v[54:57], v[182:185], v[150:153], v[54:57]
	v_mfma_f32_16x16x32_bf16 v[50:53], v[204:207], v[150:153], v[50:53]
	v_mfma_f32_16x16x32_bf16 v[38:41], v[182:185], v[158:161], v[38:41]
	v_mfma_f32_16x16x32_bf16 v[34:37], v[204:207], v[158:161], v[34:37]
	v_mfma_f32_16x16x32_bf16 v[22:25], v[182:185], v[166:169], v[22:25]
	v_mfma_f32_16x16x32_bf16 v[18:21], v[204:207], v[166:169], v[18:21]
	v_mfma_f32_16x16x32_bf16 v[6:9], v[182:185], v[174:177], v[6:9]
	v_mfma_f32_16x16x32_bf16 v[2:5], v[204:207], v[174:177], v[2:5]
	s_barrier
	s_add_u32 s88, s92, 0xc0000
	s_addc_u32 s89, s93, 0
	s_mov_b32 m0, s43
	ds_read_b128 v[146:149], v213 offset:32768
	ds_read_b128 v[150:153], v213 offset:33792
	ds_read_b128 v[154:157], v213 offset:34816
	ds_read_b128 v[158:161], v213 offset:35840
	ds_read_b128 v[162:165], v213 offset:36864
	ds_read_b128 v[166:169], v213 offset:37888
	ds_read_b128 v[170:173], v213 offset:38912
	ds_read_b128 v[174:177], v213 offset:39936
	global_load_lds_dwordx4 v190, s[88:89]
	s_mov_b32 m0, s44
	s_nop 0
	global_load_lds_dwordx4 v192, s[88:89]
	s_waitcnt lgkmcnt(8)
	s_barrier
	s_waitcnt lgkmcnt(0)
	v_mfma_f32_16x16x32_bf16 v[126:129], v[130:133], v[146:149], v[126:129]
	v_mfma_f32_16x16x32_bf16 v[122:125], v[138:141], v[146:149], v[122:125]
	v_mfma_f32_16x16x32_bf16 v[110:113], v[130:133], v[154:157], v[110:113]
	v_mfma_f32_16x16x32_bf16 v[106:109], v[138:141], v[154:157], v[106:109]
	v_mfma_f32_16x16x32_bf16 v[94:97], v[130:133], v[162:165], v[94:97]
	v_mfma_f32_16x16x32_bf16 v[90:93], v[138:141], v[162:165], v[90:93]
	v_mfma_f32_16x16x32_bf16 v[78:81], v[130:133], v[170:173], v[78:81]
	v_mfma_f32_16x16x32_bf16 v[74:77], v[138:141], v[170:173], v[74:77]
	v_mfma_f32_16x16x32_bf16 v[126:129], v[134:137], v[150:153], v[126:129]
	v_mfma_f32_16x16x32_bf16 v[122:125], v[142:145], v[150:153], v[122:125]
	v_mfma_f32_16x16x32_bf16 v[110:113], v[134:137], v[158:161], v[110:113]
	v_mfma_f32_16x16x32_bf16 v[106:109], v[142:145], v[158:161], v[106:109]
	v_mfma_f32_16x16x32_bf16 v[94:97], v[134:137], v[166:169], v[94:97]
	v_mfma_f32_16x16x32_bf16 v[90:93], v[142:145], v[166:169], v[90:93]
	v_mfma_f32_16x16x32_bf16 v[78:81], v[134:137], v[174:177], v[78:81]
	v_mfma_f32_16x16x32_bf16 v[74:77], v[142:145], v[174:177], v[74:77]
	s_barrier
	s_add_i32 s87, 0, 0x1c000
	v_add_u32_e32 v204, s87, v212
	s_add_i32 m0, s38, 0x18000
	ds_read_b128 v[178:181], v204
	ds_read_b128 v[182:185], v204 offset:1024
	ds_read_b128 v[200:203], v204 offset:2048
	ds_read_b128 v[204:207], v204 offset:3072
	s_add_u32 s98, s90, s40
	s_addc_u32 s99, s91, s41
	global_load_lds_dwordx4 v0, s[98:99]
	s_add_i32 m0, s38, 0x1a000
	s_nop 0
	global_load_lds_dwordx4 v194, s[98:99]
	s_barrier
	s_waitcnt lgkmcnt(0)
	v_mfma_f32_16x16x32_bf16 v[118:121], v[178:181], v[146:149], v[118:121]
	v_mfma_f32_16x16x32_bf16 v[114:117], v[200:203], v[146:149], v[114:117]
	v_mfma_f32_16x16x32_bf16 v[102:105], v[178:181], v[154:157], v[102:105]
	v_mfma_f32_16x16x32_bf16 v[98:101], v[200:203], v[154:157], v[98:101]
	v_mfma_f32_16x16x32_bf16 v[86:89], v[178:181], v[162:165], v[86:89]
	v_mfma_f32_16x16x32_bf16 v[82:85], v[200:203], v[162:165], v[82:85]
	v_mfma_f32_16x16x32_bf16 v[70:73], v[178:181], v[170:173], v[70:73]
	v_mfma_f32_16x16x32_bf16 v[66:69], v[200:203], v[170:173], v[66:69]
	v_mfma_f32_16x16x32_bf16 v[118:121], v[182:185], v[150:153], v[118:121]
	v_mfma_f32_16x16x32_bf16 v[114:117], v[204:207], v[150:153], v[114:117]
	v_mfma_f32_16x16x32_bf16 v[102:105], v[182:185], v[158:161], v[102:105]
	v_mfma_f32_16x16x32_bf16 v[98:101], v[204:207], v[158:161], v[98:101]
	v_mfma_f32_16x16x32_bf16 v[86:89], v[182:185], v[166:169], v[86:89]
	v_mfma_f32_16x16x32_bf16 v[82:85], v[204:207], v[166:169], v[82:85]
	v_mfma_f32_16x16x32_bf16 v[70:73], v[182:185], v[174:177], v[70:73]
	v_mfma_f32_16x16x32_bf16 v[66:69], v[204:207], v[174:177], v[66:69]
	s_mov_b32 m0, s60
	s_barrier
	ds_read_b128 v[146:149], v213 offset:49152
	ds_read_b128 v[150:153], v213 offset:50176
	ds_read_b128 v[154:157], v213 offset:51200
	ds_read_b128 v[158:161], v213 offset:52224
	ds_read_b128 v[162:165], v213 offset:53248
	ds_read_b128 v[166:169], v213 offset:54272
	ds_read_b128 v[170:173], v213 offset:55296
	ds_read_b128 v[174:177], v213 offset:56320
	s_add_u32 s98, s92, s40
	s_addc_u32 s99, s93, s41
	global_load_lds_dwordx4 v190, s[98:99]
	s_mov_b32 m0, s61
	s_nop 0
	global_load_lds_dwordx4 v192, s[98:99]
	s_waitcnt vmcnt(10)
	s_barrier
	s_waitcnt lgkmcnt(0)
	v_mfma_f32_16x16x32_bf16 v[62:65], v[130:133], v[146:149], v[62:65]
	v_mfma_f32_16x16x32_bf16 v[58:61], v[138:141], v[146:149], v[58:61]
	v_mfma_f32_16x16x32_bf16 v[46:49], v[130:133], v[154:157], v[46:49]
	v_mfma_f32_16x16x32_bf16 v[42:45], v[138:141], v[154:157], v[42:45]
	v_mfma_f32_16x16x32_bf16 v[30:33], v[130:133], v[162:165], v[30:33]
	v_mfma_f32_16x16x32_bf16 v[26:29], v[138:141], v[162:165], v[26:29]
	v_mfma_f32_16x16x32_bf16 v[14:17], v[130:133], v[170:173], v[14:17]
	v_mfma_f32_16x16x32_bf16 v[10:13], v[138:141], v[170:173], v[10:13]
	v_mfma_f32_16x16x32_bf16 v[62:65], v[134:137], v[150:153], v[62:65]
	v_mfma_f32_16x16x32_bf16 v[58:61], v[142:145], v[150:153], v[58:61]
	v_mfma_f32_16x16x32_bf16 v[46:49], v[134:137], v[158:161], v[46:49]
	v_mfma_f32_16x16x32_bf16 v[42:45], v[142:145], v[158:161], v[42:45]
	v_mfma_f32_16x16x32_bf16 v[30:33], v[134:137], v[166:169], v[30:33]
	v_mfma_f32_16x16x32_bf16 v[26:29], v[142:145], v[166:169], v[26:29]
	v_mfma_f32_16x16x32_bf16 v[14:17], v[134:137], v[174:177], v[14:17]
	v_mfma_f32_16x16x32_bf16 v[10:13], v[142:145], v[174:177], v[10:13]
	s_barrier
	s_add_u32 s88, s90, 0x40080
	s_addc_u32 s89, s91, 0
	s_add_i32 m0, s38, 0x1c000
	s_nop 0
	global_load_lds_dwordx4 v0, s[88:89]
	s_add_i32 m0, s38, 0x1e000
	s_nop 0
	global_load_lds_dwordx4 v194, s[88:89]
	ds_read_b128 v[130:133], v189
	ds_read_b128 v[134:137], v189 offset:1024
	ds_read_b128 v[138:141], v189 offset:2048
	ds_read_b128 v[142:145], v189 offset:3072
	s_waitcnt vmcnt(6)
	s_barrier
	v_mfma_f32_16x16x32_bf16 v[54:57], v[178:181], v[146:149], v[54:57]
	v_mfma_f32_16x16x32_bf16 v[50:53], v[200:203], v[146:149], v[50:53]
	v_mfma_f32_16x16x32_bf16 v[38:41], v[178:181], v[154:157], v[38:41]
	v_mfma_f32_16x16x32_bf16 v[34:37], v[200:203], v[154:157], v[34:37]
	v_mfma_f32_16x16x32_bf16 v[22:25], v[178:181], v[162:165], v[22:25]
	v_mfma_f32_16x16x32_bf16 v[18:21], v[200:203], v[162:165], v[18:21]
	v_mfma_f32_16x16x32_bf16 v[6:9], v[178:181], v[170:173], v[6:9]
	v_mfma_f32_16x16x32_bf16 v[2:5], v[200:203], v[170:173], v[2:5]
	v_mfma_f32_16x16x32_bf16 v[54:57], v[182:185], v[150:153], v[54:57]
	v_mfma_f32_16x16x32_bf16 v[50:53], v[204:207], v[150:153], v[50:53]
	v_mfma_f32_16x16x32_bf16 v[38:41], v[182:185], v[158:161], v[38:41]
	v_mfma_f32_16x16x32_bf16 v[34:37], v[204:207], v[158:161], v[34:37]
	v_mfma_f32_16x16x32_bf16 v[22:25], v[182:185], v[166:169], v[22:25]
	v_mfma_f32_16x16x32_bf16 v[18:21], v[204:207], v[166:169], v[18:21]
	v_mfma_f32_16x16x32_bf16 v[6:9], v[182:185], v[174:177], v[6:9]
	v_mfma_f32_16x16x32_bf16 v[2:5], v[204:207], v[174:177], v[2:5]
	s_add_i32 s78, s78, 2
	s_add_u32 s34, s34, 0x100
	s_addc_u32 s75, s75, 0
	s_mov_b64 s[88:89], s[4:5]
	s_add_u32 s4, s88, 0x100
	s_addc_u32 s5, s89, 0
	s_cmp_eq_u32 s78, 12
	s_cselect_b32 s93, s17, s5
	s_cselect_b32 s92, s16, s4
	s_cselect_b32 s91, s15, s75
	s_cselect_b32 s90, s23, s34
	s_cmp_gt_u32 s78, 13
	s_barrier
.LBB0_838:
	v_lshl_add_u64 v[178:179], s[88:89], 0, v[196:197]
	s_add_i32 m0, s39, 0xc000
	ds_read_b128 v[146:149], v213
	ds_read_b128 v[150:153], v213 offset:1024
	ds_read_b128 v[154:157], v213 offset:2048
	ds_read_b128 v[158:161], v213 offset:3072
	ds_read_b128 v[162:165], v213 offset:4096
	ds_read_b128 v[166:169], v213 offset:5120
	ds_read_b128 v[170:173], v213 offset:6144
	ds_read_b128 v[174:177], v213 offset:7168
	global_load_lds_dwordx4 v[178:179], off
	s_add_i32 m0, s39, 0xe000
	v_lshl_add_u64 v[178:179], s[88:89], 0, v[198:199]
	global_load_lds_dwordx4 v[178:179], off
	s_waitcnt lgkmcnt(8)
	s_barrier
	s_waitcnt lgkmcnt(0)
	v_mfma_f32_16x16x32_bf16 v[126:129], v[130:133], v[146:149], v[126:129]
	v_mfma_f32_16x16x32_bf16 v[122:125], v[138:141], v[146:149], v[122:125]
	v_mfma_f32_16x16x32_bf16 v[110:113], v[130:133], v[154:157], v[110:113]
	v_mfma_f32_16x16x32_bf16 v[106:109], v[138:141], v[154:157], v[106:109]
	v_mfma_f32_16x16x32_bf16 v[94:97], v[130:133], v[162:165], v[94:97]
	v_mfma_f32_16x16x32_bf16 v[90:93], v[138:141], v[162:165], v[90:93]
	v_mfma_f32_16x16x32_bf16 v[78:81], v[130:133], v[170:173], v[78:81]
	v_mfma_f32_16x16x32_bf16 v[74:77], v[138:141], v[170:173], v[74:77]
	v_mfma_f32_16x16x32_bf16 v[126:129], v[134:137], v[150:153], v[126:129]
	v_mfma_f32_16x16x32_bf16 v[122:125], v[142:145], v[150:153], v[122:125]
	v_mfma_f32_16x16x32_bf16 v[110:113], v[134:137], v[158:161], v[110:113]
	v_mfma_f32_16x16x32_bf16 v[106:109], v[142:145], v[158:161], v[106:109]
	v_mfma_f32_16x16x32_bf16 v[94:97], v[134:137], v[166:169], v[94:97]
	v_mfma_f32_16x16x32_bf16 v[90:93], v[142:145], v[166:169], v[90:93]
	v_mfma_f32_16x16x32_bf16 v[78:81], v[134:137], v[174:177], v[78:81]
	v_mfma_f32_16x16x32_bf16 v[74:77], v[142:145], v[174:177], v[74:77]
	s_barrier
	ds_read_b128 v[178:181], v189 offset:16384
	ds_read_b128 v[182:185], v189 offset:17408
	ds_read_b128 v[200:203], v189 offset:18432
	ds_read_b128 v[204:207], v189 offset:19456
	s_add_i32 m0, s38, 0x10000
	global_load_lds_dwordx4 v0, s[90:91]
	s_add_i32 m0, s38, 0x12000
	s_nop 0
	global_load_lds_dwordx4 v194, s[90:91]
	s_barrier
	s_waitcnt lgkmcnt(0)
	v_mfma_f32_16x16x32_bf16 v[118:121], v[178:181], v[146:149], v[118:121]
	v_mfma_f32_16x16x32_bf16 v[114:117], v[200:203], v[146:149], v[114:117]
	v_mfma_f32_16x16x32_bf16 v[102:105], v[178:181], v[154:157], v[102:105]
	v_mfma_f32_16x16x32_bf16 v[98:101], v[200:203], v[154:157], v[98:101]
	v_mfma_f32_16x16x32_bf16 v[86:89], v[178:181], v[162:165], v[86:89]
	v_mfma_f32_16x16x32_bf16 v[82:85], v[200:203], v[162:165], v[82:85]
	v_mfma_f32_16x16x32_bf16 v[70:73], v[178:181], v[170:173], v[70:73]
	v_mfma_f32_16x16x32_bf16 v[66:69], v[200:203], v[170:173], v[66:69]
	v_mfma_f32_16x16x32_bf16 v[118:121], v[182:185], v[150:153], v[118:121]
	v_mfma_f32_16x16x32_bf16 v[114:117], v[204:207], v[150:153], v[114:117]
	v_mfma_f32_16x16x32_bf16 v[102:105], v[182:185], v[158:161], v[102:105]
	v_mfma_f32_16x16x32_bf16 v[98:101], v[204:207], v[158:161], v[98:101]
	v_mfma_f32_16x16x32_bf16 v[86:89], v[182:185], v[166:169], v[86:89]
	v_mfma_f32_16x16x32_bf16 v[82:85], v[204:207], v[166:169], v[82:85]
	v_mfma_f32_16x16x32_bf16 v[70:73], v[182:185], v[174:177], v[70:73]
	v_mfma_f32_16x16x32_bf16 v[66:69], v[204:207], v[174:177], v[66:69]
	s_mov_b32 m0, s39
	s_barrier
	ds_read_b128 v[146:149], v213 offset:16384
	ds_read_b128 v[150:153], v213 offset:17408
	ds_read_b128 v[154:157], v213 offset:18432
	ds_read_b128 v[158:161], v213 offset:19456
	ds_read_b128 v[162:165], v213 offset:20480
	ds_read_b128 v[166:169], v213 offset:21504
	ds_read_b128 v[170:173], v213 offset:22528
	ds_read_b128 v[174:177], v213 offset:23552
	global_load_lds_dwordx4 v190, s[92:93]
	s_mov_b32 m0, s42
	s_nop 0
	global_load_lds_dwordx4 v192, s[92:93]
	s_waitcnt vmcnt(10)
	s_barrier
	s_waitcnt lgkmcnt(0)
	v_mfma_f32_16x16x32_bf16 v[62:65], v[130:133], v[146:149], v[62:65]
	v_mfma_f32_16x16x32_bf16 v[58:61], v[138:141], v[146:149], v[58:61]
	v_mfma_f32_16x16x32_bf16 v[46:49], v[130:133], v[154:157], v[46:49]
	v_mfma_f32_16x16x32_bf16 v[42:45], v[138:141], v[154:157], v[42:45]
	v_mfma_f32_16x16x32_bf16 v[30:33], v[130:133], v[162:165], v[30:33]
	v_mfma_f32_16x16x32_bf16 v[26:29], v[138:141], v[162:165], v[26:29]
	v_mfma_f32_16x16x32_bf16 v[14:17], v[130:133], v[170:173], v[14:17]
	v_mfma_f32_16x16x32_bf16 v[10:13], v[138:141], v[170:173], v[10:13]
	v_mfma_f32_16x16x32_bf16 v[62:65], v[134:137], v[150:153], v[62:65]
	v_mfma_f32_16x16x32_bf16 v[58:61], v[142:145], v[150:153], v[58:61]
	v_mfma_f32_16x16x32_bf16 v[46:49], v[134:137], v[158:161], v[46:49]
	v_mfma_f32_16x16x32_bf16 v[42:45], v[142:145], v[158:161], v[42:45]
	v_mfma_f32_16x16x32_bf16 v[30:33], v[134:137], v[166:169], v[30:33]
	v_mfma_f32_16x16x32_bf16 v[26:29], v[142:145], v[166:169], v[26:29]
	v_mfma_f32_16x16x32_bf16 v[14:17], v[134:137], v[174:177], v[14:17]
	v_mfma_f32_16x16x32_bf16 v[10:13], v[142:145], v[174:177], v[10:13]
	s_barrier
	s_add_u32 s88, s90, 0x40000
	s_addc_u32 s89, s91, 0
	s_add_i32 m0, s38, 0x14000
	s_nop 0
	global_load_lds_dwordx4 v0, s[88:89]
	s_add_i32 m0, s38, 0x16000
	s_nop 0
	global_load_lds_dwordx4 v194, s[88:89]
	s_add_i32 s79, 0, 0x18000
	v_add_u32_e32 v142, s79, v212
	ds_read_b128 v[130:133], v142
	ds_read_b128 v[134:137], v142 offset:1024
	ds_read_b128 v[138:141], v142 offset:2048
	ds_read_b128 v[142:145], v142 offset:3072
	s_waitcnt vmcnt(6)
	s_barrier
	v_mfma_f32_16x16x32_bf16 v[54:57], v[178:181], v[146:149], v[54:57]
	v_mfma_f32_16x16x32_bf16 v[50:53], v[200:203], v[146:149], v[50:53]
	v_mfma_f32_16x16x32_bf16 v[38:41], v[178:181], v[154:157], v[38:41]
	v_mfma_f32_16x16x32_bf16 v[34:37], v[200:203], v[154:157], v[34:37]
	v_mfma_f32_16x16x32_bf16 v[22:25], v[178:181], v[162:165], v[22:25]
	v_mfma_f32_16x16x32_bf16 v[18:21], v[200:203], v[162:165], v[18:21]
	v_mfma_f32_16x16x32_bf16 v[6:9], v[178:181], v[170:173], v[6:9]
	v_mfma_f32_16x16x32_bf16 v[2:5], v[200:203], v[170:173], v[2:5]
	v_mfma_f32_16x16x32_bf16 v[54:57], v[182:185], v[150:153], v[54:57]
	v_mfma_f32_16x16x32_bf16 v[50:53], v[204:207], v[150:153], v[50:53]
	v_mfma_f32_16x16x32_bf16 v[38:41], v[182:185], v[158:161], v[38:41]
	v_mfma_f32_16x16x32_bf16 v[34:37], v[204:207], v[158:161], v[34:37]
	v_mfma_f32_16x16x32_bf16 v[22:25], v[182:185], v[166:169], v[22:25]
	v_mfma_f32_16x16x32_bf16 v[18:21], v[204:207], v[166:169], v[18:21]
	v_mfma_f32_16x16x32_bf16 v[6:9], v[182:185], v[174:177], v[6:9]
	v_mfma_f32_16x16x32_bf16 v[2:5], v[204:207], v[174:177], v[2:5]
	s_barrier
	s_add_u32 s88, s92, 0xc0000
	s_addc_u32 s89, s93, 0
	s_mov_b32 m0, s43
	ds_read_b128 v[146:149], v213 offset:32768
	ds_read_b128 v[150:153], v213 offset:33792
	ds_read_b128 v[154:157], v213 offset:34816
	ds_read_b128 v[158:161], v213 offset:35840
	ds_read_b128 v[162:165], v213 offset:36864
	ds_read_b128 v[166:169], v213 offset:37888
	ds_read_b128 v[170:173], v213 offset:38912
	ds_read_b128 v[174:177], v213 offset:39936
	global_load_lds_dwordx4 v190, s[88:89]
	s_mov_b32 m0, s44
	s_nop 0
	global_load_lds_dwordx4 v192, s[88:89]
	s_waitcnt lgkmcnt(8)
	s_barrier
	s_waitcnt lgkmcnt(0)
	v_mfma_f32_16x16x32_bf16 v[126:129], v[130:133], v[146:149], v[126:129]
	v_mfma_f32_16x16x32_bf16 v[122:125], v[138:141], v[146:149], v[122:125]
	v_mfma_f32_16x16x32_bf16 v[110:113], v[130:133], v[154:157], v[110:113]
	v_mfma_f32_16x16x32_bf16 v[106:109], v[138:141], v[154:157], v[106:109]
	v_mfma_f32_16x16x32_bf16 v[94:97], v[130:133], v[162:165], v[94:97]
	v_mfma_f32_16x16x32_bf16 v[90:93], v[138:141], v[162:165], v[90:93]
	v_mfma_f32_16x16x32_bf16 v[78:81], v[130:133], v[170:173], v[78:81]
	v_mfma_f32_16x16x32_bf16 v[74:77], v[138:141], v[170:173], v[74:77]
	v_mfma_f32_16x16x32_bf16 v[126:129], v[134:137], v[150:153], v[126:129]
	v_mfma_f32_16x16x32_bf16 v[122:125], v[142:145], v[150:153], v[122:125]
	v_mfma_f32_16x16x32_bf16 v[110:113], v[134:137], v[158:161], v[110:113]
	v_mfma_f32_16x16x32_bf16 v[106:109], v[142:145], v[158:161], v[106:109]
	v_mfma_f32_16x16x32_bf16 v[94:97], v[134:137], v[166:169], v[94:97]
	v_mfma_f32_16x16x32_bf16 v[90:93], v[142:145], v[166:169], v[90:93]
	v_mfma_f32_16x16x32_bf16 v[78:81], v[134:137], v[174:177], v[78:81]
	v_mfma_f32_16x16x32_bf16 v[74:77], v[142:145], v[174:177], v[74:77]
	s_barrier
	s_add_i32 s87, 0, 0x1c000
	v_add_u32_e32 v204, s87, v212
	s_add_i32 m0, s38, 0x18000
	ds_read_b128 v[178:181], v204
	ds_read_b128 v[182:185], v204 offset:1024
	ds_read_b128 v[200:203], v204 offset:2048
	ds_read_b128 v[204:207], v204 offset:3072
	s_add_u32 s98, s90, s40
	s_addc_u32 s99, s91, s41
	global_load_lds_dwordx4 v0, s[98:99]
	s_add_i32 m0, s38, 0x1a000
	s_nop 0
	global_load_lds_dwordx4 v194, s[98:99]
	s_barrier
	s_waitcnt lgkmcnt(0)
	v_mfma_f32_16x16x32_bf16 v[118:121], v[178:181], v[146:149], v[118:121]
	v_mfma_f32_16x16x32_bf16 v[114:117], v[200:203], v[146:149], v[114:117]
	v_mfma_f32_16x16x32_bf16 v[102:105], v[178:181], v[154:157], v[102:105]
	v_mfma_f32_16x16x32_bf16 v[98:101], v[200:203], v[154:157], v[98:101]
	v_mfma_f32_16x16x32_bf16 v[86:89], v[178:181], v[162:165], v[86:89]
	v_mfma_f32_16x16x32_bf16 v[82:85], v[200:203], v[162:165], v[82:85]
	v_mfma_f32_16x16x32_bf16 v[70:73], v[178:181], v[170:173], v[70:73]
	v_mfma_f32_16x16x32_bf16 v[66:69], v[200:203], v[170:173], v[66:69]
	v_mfma_f32_16x16x32_bf16 v[118:121], v[182:185], v[150:153], v[118:121]
	v_mfma_f32_16x16x32_bf16 v[114:117], v[204:207], v[150:153], v[114:117]
	v_mfma_f32_16x16x32_bf16 v[102:105], v[182:185], v[158:161], v[102:105]
	v_mfma_f32_16x16x32_bf16 v[98:101], v[204:207], v[158:161], v[98:101]
	v_mfma_f32_16x16x32_bf16 v[86:89], v[182:185], v[166:169], v[86:89]
	v_mfma_f32_16x16x32_bf16 v[82:85], v[204:207], v[166:169], v[82:85]
	v_mfma_f32_16x16x32_bf16 v[70:73], v[182:185], v[174:177], v[70:73]
	v_mfma_f32_16x16x32_bf16 v[66:69], v[204:207], v[174:177], v[66:69]
	s_mov_b32 m0, s60
	s_barrier
	ds_read_b128 v[146:149], v213 offset:49152
	ds_read_b128 v[150:153], v213 offset:50176
	ds_read_b128 v[154:157], v213 offset:51200
	ds_read_b128 v[158:161], v213 offset:52224
	ds_read_b128 v[162:165], v213 offset:53248
	ds_read_b128 v[166:169], v213 offset:54272
	ds_read_b128 v[170:173], v213 offset:55296
	ds_read_b128 v[174:177], v213 offset:56320
	s_add_u32 s98, s92, s40
	s_addc_u32 s99, s93, s41
	global_load_lds_dwordx4 v190, s[98:99]
	s_mov_b32 m0, s61
	s_nop 0
	global_load_lds_dwordx4 v192, s[98:99]
	s_waitcnt vmcnt(10)
	s_barrier
	s_waitcnt lgkmcnt(0)
	v_mfma_f32_16x16x32_bf16 v[62:65], v[130:133], v[146:149], v[62:65]
	v_mfma_f32_16x16x32_bf16 v[58:61], v[138:141], v[146:149], v[58:61]
	v_mfma_f32_16x16x32_bf16 v[46:49], v[130:133], v[154:157], v[46:49]
	v_mfma_f32_16x16x32_bf16 v[42:45], v[138:141], v[154:157], v[42:45]
	v_mfma_f32_16x16x32_bf16 v[30:33], v[130:133], v[162:165], v[30:33]
	v_mfma_f32_16x16x32_bf16 v[26:29], v[138:141], v[162:165], v[26:29]
	v_mfma_f32_16x16x32_bf16 v[14:17], v[130:133], v[170:173], v[14:17]
	v_mfma_f32_16x16x32_bf16 v[10:13], v[138:141], v[170:173], v[10:13]
	v_mfma_f32_16x16x32_bf16 v[62:65], v[134:137], v[150:153], v[62:65]
	v_mfma_f32_16x16x32_bf16 v[58:61], v[142:145], v[150:153], v[58:61]
	v_mfma_f32_16x16x32_bf16 v[46:49], v[134:137], v[158:161], v[46:49]
	v_mfma_f32_16x16x32_bf16 v[42:45], v[142:145], v[158:161], v[42:45]
	v_mfma_f32_16x16x32_bf16 v[30:33], v[134:137], v[166:169], v[30:33]
	v_mfma_f32_16x16x32_bf16 v[26:29], v[142:145], v[166:169], v[26:29]
	v_mfma_f32_16x16x32_bf16 v[14:17], v[134:137], v[174:177], v[14:17]
	v_mfma_f32_16x16x32_bf16 v[10:13], v[142:145], v[174:177], v[10:13]
	s_barrier
	s_add_u32 s88, s90, 0x40080
	s_addc_u32 s89, s91, 0
	s_add_i32 m0, s38, 0x1c000
	s_nop 0
	global_load_lds_dwordx4 v0, s[88:89]
	s_add_i32 m0, s38, 0x1e000
	s_nop 0
	global_load_lds_dwordx4 v194, s[88:89]
	ds_read_b128 v[130:133], v189
	ds_read_b128 v[134:137], v189 offset:1024
	ds_read_b128 v[138:141], v189 offset:2048
	ds_read_b128 v[142:145], v189 offset:3072
	s_waitcnt vmcnt(6)
	s_barrier
	v_mfma_f32_16x16x32_bf16 v[54:57], v[178:181], v[146:149], v[54:57]
	v_mfma_f32_16x16x32_bf16 v[50:53], v[200:203], v[146:149], v[50:53]
	v_mfma_f32_16x16x32_bf16 v[38:41], v[178:181], v[154:157], v[38:41]
	v_mfma_f32_16x16x32_bf16 v[34:37], v[200:203], v[154:157], v[34:37]
	v_mfma_f32_16x16x32_bf16 v[22:25], v[178:181], v[162:165], v[22:25]
	v_mfma_f32_16x16x32_bf16 v[18:21], v[200:203], v[162:165], v[18:21]
	v_mfma_f32_16x16x32_bf16 v[6:9], v[178:181], v[170:173], v[6:9]
	v_mfma_f32_16x16x32_bf16 v[2:5], v[200:203], v[170:173], v[2:5]
	v_mfma_f32_16x16x32_bf16 v[54:57], v[182:185], v[150:153], v[54:57]
	v_mfma_f32_16x16x32_bf16 v[50:53], v[204:207], v[150:153], v[50:53]
	v_mfma_f32_16x16x32_bf16 v[38:41], v[182:185], v[158:161], v[38:41]
	v_mfma_f32_16x16x32_bf16 v[34:37], v[204:207], v[158:161], v[34:37]
	v_mfma_f32_16x16x32_bf16 v[22:25], v[182:185], v[166:169], v[22:25]
	v_mfma_f32_16x16x32_bf16 v[18:21], v[204:207], v[166:169], v[18:21]
	v_mfma_f32_16x16x32_bf16 v[6:9], v[182:185], v[174:177], v[6:9]
	v_mfma_f32_16x16x32_bf16 v[2:5], v[204:207], v[174:177], v[2:5]
	s_add_i32 s78, s78, 2
	s_add_u32 s34, s34, 0x100
	s_addc_u32 s75, s75, 0
	s_mov_b64 s[88:89], s[4:5]
	s_add_u32 s4, s88, 0x100
	s_addc_u32 s5, s89, 0
	s_cmp_eq_u32 s78, 12
	s_cselect_b32 s93, s17, s5
	s_cselect_b32 s92, s16, s4
	s_cselect_b32 s91, s15, s75
	s_cselect_b32 s90, s23, s34
	s_cmp_gt_u32 s78, 13
	s_barrier
	s_cbranch_scc0 .LBB0_838
	s_waitcnt lgkmcnt(0)
	s_lshl_b32 s4, s22, 8
	v_mov_b32_e32 v186, v252
	s_add_i32 s4, s4, s47
	s_nop 0
	v_and_or_b32 v202, v186, 15, s4
	s_lshl_b32 s4, s86, 8
	s_or_b32 s4, s4, s55
	v_lshrrev_b32_e32 v130, 1, v186
	v_and_or_b32 v200, v130, 24, s4
	v_ashrrev_i32_e32 v201, 31, v200
	v_ashrrev_i32_e32 v203, 31, v202
	v_lshl_add_u64 v[204:205], v[200:201], 2, s[6:7]
	v_lshlrev_b64 v[130:131], 12, v[202:203]
	v_lshl_add_u64 v[130:131], v[204:205], 0, v[130:131]
	global_load_dwordx4 v[216:219], v[130:131], off offset:16
	global_load_dwordx4 v[220:223], v[130:131], off
	global_load_dwordx4 v[178:181], v[130:131], off offset:528
	global_load_dwordx4 v[182:185], v[130:131], off offset:512
	v_or_b32_e32 v210, 16, v202
	v_ashrrev_i32_e32 v211, 31, v210
	v_lshlrev_b64 v[130:131], 12, v[210:211]
	v_or_b32_e32 v208, 32, v202
	v_lshl_add_u64 v[130:131], v[204:205], 0, v[130:131]
	v_ashrrev_i32_e32 v209, 31, v208
	global_load_dwordx4 v[170:173], v[130:131], off offset:16
	global_load_dwordx4 v[174:177], v[130:131], off
	global_load_dwordx4 v[162:165], v[130:131], off offset:528
	global_load_dwordx4 v[166:169], v[130:131], off offset:512
	v_lshlrev_b64 v[130:131], 12, v[208:209]
	v_or_b32_e32 v206, 48, v202
	v_lshl_add_u64 v[130:131], v[204:205], 0, v[130:131]
	v_ashrrev_i32_e32 v207, 31, v206
	global_load_dwordx4 v[154:157], v[130:131], off offset:16
	global_load_dwordx4 v[158:161], v[130:131], off
	global_load_dwordx4 v[138:141], v[130:131], off offset:528
	global_load_dwordx4 v[142:145], v[130:131], off offset:512
	v_lshlrev_b64 v[130:131], 12, v[206:207]
	v_lshl_add_u64 v[134:135], v[204:205], 0, v[130:131]
	global_load_dwordx4 v[146:149], v[134:135], off offset:16
	global_load_dwordx4 v[150:153], v[134:135], off
	global_load_dwordx4 v[130:133], v[134:135], off offset:528
	s_nop 0
	global_load_dwordx4 v[134:137], v[134:135], off offset:512
	v_and_b32_e32 v186, 63, v186
	v_lshlrev_b32_e32 v187, 2, v186
	v_xor_b32_e32 v215, 64, v187
	v_xor_b32_e32 v214, 0x80, v187
	v_cmp_gt_u32_e32 vcc, 16, v186
	v_lshlrev_b64 v[186:187], 10, v[202:203]
	v_lshl_add_u64 v[186:187], v[186:187], 0, v[200:201]
	s_lshl_b32 s4, s86, 2
	s_ashr_i32 s5, s4, 31
	s_waitcnt vmcnt(0)
	v_pk_add_f32 v[124:125], v[124:125], v[218:219]
	v_pk_add_f32 v[128:129], v[128:129], v[222:223]
	v_pk_add_f32 v[126:127], v[126:127], v[220:221]
	v_pk_mul_f32 v[218:219], v[128:129], v[128:129]
	v_pk_mul_f32 v[220:221], v[126:127], v[126:127]
	v_pk_add_f32 v[122:123], v[122:123], v[216:217]
	v_lshl_add_u64 v[216:217], v[186:187], 2, s[12:13]
	v_add_f32_e32 v220, v220, v221
	v_add_f32_e32 v218, v218, v219
	global_store_dwordx4 v[216:217], v[126:129], off
	global_store_dwordx4 v[216:217], v[122:125], off offset:16
	v_add_f32_e32 v222, v220, v218
	v_pk_mul_f32 v[220:221], v[122:123], v[122:123]
	v_cvt_pk_bf16_f32 v126, v126, v127
	v_cvt_pk_bf16_f32 v127, v128, v129
	v_cvt_pk_bf16_f32 v128, v122, v123
	v_cvt_pk_bf16_f32 v129, v124, v125
	v_lshl_add_u64 v[122:123], v[186:187], 1, s[8:9]
	v_pk_add_f32 v[120:121], v[120:121], v[184:185]
	v_pk_add_f32 v[118:119], v[118:119], v[182:183]
	v_pk_mul_f32 v[218:219], v[124:125], v[124:125]
	global_store_dwordx4 v[122:123], v[126:129], off
	v_pk_mul_f32 v[124:125], v[120:121], v[120:121]
	v_pk_add_f32 v[116:117], v[116:117], v[180:181]
	v_pk_mul_f32 v[126:127], v[118:119], v[118:119]
	v_pk_add_f32 v[114:115], v[114:115], v[178:179]
	v_add_f32_e32 v126, v126, v127
	v_add_f32_e32 v124, v124, v125
	v_add_f32_e32 v128, v126, v124
	v_pk_mul_f32 v[124:125], v[116:117], v[116:117]
	v_pk_mul_f32 v[126:127], v[114:115], v[114:115]
	v_add_f32_e32 v220, v220, v221
	v_add_f32_e32 v218, v218, v219
	v_add_f32_e32 v126, v126, v127
	v_add_f32_e32 v124, v124, v125
	v_add_f32_e32 v218, v220, v218
	v_add_f32_e32 v124, v126, v124
	v_add_f32_e32 v218, v222, v218
	v_add_f32_e32 v124, v128, v124
	v_add_f32_e32 v124, v218, v124
	global_store_dwordx4 v[216:217], v[118:121], off offset:512
	global_store_dwordx4 v[216:217], v[114:117], off offset:528
	s_nop 0
	v_cvt_pk_bf16_f32 v118, v118, v119
	v_cvt_pk_bf16_f32 v119, v120, v121
	v_cvt_pk_bf16_f32 v120, v114, v115
	ds_bpermute_b32 v114, v215, v124
	v_cvt_pk_bf16_f32 v121, v116, v117
	global_store_dwordx4 v[122:123], v[118:121], off offset:256
	s_waitcnt lgkmcnt(0)
	v_add_f32_e32 v114, v124, v114
	ds_bpermute_b32 v115, v214, v114
	s_and_saveexec_b64 s[22:23], vcc
	s_cbranch_execz .LBB0_841
	v_lshlrev_b64 v[116:117], 6, v[202:203]
	v_lshl_add_u64 v[116:117], s[10:11], 0, v[116:117]
	v_lshl_add_u64 v[116:117], s[4:5], 2, v[116:117]
	s_lshl_b32 s34, s45, 2
	v_lshl_add_u64 v[116:117], v[116:117], 0, s[34:35]
	s_waitcnt lgkmcnt(0)
	v_add_f32_e32 v114, v114, v115
	global_store_dword v[116:117], v114, off

.LBB0_918:
	s_ashr_i32 s17, s16, 31
	s_lshl_b64 s[22:23], s[16:17], 19
	v_mov_b64_e32 v[2:3], 0xb00
	s_add_u32 s84, s8, s22
	v_cmp_lt_i64_e32 vcc, s[28:29], v[2:3]
	s_addc_u32 s85, s9, s23
	s_and_b64 s[22:23], vcc, exec
	s_cselect_b32 s17, s85, s7
	s_cselect_b32 s22, s84, s6
	s_ashr_i32 s15, s14, 31
	s_lshl_b64 s[28:29], s[14:15], 19
	s_add_u32 s86, s37, s28
	s_addc_u32 s87, s38, s29
	s_and_b64 s[28:29], vcc, exec
	s_cselect_b32 s15, s87, s89
	s_cselect_b32 s23, s86, s88
	s_add_u32 s28, s88, 0x100
	s_addc_u32 s29, s89, 0
	s_mov_b32 s45, -2
	s_add_i32 vcc_lo, 0, 0x10000
	v_add_u32_e32 v0, vcc_lo, v254
	v_add_u32_e32 v189, 0x10000, v254
	ds_read_b128 v[130:133], v0
	ds_read_b128 v[134:137], v0 offset:1024
	ds_read_b128 v[138:141], v0 offset:2048
	ds_read_b128 v[142:145], v0 offset:3072
	s_add_u32 s88, s6, 0x100
	s_addc_u32 s89, s7, 0
	s_cmp_eq_u32 s45, 12
	s_cselect_b32 s93, s17, s89
	s_cselect_b32 s92, s22, s88
	s_cselect_b32 s91, s15, s29
	s_cselect_b32 s90, s23, s28
	s_add_i32 m0, s43, 0xc000
	ds_read_b128 v[146:149], v253
	ds_read_b128 v[150:153], v253 offset:1024
	ds_read_b128 v[168:171], v253 offset:2048
	ds_read_b128 v[172:175], v253 offset:3072
	ds_read_b128 v[176:179], v253 offset:4096
	ds_read_b128 v[180:183], v253 offset:5120
	ds_read_b128 v[184:187], v253 offset:6144
	ds_read_b128 v[190:193], v253 offset:7168
	global_load_lds_dwordx4 v164, s[6:7]
	s_add_i32 m0, s43, 0xe000
	v_lshl_add_u64 v[154:155], s[6:7], 0, v[166:167]
	global_load_lds_dwordx4 v[154:155], off
	s_waitcnt lgkmcnt(8)
	s_barrier
	s_waitcnt lgkmcnt(0)
	v_mfma_f32_16x16x32_bf16 v[126:129], v[130:133], v[146:149], 0
	v_mfma_f32_16x16x32_bf16 v[70:73], v[138:141], v[146:149], 0
	v_mfma_f32_16x16x32_bf16 v[122:125], v[130:133], v[168:171], 0
	v_mfma_f32_16x16x32_bf16 v[74:77], v[138:141], v[168:171], 0
	v_mfma_f32_16x16x32_bf16 v[114:117], v[130:133], v[176:179], 0
	v_mfma_f32_16x16x32_bf16 v[66:69], v[138:141], v[176:179], 0
	v_mfma_f32_16x16x32_bf16 v[110:113], v[130:133], v[184:187], 0
	v_mfma_f32_16x16x32_bf16 v[78:81], v[138:141], v[184:187], 0
	v_mfma_f32_16x16x32_bf16 v[126:129], v[134:137], v[150:153], v[126:129]
	v_mfma_f32_16x16x32_bf16 v[70:73], v[142:145], v[150:153], v[70:73]
	v_mfma_f32_16x16x32_bf16 v[122:125], v[134:137], v[172:175], v[122:125]
	v_mfma_f32_16x16x32_bf16 v[74:77], v[142:145], v[172:175], v[74:77]
	v_mfma_f32_16x16x32_bf16 v[114:117], v[134:137], v[180:183], v[114:117]
	v_mfma_f32_16x16x32_bf16 v[66:69], v[142:145], v[180:183], v[66:69]
	v_mfma_f32_16x16x32_bf16 v[110:113], v[134:137], v[190:193], v[110:113]
	v_mfma_f32_16x16x32_bf16 v[78:81], v[142:145], v[190:193], v[78:81]
	s_barrier
	s_add_i32 m0, s39, 0x10000
	ds_read_b128 v[194:197], v189 offset:16384
	ds_read_b128 v[198:201], v189 offset:17408
	ds_read_b128 v[202:205], v189 offset:18432
	ds_read_b128 v[206:209], v189 offset:19456
	global_load_lds_dwordx4 v160, s[90:91]
	s_add_i32 m0, s39, 0x12000
	s_nop 0
	global_load_lds_dwordx4 v156, s[90:91]
	s_barrier
	s_waitcnt lgkmcnt(0)
	v_mfma_f32_16x16x32_bf16 v[118:121], v[194:197], v[146:149], 0
	v_mfma_f32_16x16x32_bf16 v[94:97], v[202:205], v[146:149], 0
	v_mfma_f32_16x16x32_bf16 v[106:109], v[194:197], v[168:171], 0
	v_mfma_f32_16x16x32_bf16 v[90:93], v[202:205], v[168:171], 0
	v_mfma_f32_16x16x32_bf16 v[102:105], v[194:197], v[176:179], 0
	v_mfma_f32_16x16x32_bf16 v[82:85], v[202:205], v[176:179], 0
	v_mfma_f32_16x16x32_bf16 v[98:101], v[194:197], v[184:187], 0
	v_mfma_f32_16x16x32_bf16 v[86:89], v[202:205], v[184:187], 0
	v_mfma_f32_16x16x32_bf16 v[118:121], v[198:201], v[150:153], v[118:121]
	v_mfma_f32_16x16x32_bf16 v[94:97], v[206:209], v[150:153], v[94:97]
	v_mfma_f32_16x16x32_bf16 v[106:109], v[198:201], v[172:175], v[106:109]
	v_mfma_f32_16x16x32_bf16 v[90:93], v[206:209], v[172:175], v[90:93]
	v_mfma_f32_16x16x32_bf16 v[102:105], v[198:201], v[180:183], v[102:105]
	v_mfma_f32_16x16x32_bf16 v[82:85], v[206:209], v[180:183], v[82:85]
	v_mfma_f32_16x16x32_bf16 v[98:101], v[198:201], v[190:193], v[98:101]
	v_mfma_f32_16x16x32_bf16 v[86:89], v[206:209], v[190:193], v[86:89]
	s_mov_b32 m0, s43
	s_mov_b64 s[100:101], s[92:93]
	s_barrier
	ds_read_b128 v[146:149], v253 offset:16384
	ds_read_b128 v[150:153], v253 offset:17408
	ds_read_b128 v[168:171], v253 offset:18432
	ds_read_b128 v[172:175], v253 offset:19456
	ds_read_b128 v[176:179], v253 offset:20480
	ds_read_b128 v[180:183], v253 offset:21504
	ds_read_b128 v[184:187], v253 offset:22528
	ds_read_b128 v[190:193], v253 offset:23552
	global_load_lds_dwordx4 v162, s[100:101]
	s_mov_b32 m0, s60
	s_nop 0
	global_load_lds_dwordx4 v158, s[100:101]
	s_waitcnt vmcnt(10)
	s_barrier
	s_waitcnt lgkmcnt(0)
	v_mfma_f32_16x16x32_bf16 v[62:65], v[130:133], v[146:149], 0
	v_mfma_f32_16x16x32_bf16 v[10:13], v[138:141], v[146:149], 0
	v_mfma_f32_16x16x32_bf16 v[58:61], v[130:133], v[168:171], 0
	v_mfma_f32_16x16x32_bf16 v[14:17], v[138:141], v[168:171], 0
	v_mfma_f32_16x16x32_bf16 v[54:57], v[130:133], v[176:179], 0
	v_mfma_f32_16x16x32_bf16 v[6:9], v[138:141], v[176:179], 0
	v_mfma_f32_16x16x32_bf16 v[42:45], v[130:133], v[184:187], 0
	v_mfma_f32_16x16x32_bf16 v[2:5], v[138:141], v[184:187], 0
	v_mfma_f32_16x16x32_bf16 v[62:65], v[134:137], v[150:153], v[62:65]
	v_mfma_f32_16x16x32_bf16 v[10:13], v[142:145], v[150:153], v[10:13]
	v_mfma_f32_16x16x32_bf16 v[58:61], v[134:137], v[172:175], v[58:61]
	v_mfma_f32_16x16x32_bf16 v[14:17], v[142:145], v[172:175], v[14:17]
	v_mfma_f32_16x16x32_bf16 v[54:57], v[134:137], v[180:183], v[54:57]
	v_mfma_f32_16x16x32_bf16 v[6:9], v[142:145], v[180:183], v[6:9]
	v_mfma_f32_16x16x32_bf16 v[42:45], v[134:137], v[190:193], v[42:45]
	v_mfma_f32_16x16x32_bf16 v[2:5], v[142:145], v[190:193], v[2:5]
	s_barrier
	s_add_u32 s6, s90, 0x40000
	s_addc_u32 s7, s91, 0
	s_add_i32 m0, s39, 0x14000
	s_nop 0
	global_load_lds_dwordx4 v160, s[6:7]
	s_add_i32 m0, s39, 0x16000
	s_nop 0
	global_load_lds_dwordx4 v156, s[6:7]
	ds_read_b128 v[130:133], v189 offset:32768
	ds_read_b128 v[134:137], v189 offset:33792
	ds_read_b128 v[138:141], v189 offset:34816
	ds_read_b128 v[142:145], v189 offset:35840
	s_waitcnt vmcnt(6)
	s_barrier
	v_mfma_f32_16x16x32_bf16 v[50:53], v[194:197], v[146:149], 0
	v_mfma_f32_16x16x32_bf16 v[26:29], v[202:205], v[146:149], 0
	v_mfma_f32_16x16x32_bf16 v[46:49], v[194:197], v[168:171], 0
	v_mfma_f32_16x16x32_bf16 v[30:33], v[202:205], v[168:171], 0
	v_mfma_f32_16x16x32_bf16 v[38:41], v[194:197], v[176:179], 0
	v_mfma_f32_16x16x32_bf16 v[22:25], v[202:205], v[176:179], 0
	v_mfma_f32_16x16x32_bf16 v[34:37], v[194:197], v[184:187], 0
	v_mfma_f32_16x16x32_bf16 v[18:21], v[202:205], v[184:187], 0
	v_mfma_f32_16x16x32_bf16 v[50:53], v[198:201], v[150:153], v[50:53]
	v_mfma_f32_16x16x32_bf16 v[26:29], v[206:209], v[150:153], v[26:29]
	v_mfma_f32_16x16x32_bf16 v[46:49], v[198:201], v[172:175], v[46:49]
	v_mfma_f32_16x16x32_bf16 v[30:33], v[206:209], v[172:175], v[30:33]
	v_mfma_f32_16x16x32_bf16 v[38:41], v[198:201], v[180:183], v[38:41]
	v_mfma_f32_16x16x32_bf16 v[22:25], v[206:209], v[180:183], v[22:25]
	v_mfma_f32_16x16x32_bf16 v[34:37], v[198:201], v[190:193], v[34:37]
	v_mfma_f32_16x16x32_bf16 v[18:21], v[206:209], v[190:193], v[18:21]
	s_barrier
	s_add_u32 s6, s92, 0x40000
	s_addc_u32 s7, s93, 0
	s_mov_b32 m0, s61
	ds_read_b128 v[146:149], v253 offset:32768
	ds_read_b128 v[150:153], v253 offset:33792
	ds_read_b128 v[168:171], v253 offset:34816
	ds_read_b128 v[172:175], v253 offset:35840
	ds_read_b128 v[176:179], v253 offset:36864
	ds_read_b128 v[180:183], v253 offset:37888
	ds_read_b128 v[184:187], v253 offset:38912
	ds_read_b128 v[190:193], v253 offset:39936
	global_load_lds_dwordx4 v162, s[6:7]
	s_mov_b32 m0, s72
	s_nop 0
	global_load_lds_dwordx4 v158, s[6:7]
	s_waitcnt lgkmcnt(8)
	s_barrier
	s_waitcnt lgkmcnt(0)
	v_mfma_f32_16x16x32_bf16 v[126:129], v[130:133], v[146:149], v[126:129]
	v_mfma_f32_16x16x32_bf16 v[70:73], v[138:141], v[146:149], v[70:73]
	v_mfma_f32_16x16x32_bf16 v[122:125], v[130:133], v[168:171], v[122:125]
	v_mfma_f32_16x16x32_bf16 v[74:77], v[138:141], v[168:171], v[74:77]
	v_mfma_f32_16x16x32_bf16 v[114:117], v[130:133], v[176:179], v[114:117]
	v_mfma_f32_16x16x32_bf16 v[66:69], v[138:141], v[176:179], v[66:69]
	v_mfma_f32_16x16x32_bf16 v[110:113], v[130:133], v[184:187], v[110:113]
	v_mfma_f32_16x16x32_bf16 v[78:81], v[138:141], v[184:187], v[78:81]
	v_mfma_f32_16x16x32_bf16 v[126:129], v[134:137], v[150:153], v[126:129]
	v_mfma_f32_16x16x32_bf16 v[70:73], v[142:145], v[150:153], v[70:73]
	v_mfma_f32_16x16x32_bf16 v[122:125], v[134:137], v[172:175], v[122:125]
	v_mfma_f32_16x16x32_bf16 v[74:77], v[142:145], v[172:175], v[74:77]
	v_mfma_f32_16x16x32_bf16 v[114:117], v[134:137], v[180:183], v[114:117]
	v_mfma_f32_16x16x32_bf16 v[66:69], v[142:145], v[180:183], v[66:69]
	v_mfma_f32_16x16x32_bf16 v[110:113], v[134:137], v[190:193], v[110:113]
	v_mfma_f32_16x16x32_bf16 v[78:81], v[142:145], v[190:193], v[78:81]
	s_barrier
	s_add_i32 m0, s39, 0x18000
	ds_read_b128 v[194:197], v189 offset:49152
	ds_read_b128 v[198:201], v189 offset:50176
	ds_read_b128 v[202:205], v189 offset:51200
	ds_read_b128 v[206:209], v189 offset:52224
	s_add_u32 s98, s90, s40
	s_addc_u32 s99, s91, s41
	global_load_lds_dwordx4 v160, s[98:99]
	s_add_i32 m0, s39, 0x1a000
	s_nop 0
	global_load_lds_dwordx4 v156, s[98:99]
	s_barrier
	s_waitcnt lgkmcnt(0)
	v_mfma_f32_16x16x32_bf16 v[118:121], v[194:197], v[146:149], v[118:121]
	v_mfma_f32_16x16x32_bf16 v[94:97], v[202:205], v[146:149], v[94:97]
	v_mfma_f32_16x16x32_bf16 v[106:109], v[194:197], v[168:171], v[106:109]
	v_mfma_f32_16x16x32_bf16 v[90:93], v[202:205], v[168:171], v[90:93]
	v_mfma_f32_16x16x32_bf16 v[102:105], v[194:197], v[176:179], v[102:105]
	v_mfma_f32_16x16x32_bf16 v[82:85], v[202:205], v[176:179], v[82:85]
	v_mfma_f32_16x16x32_bf16 v[98:101], v[194:197], v[184:187], v[98:101]
	v_mfma_f32_16x16x32_bf16 v[86:89], v[202:205], v[184:187], v[86:89]
	v_mfma_f32_16x16x32_bf16 v[118:121], v[198:201], v[150:153], v[118:121]
	v_mfma_f32_16x16x32_bf16 v[94:97], v[206:209], v[150:153], v[94:97]
	v_mfma_f32_16x16x32_bf16 v[106:109], v[198:201], v[172:175], v[106:109]
	v_mfma_f32_16x16x32_bf16 v[90:93], v[206:209], v[172:175], v[90:93]
	v_mfma_f32_16x16x32_bf16 v[102:105], v[198:201], v[180:183], v[102:105]
	v_mfma_f32_16x16x32_bf16 v[82:85], v[206:209], v[180:183], v[82:85]
	v_mfma_f32_16x16x32_bf16 v[98:101], v[198:201], v[190:193], v[98:101]
	v_mfma_f32_16x16x32_bf16 v[86:89], v[206:209], v[190:193], v[86:89]
	s_mov_b32 m0, s95
	s_barrier
	ds_read_b128 v[146:149], v253 offset:49152
	ds_read_b128 v[150:153], v253 offset:50176
	ds_read_b128 v[168:171], v253 offset:51200
	ds_read_b128 v[172:175], v253 offset:52224
	ds_read_b128 v[176:179], v253 offset:53248
	ds_read_b128 v[180:183], v253 offset:54272
	ds_read_b128 v[184:187], v253 offset:55296
	ds_read_b128 v[190:193], v253 offset:56320
	s_add_u32 s98, s100, s40
	s_addc_u32 s99, s101, s41
	global_load_lds_dwordx4 v162, s[98:99]
	s_mov_b32 m0, s96
	s_nop 0
	global_load_lds_dwordx4 v158, s[98:99]
	s_waitcnt vmcnt(10)
	s_barrier
	s_waitcnt lgkmcnt(0)
	v_mfma_f32_16x16x32_bf16 v[62:65], v[130:133], v[146:149], v[62:65]
	v_mfma_f32_16x16x32_bf16 v[10:13], v[138:141], v[146:149], v[10:13]
	v_mfma_f32_16x16x32_bf16 v[58:61], v[130:133], v[168:171], v[58:61]
	v_mfma_f32_16x16x32_bf16 v[14:17], v[138:141], v[168:171], v[14:17]
	v_mfma_f32_16x16x32_bf16 v[54:57], v[130:133], v[176:179], v[54:57]
	v_mfma_f32_16x16x32_bf16 v[6:9], v[138:141], v[176:179], v[6:9]
	v_mfma_f32_16x16x32_bf16 v[42:45], v[130:133], v[184:187], v[42:45]
	v_mfma_f32_16x16x32_bf16 v[2:5], v[138:141], v[184:187], v[2:5]
	v_mfma_f32_16x16x32_bf16 v[62:65], v[134:137], v[150:153], v[62:65]
	v_mfma_f32_16x16x32_bf16 v[10:13], v[142:145], v[150:153], v[10:13]
	v_mfma_f32_16x16x32_bf16 v[58:61], v[134:137], v[172:175], v[58:61]
	v_mfma_f32_16x16x32_bf16 v[14:17], v[142:145], v[172:175], v[14:17]
	v_mfma_f32_16x16x32_bf16 v[54:57], v[134:137], v[180:183], v[54:57]
	v_mfma_f32_16x16x32_bf16 v[6:9], v[142:145], v[180:183], v[6:9]
	v_mfma_f32_16x16x32_bf16 v[42:45], v[134:137], v[190:193], v[42:45]
	v_mfma_f32_16x16x32_bf16 v[2:5], v[142:145], v[190:193], v[2:5]
	s_barrier
	s_add_u32 s6, s90, 0x40080
	s_addc_u32 s7, s91, 0
	s_add_i32 m0, s39, 0x1c000
	s_nop 0
	global_load_lds_dwordx4 v160, s[6:7]
	s_add_i32 m0, s39, 0x1e000
	s_nop 0
	global_load_lds_dwordx4 v156, s[6:7]
	ds_read_b128 v[130:133], v189
	ds_read_b128 v[134:137], v189 offset:1024
	ds_read_b128 v[138:141], v189 offset:2048
	ds_read_b128 v[142:145], v189 offset:3072
	s_waitcnt vmcnt(6)
	s_barrier
	v_mfma_f32_16x16x32_bf16 v[50:53], v[194:197], v[146:149], v[50:53]
	v_mfma_f32_16x16x32_bf16 v[26:29], v[202:205], v[146:149], v[26:29]
	v_mfma_f32_16x16x32_bf16 v[46:49], v[194:197], v[168:171], v[46:49]
	v_mfma_f32_16x16x32_bf16 v[30:33], v[202:205], v[168:171], v[30:33]
	v_mfma_f32_16x16x32_bf16 v[38:41], v[194:197], v[176:179], v[38:41]
	v_mfma_f32_16x16x32_bf16 v[22:25], v[202:205], v[176:179], v[22:25]
	v_mfma_f32_16x16x32_bf16 v[34:37], v[194:197], v[184:187], v[34:37]
	v_mfma_f32_16x16x32_bf16 v[18:21], v[202:205], v[184:187], v[18:21]
	v_mfma_f32_16x16x32_bf16 v[50:53], v[198:201], v[150:153], v[50:53]
	v_mfma_f32_16x16x32_bf16 v[26:29], v[206:209], v[150:153], v[26:29]
	v_mfma_f32_16x16x32_bf16 v[46:49], v[198:201], v[172:175], v[46:49]
	v_mfma_f32_16x16x32_bf16 v[30:33], v[206:209], v[172:175], v[30:33]
	v_mfma_f32_16x16x32_bf16 v[38:41], v[198:201], v[180:183], v[38:41]
	v_mfma_f32_16x16x32_bf16 v[22:25], v[206:209], v[180:183], v[22:25]
	v_mfma_f32_16x16x32_bf16 v[34:37], v[198:201], v[190:193], v[34:37]
	v_mfma_f32_16x16x32_bf16 v[18:21], v[206:209], v[190:193], v[18:21]
	s_add_i32 s45, s45, 2
	s_add_u32 s28, s28, 0x100
	s_addc_u32 s29, s29, 0
	s_mov_b64 s[6:7], s[88:89]
	s_add_u32 s88, s6, 0x100
	s_addc_u32 s89, s7, 0
	s_cmp_eq_u32 s45, 12
	s_cselect_b32 s93, s17, s89
	s_cselect_b32 s92, s22, s88
	s_cselect_b32 s91, s15, s29
	s_cselect_b32 s90, s23, s28
	s_cmp_gt_u32 s45, 13
	s_barrier
.LBB0_919:
	s_add_i32 m0, s43, 0xc000
	ds_read_b128 v[146:149], v253
	ds_read_b128 v[150:153], v253 offset:1024
	ds_read_b128 v[168:171], v253 offset:2048
	ds_read_b128 v[172:175], v253 offset:3072
	ds_read_b128 v[176:179], v253 offset:4096
	ds_read_b128 v[180:183], v253 offset:5120
	ds_read_b128 v[184:187], v253 offset:6144
	ds_read_b128 v[190:193], v253 offset:7168
	global_load_lds_dwordx4 v164, s[6:7]
	s_add_i32 m0, s43, 0xe000
	v_lshl_add_u64 v[154:155], s[6:7], 0, v[166:167]
	global_load_lds_dwordx4 v[154:155], off
	s_waitcnt lgkmcnt(8)
	s_barrier
	s_waitcnt lgkmcnt(0)
	v_mfma_f32_16x16x32_bf16 v[126:129], v[130:133], v[146:149], v[126:129]
	v_mfma_f32_16x16x32_bf16 v[70:73], v[138:141], v[146:149], v[70:73]
	v_mfma_f32_16x16x32_bf16 v[122:125], v[130:133], v[168:171], v[122:125]
	v_mfma_f32_16x16x32_bf16 v[74:77], v[138:141], v[168:171], v[74:77]
	v_mfma_f32_16x16x32_bf16 v[114:117], v[130:133], v[176:179], v[114:117]
	v_mfma_f32_16x16x32_bf16 v[66:69], v[138:141], v[176:179], v[66:69]
	v_mfma_f32_16x16x32_bf16 v[110:113], v[130:133], v[184:187], v[110:113]
	v_mfma_f32_16x16x32_bf16 v[78:81], v[138:141], v[184:187], v[78:81]
	v_mfma_f32_16x16x32_bf16 v[126:129], v[134:137], v[150:153], v[126:129]
	v_mfma_f32_16x16x32_bf16 v[70:73], v[142:145], v[150:153], v[70:73]
	v_mfma_f32_16x16x32_bf16 v[122:125], v[134:137], v[172:175], v[122:125]
	v_mfma_f32_16x16x32_bf16 v[74:77], v[142:145], v[172:175], v[74:77]
	v_mfma_f32_16x16x32_bf16 v[114:117], v[134:137], v[180:183], v[114:117]
	v_mfma_f32_16x16x32_bf16 v[66:69], v[142:145], v[180:183], v[66:69]
	v_mfma_f32_16x16x32_bf16 v[110:113], v[134:137], v[190:193], v[110:113]
	v_mfma_f32_16x16x32_bf16 v[78:81], v[142:145], v[190:193], v[78:81]
	s_barrier
	s_add_i32 m0, s39, 0x10000
	ds_read_b128 v[194:197], v189 offset:16384
	ds_read_b128 v[198:201], v189 offset:17408
	ds_read_b128 v[202:205], v189 offset:18432
	ds_read_b128 v[206:209], v189 offset:19456
	global_load_lds_dwordx4 v160, s[90:91]
	s_add_i32 m0, s39, 0x12000
	s_nop 0
	global_load_lds_dwordx4 v156, s[90:91]
	s_barrier
	s_waitcnt lgkmcnt(0)
	v_mfma_f32_16x16x32_bf16 v[118:121], v[194:197], v[146:149], v[118:121]
	v_mfma_f32_16x16x32_bf16 v[94:97], v[202:205], v[146:149], v[94:97]
	v_mfma_f32_16x16x32_bf16 v[106:109], v[194:197], v[168:171], v[106:109]
	v_mfma_f32_16x16x32_bf16 v[90:93], v[202:205], v[168:171], v[90:93]
	v_mfma_f32_16x16x32_bf16 v[102:105], v[194:197], v[176:179], v[102:105]
	v_mfma_f32_16x16x32_bf16 v[82:85], v[202:205], v[176:179], v[82:85]
	v_mfma_f32_16x16x32_bf16 v[98:101], v[194:197], v[184:187], v[98:101]
	v_mfma_f32_16x16x32_bf16 v[86:89], v[202:205], v[184:187], v[86:89]
	v_mfma_f32_16x16x32_bf16 v[118:121], v[198:201], v[150:153], v[118:121]
	v_mfma_f32_16x16x32_bf16 v[94:97], v[206:209], v[150:153], v[94:97]
	v_mfma_f32_16x16x32_bf16 v[106:109], v[198:201], v[172:175], v[106:109]
	v_mfma_f32_16x16x32_bf16 v[90:93], v[206:209], v[172:175], v[90:93]
	v_mfma_f32_16x16x32_bf16 v[102:105], v[198:201], v[180:183], v[102:105]
	v_mfma_f32_16x16x32_bf16 v[82:85], v[206:209], v[180:183], v[82:85]
	v_mfma_f32_16x16x32_bf16 v[98:101], v[198:201], v[190:193], v[98:101]
	v_mfma_f32_16x16x32_bf16 v[86:89], v[206:209], v[190:193], v[86:89]
	s_mov_b32 m0, s43
	s_mov_b64 s[100:101], s[92:93]
	s_barrier
	ds_read_b128 v[146:149], v253 offset:16384
	ds_read_b128 v[150:153], v253 offset:17408
	ds_read_b128 v[168:171], v253 offset:18432
	ds_read_b128 v[172:175], v253 offset:19456
	ds_read_b128 v[176:179], v253 offset:20480
	ds_read_b128 v[180:183], v253 offset:21504
	ds_read_b128 v[184:187], v253 offset:22528
	ds_read_b128 v[190:193], v253 offset:23552
	global_load_lds_dwordx4 v162, s[100:101]
	s_mov_b32 m0, s60
	s_nop 0
	global_load_lds_dwordx4 v158, s[100:101]
	s_waitcnt vmcnt(10)
	s_barrier
	s_waitcnt lgkmcnt(0)
	v_mfma_f32_16x16x32_bf16 v[62:65], v[130:133], v[146:149], v[62:65]
	v_mfma_f32_16x16x32_bf16 v[10:13], v[138:141], v[146:149], v[10:13]
	v_mfma_f32_16x16x32_bf16 v[58:61], v[130:133], v[168:171], v[58:61]
	v_mfma_f32_16x16x32_bf16 v[14:17], v[138:141], v[168:171], v[14:17]
	v_mfma_f32_16x16x32_bf16 v[54:57], v[130:133], v[176:179], v[54:57]
	v_mfma_f32_16x16x32_bf16 v[6:9], v[138:141], v[176:179], v[6:9]
	v_mfma_f32_16x16x32_bf16 v[42:45], v[130:133], v[184:187], v[42:45]
	v_mfma_f32_16x16x32_bf16 v[2:5], v[138:141], v[184:187], v[2:5]
	v_mfma_f32_16x16x32_bf16 v[62:65], v[134:137], v[150:153], v[62:65]
	v_mfma_f32_16x16x32_bf16 v[10:13], v[142:145], v[150:153], v[10:13]
	v_mfma_f32_16x16x32_bf16 v[58:61], v[134:137], v[172:175], v[58:61]
	v_mfma_f32_16x16x32_bf16 v[14:17], v[142:145], v[172:175], v[14:17]
	v_mfma_f32_16x16x32_bf16 v[54:57], v[134:137], v[180:183], v[54:57]
	v_mfma_f32_16x16x32_bf16 v[6:9], v[142:145], v[180:183], v[6:9]
	v_mfma_f32_16x16x32_bf16 v[42:45], v[134:137], v[190:193], v[42:45]
	v_mfma_f32_16x16x32_bf16 v[2:5], v[142:145], v[190:193], v[2:5]
	s_barrier
	s_add_u32 s6, s90, 0x40000
	s_addc_u32 s7, s91, 0
	s_add_i32 m0, s39, 0x14000
	s_nop 0
	global_load_lds_dwordx4 v160, s[6:7]
	s_add_i32 m0, s39, 0x16000
	s_nop 0
	global_load_lds_dwordx4 v156, s[6:7]
	ds_read_b128 v[130:133], v189 offset:32768
	ds_read_b128 v[134:137], v189 offset:33792
	ds_read_b128 v[138:141], v189 offset:34816
	ds_read_b128 v[142:145], v189 offset:35840
	s_waitcnt vmcnt(6)
	s_barrier
	v_mfma_f32_16x16x32_bf16 v[50:53], v[194:197], v[146:149], v[50:53]
	v_mfma_f32_16x16x32_bf16 v[26:29], v[202:205], v[146:149], v[26:29]
	v_mfma_f32_16x16x32_bf16 v[46:49], v[194:197], v[168:171], v[46:49]
	v_mfma_f32_16x16x32_bf16 v[30:33], v[202:205], v[168:171], v[30:33]
	v_mfma_f32_16x16x32_bf16 v[38:41], v[194:197], v[176:179], v[38:41]
	v_mfma_f32_16x16x32_bf16 v[22:25], v[202:205], v[176:179], v[22:25]
	v_mfma_f32_16x16x32_bf16 v[34:37], v[194:197], v[184:187], v[34:37]
	v_mfma_f32_16x16x32_bf16 v[18:21], v[202:205], v[184:187], v[18:21]
	v_mfma_f32_16x16x32_bf16 v[50:53], v[198:201], v[150:153], v[50:53]
	v_mfma_f32_16x16x32_bf16 v[26:29], v[206:209], v[150:153], v[26:29]
	v_mfma_f32_16x16x32_bf16 v[46:49], v[198:201], v[172:175], v[46:49]
	v_mfma_f32_16x16x32_bf16 v[30:33], v[206:209], v[172:175], v[30:33]
	v_mfma_f32_16x16x32_bf16 v[38:41], v[198:201], v[180:183], v[38:41]
	v_mfma_f32_16x16x32_bf16 v[22:25], v[206:209], v[180:183], v[22:25]
	v_mfma_f32_16x16x32_bf16 v[34:37], v[198:201], v[190:193], v[34:37]
	v_mfma_f32_16x16x32_bf16 v[18:21], v[206:209], v[190:193], v[18:21]
	s_barrier
	s_add_u32 s6, s92, 0x40000
	s_addc_u32 s7, s93, 0
	s_mov_b32 m0, s61
	ds_read_b128 v[146:149], v253 offset:32768
	ds_read_b128 v[150:153], v253 offset:33792
	ds_read_b128 v[168:171], v253 offset:34816
	ds_read_b128 v[172:175], v253 offset:35840
	ds_read_b128 v[176:179], v253 offset:36864
	ds_read_b128 v[180:183], v253 offset:37888
	ds_read_b128 v[184:187], v253 offset:38912
	ds_read_b128 v[190:193], v253 offset:39936
	global_load_lds_dwordx4 v162, s[6:7]
	s_mov_b32 m0, s72
	s_nop 0
	global_load_lds_dwordx4 v158, s[6:7]
	s_waitcnt lgkmcnt(8)
	s_barrier
	s_waitcnt lgkmcnt(0)
	v_mfma_f32_16x16x32_bf16 v[126:129], v[130:133], v[146:149], v[126:129]
	v_mfma_f32_16x16x32_bf16 v[70:73], v[138:141], v[146:149], v[70:73]
	v_mfma_f32_16x16x32_bf16 v[122:125], v[130:133], v[168:171], v[122:125]
	v_mfma_f32_16x16x32_bf16 v[74:77], v[138:141], v[168:171], v[74:77]
	v_mfma_f32_16x16x32_bf16 v[114:117], v[130:133], v[176:179], v[114:117]
	v_mfma_f32_16x16x32_bf16 v[66:69], v[138:141], v[176:179], v[66:69]
	v_mfma_f32_16x16x32_bf16 v[110:113], v[130:133], v[184:187], v[110:113]
	v_mfma_f32_16x16x32_bf16 v[78:81], v[138:141], v[184:187], v[78:81]
	v_mfma_f32_16x16x32_bf16 v[126:129], v[134:137], v[150:153], v[126:129]
	v_mfma_f32_16x16x32_bf16 v[70:73], v[142:145], v[150:153], v[70:73]
	v_mfma_f32_16x16x32_bf16 v[122:125], v[134:137], v[172:175], v[122:125]
	v_mfma_f32_16x16x32_bf16 v[74:77], v[142:145], v[172:175], v[74:77]
	v_mfma_f32_16x16x32_bf16 v[114:117], v[134:137], v[180:183], v[114:117]
	v_mfma_f32_16x16x32_bf16 v[66:69], v[142:145], v[180:183], v[66:69]
	v_mfma_f32_16x16x32_bf16 v[110:113], v[134:137], v[190:193], v[110:113]
	v_mfma_f32_16x16x32_bf16 v[78:81], v[142:145], v[190:193], v[78:81]
	s_barrier
	s_add_i32 m0, s39, 0x18000
	ds_read_b128 v[194:197], v189 offset:49152
	ds_read_b128 v[198:201], v189 offset:50176
	ds_read_b128 v[202:205], v189 offset:51200
	ds_read_b128 v[206:209], v189 offset:52224
	s_add_u32 s98, s90, s40
	s_addc_u32 s99, s91, s41
	global_load_lds_dwordx4 v160, s[98:99]
	s_add_i32 m0, s39, 0x1a000
	s_nop 0
	global_load_lds_dwordx4 v156, s[98:99]
	s_barrier
	s_waitcnt lgkmcnt(0)
	v_mfma_f32_16x16x32_bf16 v[118:121], v[194:197], v[146:149], v[118:121]
	v_mfma_f32_16x16x32_bf16 v[94:97], v[202:205], v[146:149], v[94:97]
	v_mfma_f32_16x16x32_bf16 v[106:109], v[194:197], v[168:171], v[106:109]
	v_mfma_f32_16x16x32_bf16 v[90:93], v[202:205], v[168:171], v[90:93]
	v_mfma_f32_16x16x32_bf16 v[102:105], v[194:197], v[176:179], v[102:105]
	v_mfma_f32_16x16x32_bf16 v[82:85], v[202:205], v[176:179], v[82:85]
	v_mfma_f32_16x16x32_bf16 v[98:101], v[194:197], v[184:187], v[98:101]
	v_mfma_f32_16x16x32_bf16 v[86:89], v[202:205], v[184:187], v[86:89]
	v_mfma_f32_16x16x32_bf16 v[118:121], v[198:201], v[150:153], v[118:121]
	v_mfma_f32_16x16x32_bf16 v[94:97], v[206:209], v[150:153], v[94:97]
	v_mfma_f32_16x16x32_bf16 v[106:109], v[198:201], v[172:175], v[106:109]
	v_mfma_f32_16x16x32_bf16 v[90:93], v[206:209], v[172:175], v[90:93]
	v_mfma_f32_16x16x32_bf16 v[102:105], v[198:201], v[180:183], v[102:105]
	v_mfma_f32_16x16x32_bf16 v[82:85], v[206:209], v[180:183], v[82:85]
	v_mfma_f32_16x16x32_bf16 v[98:101], v[198:201], v[190:193], v[98:101]
	v_mfma_f32_16x16x32_bf16 v[86:89], v[206:209], v[190:193], v[86:89]
	s_mov_b32 m0, s95
	s_barrier
	ds_read_b128 v[146:149], v253 offset:49152
	ds_read_b128 v[150:153], v253 offset:50176
	ds_read_b128 v[168:171], v253 offset:51200
	ds_read_b128 v[172:175], v253 offset:52224
	ds_read_b128 v[176:179], v253 offset:53248
	ds_read_b128 v[180:183], v253 offset:54272
	ds_read_b128 v[184:187], v253 offset:55296
	ds_read_b128 v[190:193], v253 offset:56320
	s_add_u32 s98, s100, s40
	s_addc_u32 s99, s101, s41
	global_load_lds_dwordx4 v162, s[98:99]
	s_mov_b32 m0, s96
	s_nop 0
	global_load_lds_dwordx4 v158, s[98:99]
	s_waitcnt vmcnt(10)
	s_barrier
	s_waitcnt lgkmcnt(0)
	v_mfma_f32_16x16x32_bf16 v[62:65], v[130:133], v[146:149], v[62:65]
	v_mfma_f32_16x16x32_bf16 v[10:13], v[138:141], v[146:149], v[10:13]
	v_mfma_f32_16x16x32_bf16 v[58:61], v[130:133], v[168:171], v[58:61]
	v_mfma_f32_16x16x32_bf16 v[14:17], v[138:141], v[168:171], v[14:17]
	v_mfma_f32_16x16x32_bf16 v[54:57], v[130:133], v[176:179], v[54:57]
	v_mfma_f32_16x16x32_bf16 v[6:9], v[138:141], v[176:179], v[6:9]
	v_mfma_f32_16x16x32_bf16 v[42:45], v[130:133], v[184:187], v[42:45]
	v_mfma_f32_16x16x32_bf16 v[2:5], v[138:141], v[184:187], v[2:5]
	v_mfma_f32_16x16x32_bf16 v[62:65], v[134:137], v[150:153], v[62:65]
	v_mfma_f32_16x16x32_bf16 v[10:13], v[142:145], v[150:153], v[10:13]
	v_mfma_f32_16x16x32_bf16 v[58:61], v[134:137], v[172:175], v[58:61]
	v_mfma_f32_16x16x32_bf16 v[14:17], v[142:145], v[172:175], v[14:17]
	v_mfma_f32_16x16x32_bf16 v[54:57], v[134:137], v[180:183], v[54:57]
	v_mfma_f32_16x16x32_bf16 v[6:9], v[142:145], v[180:183], v[6:9]
	v_mfma_f32_16x16x32_bf16 v[42:45], v[134:137], v[190:193], v[42:45]
	v_mfma_f32_16x16x32_bf16 v[2:5], v[142:145], v[190:193], v[2:5]
	s_barrier
	s_add_u32 s6, s90, 0x40080
	s_addc_u32 s7, s91, 0
	s_add_i32 m0, s39, 0x1c000
	s_nop 0
	global_load_lds_dwordx4 v160, s[6:7]
	s_add_i32 m0, s39, 0x1e000
	s_nop 0
	global_load_lds_dwordx4 v156, s[6:7]
	ds_read_b128 v[130:133], v189
	ds_read_b128 v[134:137], v189 offset:1024
	ds_read_b128 v[138:141], v189 offset:2048
	ds_read_b128 v[142:145], v189 offset:3072
	s_waitcnt vmcnt(6)
	s_barrier
	v_mfma_f32_16x16x32_bf16 v[50:53], v[194:197], v[146:149], v[50:53]
	v_mfma_f32_16x16x32_bf16 v[26:29], v[202:205], v[146:149], v[26:29]
	v_mfma_f32_16x16x32_bf16 v[46:49], v[194:197], v[168:171], v[46:49]
	v_mfma_f32_16x16x32_bf16 v[30:33], v[202:205], v[168:171], v[30:33]
	v_mfma_f32_16x16x32_bf16 v[38:41], v[194:197], v[176:179], v[38:41]
	v_mfma_f32_16x16x32_bf16 v[22:25], v[202:205], v[176:179], v[22:25]
	v_mfma_f32_16x16x32_bf16 v[34:37], v[194:197], v[184:187], v[34:37]
	v_mfma_f32_16x16x32_bf16 v[18:21], v[202:205], v[184:187], v[18:21]
	v_mfma_f32_16x16x32_bf16 v[50:53], v[198:201], v[150:153], v[50:53]
	v_mfma_f32_16x16x32_bf16 v[26:29], v[206:209], v[150:153], v[26:29]
	v_mfma_f32_16x16x32_bf16 v[46:49], v[198:201], v[172:175], v[46:49]
	v_mfma_f32_16x16x32_bf16 v[30:33], v[206:209], v[172:175], v[30:33]
	v_mfma_f32_16x16x32_bf16 v[38:41], v[198:201], v[180:183], v[38:41]
	v_mfma_f32_16x16x32_bf16 v[22:25], v[206:209], v[180:183], v[22:25]
	v_mfma_f32_16x16x32_bf16 v[34:37], v[198:201], v[190:193], v[34:37]
	v_mfma_f32_16x16x32_bf16 v[18:21], v[206:209], v[190:193], v[18:21]
	s_add_i32 s45, s45, 2
	s_add_u32 s28, s28, 0x100
	s_addc_u32 s29, s29, 0
	s_mov_b64 s[6:7], s[88:89]
	s_add_u32 s88, s6, 0x100
	s_addc_u32 s89, s7, 0
	s_cmp_eq_u32 s45, 12
	s_cselect_b32 s93, s17, s89
	s_cselect_b32 s92, s22, s88
	s_cselect_b32 s91, s15, s29
	s_cselect_b32 s90, s23, s28
	s_cmp_gt_u32 s45, 13
	s_barrier
	s_cbranch_scc0 .LBB0_919
	s_waitcnt lgkmcnt(0)
	v_mov_b32_e32 v131, v252
	s_lshl_b32 s88, s5, 7
	v_bfe_u32 v130, v131, 4, 2
	v_and_b32_e32 v134, 15, v131
	v_lshlrev_b32_e32 v0, 4, v130
	s_ashr_i32 s89, s88, 31
	s_lshl_b32 s15, s4, 8
	v_or3_b32 v135, v0, s97, v134
	s_lshl_b64 s[4:5], s[88:89], 2
	v_lshrrev_b32_e32 v140, 1, v135
	s_add_u32 s4, s73, s4
	s_addc_u32 s5, s74, s5
	v_lshlrev_b32_e32 v0, 2, v140
	v_and_b32_e32 v144, 1, v131
	v_lshl_add_u64 v[132:133], s[4:5], 0, v[0:1]
	v_cmp_eq_u32_e32 vcc, 1, v144
	v_mov_b32_e32 v0, 0xb00
	s_movk_i32 s4, 0x5000
	v_cndmask_b32_e32 v141, 0, v0, vcc
	v_lshlrev_b32_e32 v0, 2, v141
	v_lshl_add_u64 v[132:133], v[132:133], 0, v[0:1]
	v_add_co_u32_e32 v138, vcc, s4, v132
	s_mov_b32 s4, 0xb000
	s_nop 0
	v_addc_co_u32_e32 v139, vcc, 0, v133, vcc
	global_load_dword v136, v[132:133], off
	global_load_dword v137, v[138:139], off offset:2048
	v_add_co_u32_e32 v132, vcc, s4, v132
	v_add_u32_e32 v0, s88, v141
	s_nop 0
	v_addc_co_u32_e32 v133, vcc, 0, v133, vcc
	global_load_dword v138, v[132:133], off
	v_or_b32_e32 v132, v140, v0
	v_ashrrev_i32_e32 v133, 31, v132
	v_lshl_add_u64 v[132:133], v[132:133], 2, s[12:13]
	global_load_dword v139, v[132:133], off
	v_lshl_add_u32 v152, v135, 4, s78
	v_and_b32_e32 v135, 63, v131
	v_cmp_eq_u32_e32 vcc, 0, v144
	v_or_b32_e32 v0, s97, v135
	v_lshrrev_b32_e32 v0, 1, v0
	v_and_or_b32 v131, v0, 63, s55
	v_add_u32_e32 v132, s15, v131
	v_ashrrev_i32_e32 v133, 31, v132
	v_lshlrev_b64 v[132:133], 6, v[132:133]
	v_lshl_add_u64 v[132:133], s[10:11], 0, v[132:133]
	v_lshlrev_b32_e32 v0, 5, v144
	v_lshl_add_u64 v[132:133], v[132:133], 0, v[0:1]
	global_load_dwordx4 v[148:151], v[132:133], off offset:16
	global_load_dwordx4 v[140:143], v[132:133], off
	s_waitcnt vmcnt(2)
	ds_write_b128 v152, v[136:139]
	s_waitcnt vmcnt(0)
	v_add_f32_e32 v133, v150, v151
	v_add_f32_e32 v0, v140, v141
	v_add_f32_e32 v132, v142, v143
	v_add_f32_e32 v0, v0, v132
	v_add_f32_e32 v132, v148, v149
	v_add_f32_e32 v132, v132, v133
	v_add_f32_e32 v0, v0, v132
	v_lshlrev_b32_e32 v132, 2, v135
	v_xor_b32_e32 v132, 4, v132
	ds_bpermute_b32 v132, v132, v0
	s_and_saveexec_b64 s[4:5], vcc
	s_cbranch_execz .LBB0_922
	s_waitcnt lgkmcnt(0)
	v_add_f32_e32 v0, v0, v132
	v_mov_b32_e32 v132, 0x358637bd
	v_fmamk_f32 v0, v0, 0x3a800000, v132
	s_mov_b32 s6, 0x800000
	v_mul_f32_e32 v132, 0x4b800000, v0
	v_cmp_gt_f32_e32 vcc, s6, v0
	v_lshl_add_u32 v131, v131, 2, 0
	v_add_u32_e32 v131, 0x20000, v131
	v_cndmask_b32_e32 v0, v0, v132, vcc
	v_rsq_f32_e32 v0, v0
	s_nop 0
	v_mul_f32_e32 v132, 0x45800000, v0
	v_cndmask_b32_e32 v0, v0, v132, vcc
	ds_write_b32 v131, v0

.LBB0_1089:
	s_add_u32 s34, s84, 0x100
	s_addc_u32 s78, s85, 0
	s_mov_b32 s79, -2
	s_waitcnt lgkmcnt(0)
	s_add_i32 s90, 0, 0x10000
	v_add_u32_e32 v142, s90, v212
	v_add_u32_e32 v189, 0x10000, v212
	ds_read_b128 v[130:133], v142
	ds_read_b128 v[134:137], v142 offset:1024
	ds_read_b128 v[138:141], v142 offset:2048
	ds_read_b128 v[142:145], v142 offset:3072
	s_add_u32 s84, s16, 0x100
	s_addc_u32 s85, s17, 0
	s_cmp_eq_u32 s79, 40
	s_cselect_b32 s89, s5, s85
	s_cselect_b32 s88, s4, s84
	s_cselect_b32 s87, s7, s78
	s_cselect_b32 s86, s6, s34
	v_lshl_add_u64 v[178:179], s[16:17], 0, v[196:197]
	s_add_i32 m0, s39, 0xc000
	ds_read_b128 v[146:149], v213
	ds_read_b128 v[150:153], v213 offset:1024
	ds_read_b128 v[154:157], v213 offset:2048
	ds_read_b128 v[158:161], v213 offset:3072
	ds_read_b128 v[162:165], v213 offset:4096
	ds_read_b128 v[166:169], v213 offset:5120
	ds_read_b128 v[170:173], v213 offset:6144
	ds_read_b128 v[174:177], v213 offset:7168
	global_load_lds_dwordx4 v[178:179], off
	s_add_i32 m0, s39, 0xe000
	v_lshl_add_u64 v[178:179], s[16:17], 0, v[198:199]
	global_load_lds_dwordx4 v[178:179], off
	s_waitcnt lgkmcnt(8)
	s_barrier
	s_waitcnt lgkmcnt(0)
	v_mfma_f32_16x16x32_bf16 v[126:129], v[130:133], v[146:149], 0
	v_mfma_f32_16x16x32_bf16 v[122:125], v[138:141], v[146:149], 0
	v_mfma_f32_16x16x32_bf16 v[110:113], v[130:133], v[154:157], 0
	v_mfma_f32_16x16x32_bf16 v[106:109], v[138:141], v[154:157], 0
	v_mfma_f32_16x16x32_bf16 v[94:97], v[130:133], v[162:165], 0
	v_mfma_f32_16x16x32_bf16 v[90:93], v[138:141], v[162:165], 0
	v_mfma_f32_16x16x32_bf16 v[78:81], v[130:133], v[170:173], 0
	v_mfma_f32_16x16x32_bf16 v[74:77], v[138:141], v[170:173], 0
	v_mfma_f32_16x16x32_bf16 v[126:129], v[134:137], v[150:153], v[126:129]
	v_mfma_f32_16x16x32_bf16 v[122:125], v[142:145], v[150:153], v[122:125]
	v_mfma_f32_16x16x32_bf16 v[110:113], v[134:137], v[158:161], v[110:113]
	v_mfma_f32_16x16x32_bf16 v[106:109], v[142:145], v[158:161], v[106:109]
	v_mfma_f32_16x16x32_bf16 v[94:97], v[134:137], v[166:169], v[94:97]
	v_mfma_f32_16x16x32_bf16 v[90:93], v[142:145], v[166:169], v[90:93]
	v_mfma_f32_16x16x32_bf16 v[78:81], v[134:137], v[174:177], v[78:81]
	v_mfma_f32_16x16x32_bf16 v[74:77], v[142:145], v[174:177], v[74:77]
	s_barrier
	ds_read_b128 v[178:181], v189 offset:16384
	ds_read_b128 v[182:185], v189 offset:17408
	ds_read_b128 v[200:203], v189 offset:18432
	ds_read_b128 v[204:207], v189 offset:19456
	s_add_i32 m0, s38, 0x10000
	global_load_lds_dwordx4 v0, s[86:87]
	s_add_i32 m0, s38, 0x12000
	s_nop 0
	global_load_lds_dwordx4 v194, s[86:87]
	s_barrier
	s_waitcnt lgkmcnt(0)
	v_mfma_f32_16x16x32_bf16 v[118:121], v[178:181], v[146:149], 0
	v_mfma_f32_16x16x32_bf16 v[114:117], v[200:203], v[146:149], 0
	v_mfma_f32_16x16x32_bf16 v[102:105], v[178:181], v[154:157], 0
	v_mfma_f32_16x16x32_bf16 v[98:101], v[200:203], v[154:157], 0
	v_mfma_f32_16x16x32_bf16 v[86:89], v[178:181], v[162:165], 0
	v_mfma_f32_16x16x32_bf16 v[82:85], v[200:203], v[162:165], 0
	v_mfma_f32_16x16x32_bf16 v[70:73], v[178:181], v[170:173], 0
	v_mfma_f32_16x16x32_bf16 v[66:69], v[200:203], v[170:173], 0
	v_mfma_f32_16x16x32_bf16 v[118:121], v[182:185], v[150:153], v[118:121]
	v_mfma_f32_16x16x32_bf16 v[114:117], v[204:207], v[150:153], v[114:117]
	v_mfma_f32_16x16x32_bf16 v[102:105], v[182:185], v[158:161], v[102:105]
	v_mfma_f32_16x16x32_bf16 v[98:101], v[204:207], v[158:161], v[98:101]
	v_mfma_f32_16x16x32_bf16 v[86:89], v[182:185], v[166:169], v[86:89]
	v_mfma_f32_16x16x32_bf16 v[82:85], v[204:207], v[166:169], v[82:85]
	v_mfma_f32_16x16x32_bf16 v[70:73], v[182:185], v[174:177], v[70:73]
	v_mfma_f32_16x16x32_bf16 v[66:69], v[204:207], v[174:177], v[66:69]
	s_mov_b32 m0, s39
	s_mov_b64 s[100:101], s[88:89]
	s_barrier
	ds_read_b128 v[146:149], v213 offset:16384
	ds_read_b128 v[150:153], v213 offset:17408
	ds_read_b128 v[154:157], v213 offset:18432
	ds_read_b128 v[158:161], v213 offset:19456
	ds_read_b128 v[162:165], v213 offset:20480
	ds_read_b128 v[166:169], v213 offset:21504
	ds_read_b128 v[170:173], v213 offset:22528
	ds_read_b128 v[174:177], v213 offset:23552
	global_load_lds_dwordx4 v190, s[100:101]
	s_mov_b32 m0, s42
	s_nop 0
	global_load_lds_dwordx4 v192, s[100:101]
	s_waitcnt vmcnt(10)
	s_barrier
	s_waitcnt lgkmcnt(0)
	v_mfma_f32_16x16x32_bf16 v[62:65], v[130:133], v[146:149], 0
	v_mfma_f32_16x16x32_bf16 v[58:61], v[138:141], v[146:149], 0
	v_mfma_f32_16x16x32_bf16 v[46:49], v[130:133], v[154:157], 0
	v_mfma_f32_16x16x32_bf16 v[42:45], v[138:141], v[154:157], 0
	v_mfma_f32_16x16x32_bf16 v[30:33], v[130:133], v[162:165], 0
	v_mfma_f32_16x16x32_bf16 v[26:29], v[138:141], v[162:165], 0
	v_mfma_f32_16x16x32_bf16 v[14:17], v[130:133], v[170:173], 0
	v_mfma_f32_16x16x32_bf16 v[10:13], v[138:141], v[170:173], 0
	v_mfma_f32_16x16x32_bf16 v[62:65], v[134:137], v[150:153], v[62:65]
	v_mfma_f32_16x16x32_bf16 v[58:61], v[142:145], v[150:153], v[58:61]
	v_mfma_f32_16x16x32_bf16 v[46:49], v[134:137], v[158:161], v[46:49]
	v_mfma_f32_16x16x32_bf16 v[42:45], v[142:145], v[158:161], v[42:45]
	v_mfma_f32_16x16x32_bf16 v[30:33], v[134:137], v[166:169], v[30:33]
	v_mfma_f32_16x16x32_bf16 v[26:29], v[142:145], v[166:169], v[26:29]
	v_mfma_f32_16x16x32_bf16 v[14:17], v[134:137], v[174:177], v[14:17]
	v_mfma_f32_16x16x32_bf16 v[10:13], v[142:145], v[174:177], v[10:13]
	s_barrier
	s_add_u32 s16, s86, 0xb0000
	s_addc_u32 s17, s87, 0
	s_add_i32 m0, s38, 0x14000
	s_nop 0
	global_load_lds_dwordx4 v0, s[16:17]
	s_add_i32 m0, s38, 0x16000
	s_nop 0
	global_load_lds_dwordx4 v194, s[16:17]
	s_add_i32 s90, 0, 0x18000
	v_add_u32_e32 v142, s90, v212
	ds_read_b128 v[130:133], v142
	ds_read_b128 v[134:137], v142 offset:1024
	ds_read_b128 v[138:141], v142 offset:2048
	ds_read_b128 v[142:145], v142 offset:3072
	s_waitcnt vmcnt(6)
	s_barrier
	v_mfma_f32_16x16x32_bf16 v[54:57], v[178:181], v[146:149], 0
	v_mfma_f32_16x16x32_bf16 v[50:53], v[200:203], v[146:149], 0
	v_mfma_f32_16x16x32_bf16 v[38:41], v[178:181], v[154:157], 0
	v_mfma_f32_16x16x32_bf16 v[34:37], v[200:203], v[154:157], 0
	v_mfma_f32_16x16x32_bf16 v[22:25], v[178:181], v[162:165], 0
	v_mfma_f32_16x16x32_bf16 v[18:21], v[200:203], v[162:165], 0
	v_mfma_f32_16x16x32_bf16 v[6:9], v[178:181], v[170:173], 0
	v_mfma_f32_16x16x32_bf16 v[2:5], v[200:203], v[170:173], 0
	v_mfma_f32_16x16x32_bf16 v[54:57], v[182:185], v[150:153], v[54:57]
	v_mfma_f32_16x16x32_bf16 v[50:53], v[204:207], v[150:153], v[50:53]
	v_mfma_f32_16x16x32_bf16 v[38:41], v[182:185], v[158:161], v[38:41]
	v_mfma_f32_16x16x32_bf16 v[34:37], v[204:207], v[158:161], v[34:37]
	v_mfma_f32_16x16x32_bf16 v[22:25], v[182:185], v[166:169], v[22:25]
	v_mfma_f32_16x16x32_bf16 v[18:21], v[204:207], v[166:169], v[18:21]
	v_mfma_f32_16x16x32_bf16 v[6:9], v[182:185], v[174:177], v[6:9]
	v_mfma_f32_16x16x32_bf16 v[2:5], v[204:207], v[174:177], v[2:5]
	s_barrier
	s_add_u32 s16, s88, 0xb0000
	s_addc_u32 s17, s89, 0
	s_mov_b32 m0, s43
	ds_read_b128 v[146:149], v213 offset:32768
	ds_read_b128 v[150:153], v213 offset:33792
	ds_read_b128 v[154:157], v213 offset:34816
	ds_read_b128 v[158:161], v213 offset:35840
	ds_read_b128 v[162:165], v213 offset:36864
	ds_read_b128 v[166:169], v213 offset:37888
	ds_read_b128 v[170:173], v213 offset:38912
	ds_read_b128 v[174:177], v213 offset:39936
	global_load_lds_dwordx4 v190, s[16:17]
	s_mov_b32 m0, s44
	s_nop 0
	global_load_lds_dwordx4 v192, s[16:17]
	s_waitcnt lgkmcnt(8)
	s_barrier
	s_waitcnt lgkmcnt(0)
	v_mfma_f32_16x16x32_bf16 v[126:129], v[130:133], v[146:149], v[126:129]
	v_mfma_f32_16x16x32_bf16 v[122:125], v[138:141], v[146:149], v[122:125]
	v_mfma_f32_16x16x32_bf16 v[110:113], v[130:133], v[154:157], v[110:113]
	v_mfma_f32_16x16x32_bf16 v[106:109], v[138:141], v[154:157], v[106:109]
	v_mfma_f32_16x16x32_bf16 v[94:97], v[130:133], v[162:165], v[94:97]
	v_mfma_f32_16x16x32_bf16 v[90:93], v[138:141], v[162:165], v[90:93]
	v_mfma_f32_16x16x32_bf16 v[78:81], v[130:133], v[170:173], v[78:81]
	v_mfma_f32_16x16x32_bf16 v[74:77], v[138:141], v[170:173], v[74:77]
	v_mfma_f32_16x16x32_bf16 v[126:129], v[134:137], v[150:153], v[126:129]
	v_mfma_f32_16x16x32_bf16 v[122:125], v[142:145], v[150:153], v[122:125]
	v_mfma_f32_16x16x32_bf16 v[110:113], v[134:137], v[158:161], v[110:113]
	v_mfma_f32_16x16x32_bf16 v[106:109], v[142:145], v[158:161], v[106:109]
	v_mfma_f32_16x16x32_bf16 v[94:97], v[134:137], v[166:169], v[94:97]
	v_mfma_f32_16x16x32_bf16 v[90:93], v[142:145], v[166:169], v[90:93]
	v_mfma_f32_16x16x32_bf16 v[78:81], v[134:137], v[174:177], v[78:81]
	v_mfma_f32_16x16x32_bf16 v[74:77], v[142:145], v[174:177], v[74:77]
	s_barrier
	s_add_i32 s88, 0, 0x1c000
	v_add_u32_e32 v204, s88, v212
	s_add_i32 m0, s38, 0x18000
	ds_read_b128 v[178:181], v204
	ds_read_b128 v[182:185], v204 offset:1024
	ds_read_b128 v[200:203], v204 offset:2048
	ds_read_b128 v[204:207], v204 offset:3072
	s_add_u32 s98, s86, s40
	s_addc_u32 s99, s87, s41
	global_load_lds_dwordx4 v0, s[98:99]
	s_add_i32 m0, s38, 0x1a000
	s_nop 0
	global_load_lds_dwordx4 v194, s[98:99]
	s_barrier
	s_waitcnt lgkmcnt(0)
	v_mfma_f32_16x16x32_bf16 v[118:121], v[178:181], v[146:149], v[118:121]
	v_mfma_f32_16x16x32_bf16 v[114:117], v[200:203], v[146:149], v[114:117]
	v_mfma_f32_16x16x32_bf16 v[102:105], v[178:181], v[154:157], v[102:105]
	v_mfma_f32_16x16x32_bf16 v[98:101], v[200:203], v[154:157], v[98:101]
	v_mfma_f32_16x16x32_bf16 v[86:89], v[178:181], v[162:165], v[86:89]
	v_mfma_f32_16x16x32_bf16 v[82:85], v[200:203], v[162:165], v[82:85]
	v_mfma_f32_16x16x32_bf16 v[70:73], v[178:181], v[170:173], v[70:73]
	v_mfma_f32_16x16x32_bf16 v[66:69], v[200:203], v[170:173], v[66:69]
	v_mfma_f32_16x16x32_bf16 v[118:121], v[182:185], v[150:153], v[118:121]
	v_mfma_f32_16x16x32_bf16 v[114:117], v[204:207], v[150:153], v[114:117]
	v_mfma_f32_16x16x32_bf16 v[102:105], v[182:185], v[158:161], v[102:105]
	v_mfma_f32_16x16x32_bf16 v[98:101], v[204:207], v[158:161], v[98:101]
	v_mfma_f32_16x16x32_bf16 v[86:89], v[182:185], v[166:169], v[86:89]
	v_mfma_f32_16x16x32_bf16 v[82:85], v[204:207], v[166:169], v[82:85]
	v_mfma_f32_16x16x32_bf16 v[70:73], v[182:185], v[174:177], v[70:73]
	v_mfma_f32_16x16x32_bf16 v[66:69], v[204:207], v[174:177], v[66:69]
	s_mov_b32 m0, s60
	s_barrier
	ds_read_b128 v[146:149], v213 offset:49152
	ds_read_b128 v[150:153], v213 offset:50176
	ds_read_b128 v[154:157], v213 offset:51200
	ds_read_b128 v[158:161], v213 offset:52224
	ds_read_b128 v[162:165], v213 offset:53248
	ds_read_b128 v[166:169], v213 offset:54272
	ds_read_b128 v[170:173], v213 offset:55296
	ds_read_b128 v[174:177], v213 offset:56320
	s_add_u32 s98, s100, s40
	s_addc_u32 s99, s101, s41
	global_load_lds_dwordx4 v190, s[98:99]
	s_mov_b32 m0, s61
	s_nop 0
	global_load_lds_dwordx4 v192, s[98:99]
	s_waitcnt vmcnt(10)
	s_barrier
	s_waitcnt lgkmcnt(0)
	v_mfma_f32_16x16x32_bf16 v[62:65], v[130:133], v[146:149], v[62:65]
	v_mfma_f32_16x16x32_bf16 v[58:61], v[138:141], v[146:149], v[58:61]
	v_mfma_f32_16x16x32_bf16 v[46:49], v[130:133], v[154:157], v[46:49]
	v_mfma_f32_16x16x32_bf16 v[42:45], v[138:141], v[154:157], v[42:45]
	v_mfma_f32_16x16x32_bf16 v[30:33], v[130:133], v[162:165], v[30:33]
	v_mfma_f32_16x16x32_bf16 v[26:29], v[138:141], v[162:165], v[26:29]
	v_mfma_f32_16x16x32_bf16 v[14:17], v[130:133], v[170:173], v[14:17]
	v_mfma_f32_16x16x32_bf16 v[10:13], v[138:141], v[170:173], v[10:13]
	v_mfma_f32_16x16x32_bf16 v[62:65], v[134:137], v[150:153], v[62:65]
	v_mfma_f32_16x16x32_bf16 v[58:61], v[142:145], v[150:153], v[58:61]
	v_mfma_f32_16x16x32_bf16 v[46:49], v[134:137], v[158:161], v[46:49]
	v_mfma_f32_16x16x32_bf16 v[42:45], v[142:145], v[158:161], v[42:45]
	v_mfma_f32_16x16x32_bf16 v[30:33], v[134:137], v[166:169], v[30:33]
	v_mfma_f32_16x16x32_bf16 v[26:29], v[142:145], v[166:169], v[26:29]
	v_mfma_f32_16x16x32_bf16 v[14:17], v[134:137], v[174:177], v[14:17]
	v_mfma_f32_16x16x32_bf16 v[10:13], v[142:145], v[174:177], v[10:13]
	s_barrier
	s_add_u32 s16, s86, 0xb0080
	s_addc_u32 s17, s87, 0
	s_add_i32 m0, s38, 0x1c000
	s_nop 0
	global_load_lds_dwordx4 v0, s[16:17]
	s_add_i32 m0, s38, 0x1e000
	s_nop 0
	global_load_lds_dwordx4 v194, s[16:17]
	ds_read_b128 v[130:133], v189
	ds_read_b128 v[134:137], v189 offset:1024
	ds_read_b128 v[138:141], v189 offset:2048
	ds_read_b128 v[142:145], v189 offset:3072
	s_waitcnt vmcnt(6)
	s_barrier
	v_mfma_f32_16x16x32_bf16 v[54:57], v[178:181], v[146:149], v[54:57]
	v_mfma_f32_16x16x32_bf16 v[50:53], v[200:203], v[146:149], v[50:53]
	v_mfma_f32_16x16x32_bf16 v[38:41], v[178:181], v[154:157], v[38:41]
	v_mfma_f32_16x16x32_bf16 v[34:37], v[200:203], v[154:157], v[34:37]
	v_mfma_f32_16x16x32_bf16 v[22:25], v[178:181], v[162:165], v[22:25]
	v_mfma_f32_16x16x32_bf16 v[18:21], v[200:203], v[162:165], v[18:21]
	v_mfma_f32_16x16x32_bf16 v[6:9], v[178:181], v[170:173], v[6:9]
	v_mfma_f32_16x16x32_bf16 v[2:5], v[200:203], v[170:173], v[2:5]
	v_mfma_f32_16x16x32_bf16 v[54:57], v[182:185], v[150:153], v[54:57]
	v_mfma_f32_16x16x32_bf16 v[50:53], v[204:207], v[150:153], v[50:53]
	v_mfma_f32_16x16x32_bf16 v[38:41], v[182:185], v[158:161], v[38:41]
	v_mfma_f32_16x16x32_bf16 v[34:37], v[204:207], v[158:161], v[34:37]
	v_mfma_f32_16x16x32_bf16 v[22:25], v[182:185], v[166:169], v[22:25]
	v_mfma_f32_16x16x32_bf16 v[18:21], v[204:207], v[166:169], v[18:21]
	v_mfma_f32_16x16x32_bf16 v[6:9], v[182:185], v[174:177], v[6:9]
	v_mfma_f32_16x16x32_bf16 v[2:5], v[204:207], v[174:177], v[2:5]
	s_add_i32 s79, s79, 2
	s_add_u32 s34, s34, 0x100
	s_addc_u32 s78, s78, 0
	s_mov_b64 s[16:17], s[84:85]
	s_add_u32 s84, s16, 0x100
	s_addc_u32 s85, s17, 0
	s_cmp_eq_u32 s79, 40
	s_cselect_b32 s89, s5, s85
	s_cselect_b32 s88, s4, s84
	s_cselect_b32 s87, s7, s78
	s_cselect_b32 s86, s6, s34
	s_cmp_gt_u32 s79, 41
	s_barrier
.LBB0_1090:
	v_lshl_add_u64 v[178:179], s[16:17], 0, v[196:197]
	s_add_i32 m0, s39, 0xc000
	ds_read_b128 v[146:149], v213
	ds_read_b128 v[150:153], v213 offset:1024
	ds_read_b128 v[154:157], v213 offset:2048
	ds_read_b128 v[158:161], v213 offset:3072
	ds_read_b128 v[162:165], v213 offset:4096
	ds_read_b128 v[166:169], v213 offset:5120
	ds_read_b128 v[170:173], v213 offset:6144
	ds_read_b128 v[174:177], v213 offset:7168
	global_load_lds_dwordx4 v[178:179], off
	s_add_i32 m0, s39, 0xe000
	v_lshl_add_u64 v[178:179], s[16:17], 0, v[198:199]
	global_load_lds_dwordx4 v[178:179], off
	s_waitcnt lgkmcnt(8)
	s_barrier
	s_waitcnt lgkmcnt(0)
	v_mfma_f32_16x16x32_bf16 v[126:129], v[130:133], v[146:149], v[126:129]
	v_mfma_f32_16x16x32_bf16 v[122:125], v[138:141], v[146:149], v[122:125]
	v_mfma_f32_16x16x32_bf16 v[110:113], v[130:133], v[154:157], v[110:113]
	v_mfma_f32_16x16x32_bf16 v[106:109], v[138:141], v[154:157], v[106:109]
	v_mfma_f32_16x16x32_bf16 v[94:97], v[130:133], v[162:165], v[94:97]
	v_mfma_f32_16x16x32_bf16 v[90:93], v[138:141], v[162:165], v[90:93]
	v_mfma_f32_16x16x32_bf16 v[78:81], v[130:133], v[170:173], v[78:81]
	v_mfma_f32_16x16x32_bf16 v[74:77], v[138:141], v[170:173], v[74:77]
	v_mfma_f32_16x16x32_bf16 v[126:129], v[134:137], v[150:153], v[126:129]
	v_mfma_f32_16x16x32_bf16 v[122:125], v[142:145], v[150:153], v[122:125]
	v_mfma_f32_16x16x32_bf16 v[110:113], v[134:137], v[158:161], v[110:113]
	v_mfma_f32_16x16x32_bf16 v[106:109], v[142:145], v[158:161], v[106:109]
	v_mfma_f32_16x16x32_bf16 v[94:97], v[134:137], v[166:169], v[94:97]
	v_mfma_f32_16x16x32_bf16 v[90:93], v[142:145], v[166:169], v[90:93]
	v_mfma_f32_16x16x32_bf16 v[78:81], v[134:137], v[174:177], v[78:81]
	v_mfma_f32_16x16x32_bf16 v[74:77], v[142:145], v[174:177], v[74:77]
	s_barrier
	ds_read_b128 v[178:181], v189 offset:16384
	ds_read_b128 v[182:185], v189 offset:17408
	ds_read_b128 v[200:203], v189 offset:18432
	ds_read_b128 v[204:207], v189 offset:19456
	s_add_i32 m0, s38, 0x10000
	global_load_lds_dwordx4 v0, s[86:87]
	s_add_i32 m0, s38, 0x12000
	s_nop 0
	global_load_lds_dwordx4 v194, s[86:87]
	s_barrier
	s_waitcnt lgkmcnt(0)
	v_mfma_f32_16x16x32_bf16 v[118:121], v[178:181], v[146:149], v[118:121]
	v_mfma_f32_16x16x32_bf16 v[114:117], v[200:203], v[146:149], v[114:117]
	v_mfma_f32_16x16x32_bf16 v[102:105], v[178:181], v[154:157], v[102:105]
	v_mfma_f32_16x16x32_bf16 v[98:101], v[200:203], v[154:157], v[98:101]
	v_mfma_f32_16x16x32_bf16 v[86:89], v[178:181], v[162:165], v[86:89]
	v_mfma_f32_16x16x32_bf16 v[82:85], v[200:203], v[162:165], v[82:85]
	v_mfma_f32_16x16x32_bf16 v[70:73], v[178:181], v[170:173], v[70:73]
	v_mfma_f32_16x16x32_bf16 v[66:69], v[200:203], v[170:173], v[66:69]
	v_mfma_f32_16x16x32_bf16 v[118:121], v[182:185], v[150:153], v[118:121]
	v_mfma_f32_16x16x32_bf16 v[114:117], v[204:207], v[150:153], v[114:117]
	v_mfma_f32_16x16x32_bf16 v[102:105], v[182:185], v[158:161], v[102:105]
	v_mfma_f32_16x16x32_bf16 v[98:101], v[204:207], v[158:161], v[98:101]
	v_mfma_f32_16x16x32_bf16 v[86:89], v[182:185], v[166:169], v[86:89]
	v_mfma_f32_16x16x32_bf16 v[82:85], v[204:207], v[166:169], v[82:85]
	v_mfma_f32_16x16x32_bf16 v[70:73], v[182:185], v[174:177], v[70:73]
	v_mfma_f32_16x16x32_bf16 v[66:69], v[204:207], v[174:177], v[66:69]
	s_mov_b32 m0, s39
	s_mov_b64 s[100:101], s[88:89]
	s_barrier
	ds_read_b128 v[146:149], v213 offset:16384
	ds_read_b128 v[150:153], v213 offset:17408
	ds_read_b128 v[154:157], v213 offset:18432
	ds_read_b128 v[158:161], v213 offset:19456
	ds_read_b128 v[162:165], v213 offset:20480
	ds_read_b128 v[166:169], v213 offset:21504
	ds_read_b128 v[170:173], v213 offset:22528
	ds_read_b128 v[174:177], v213 offset:23552
	global_load_lds_dwordx4 v190, s[100:101]
	s_mov_b32 m0, s42
	s_nop 0
	global_load_lds_dwordx4 v192, s[100:101]
	s_waitcnt vmcnt(10)
	s_barrier
	s_waitcnt lgkmcnt(0)
	v_mfma_f32_16x16x32_bf16 v[62:65], v[130:133], v[146:149], v[62:65]
	v_mfma_f32_16x16x32_bf16 v[58:61], v[138:141], v[146:149], v[58:61]
	v_mfma_f32_16x16x32_bf16 v[46:49], v[130:133], v[154:157], v[46:49]
	v_mfma_f32_16x16x32_bf16 v[42:45], v[138:141], v[154:157], v[42:45]
	v_mfma_f32_16x16x32_bf16 v[30:33], v[130:133], v[162:165], v[30:33]
	v_mfma_f32_16x16x32_bf16 v[26:29], v[138:141], v[162:165], v[26:29]
	v_mfma_f32_16x16x32_bf16 v[14:17], v[130:133], v[170:173], v[14:17]
	v_mfma_f32_16x16x32_bf16 v[10:13], v[138:141], v[170:173], v[10:13]
	v_mfma_f32_16x16x32_bf16 v[62:65], v[134:137], v[150:153], v[62:65]
	v_mfma_f32_16x16x32_bf16 v[58:61], v[142:145], v[150:153], v[58:61]
	v_mfma_f32_16x16x32_bf16 v[46:49], v[134:137], v[158:161], v[46:49]
	v_mfma_f32_16x16x32_bf16 v[42:45], v[142:145], v[158:161], v[42:45]
	v_mfma_f32_16x16x32_bf16 v[30:33], v[134:137], v[166:169], v[30:33]
	v_mfma_f32_16x16x32_bf16 v[26:29], v[142:145], v[166:169], v[26:29]
	v_mfma_f32_16x16x32_bf16 v[14:17], v[134:137], v[174:177], v[14:17]
	v_mfma_f32_16x16x32_bf16 v[10:13], v[142:145], v[174:177], v[10:13]
	s_barrier
	s_add_u32 s16, s86, 0xb0000
	s_addc_u32 s17, s87, 0
	s_add_i32 m0, s38, 0x14000
	s_nop 0
	global_load_lds_dwordx4 v0, s[16:17]
	s_add_i32 m0, s38, 0x16000
	s_nop 0
	global_load_lds_dwordx4 v194, s[16:17]
	s_add_i32 s90, 0, 0x18000
	v_add_u32_e32 v142, s90, v212
	ds_read_b128 v[130:133], v142
	ds_read_b128 v[134:137], v142 offset:1024
	ds_read_b128 v[138:141], v142 offset:2048
	ds_read_b128 v[142:145], v142 offset:3072
	s_waitcnt vmcnt(6)
	s_barrier
	v_mfma_f32_16x16x32_bf16 v[54:57], v[178:181], v[146:149], v[54:57]
	v_mfma_f32_16x16x32_bf16 v[50:53], v[200:203], v[146:149], v[50:53]
	v_mfma_f32_16x16x32_bf16 v[38:41], v[178:181], v[154:157], v[38:41]
	v_mfma_f32_16x16x32_bf16 v[34:37], v[200:203], v[154:157], v[34:37]
	v_mfma_f32_16x16x32_bf16 v[22:25], v[178:181], v[162:165], v[22:25]
	v_mfma_f32_16x16x32_bf16 v[18:21], v[200:203], v[162:165], v[18:21]
	v_mfma_f32_16x16x32_bf16 v[6:9], v[178:181], v[170:173], v[6:9]
	v_mfma_f32_16x16x32_bf16 v[2:5], v[200:203], v[170:173], v[2:5]
	v_mfma_f32_16x16x32_bf16 v[54:57], v[182:185], v[150:153], v[54:57]
	v_mfma_f32_16x16x32_bf16 v[50:53], v[204:207], v[150:153], v[50:53]
	v_mfma_f32_16x16x32_bf16 v[38:41], v[182:185], v[158:161], v[38:41]
	v_mfma_f32_16x16x32_bf16 v[34:37], v[204:207], v[158:161], v[34:37]
	v_mfma_f32_16x16x32_bf16 v[22:25], v[182:185], v[166:169], v[22:25]
	v_mfma_f32_16x16x32_bf16 v[18:21], v[204:207], v[166:169], v[18:21]
	v_mfma_f32_16x16x32_bf16 v[6:9], v[182:185], v[174:177], v[6:9]
	v_mfma_f32_16x16x32_bf16 v[2:5], v[204:207], v[174:177], v[2:5]
	s_barrier
	s_add_u32 s16, s88, 0xb0000
	s_addc_u32 s17, s89, 0
	s_mov_b32 m0, s43
	ds_read_b128 v[146:149], v213 offset:32768
	ds_read_b128 v[150:153], v213 offset:33792
	ds_read_b128 v[154:157], v213 offset:34816
	ds_read_b128 v[158:161], v213 offset:35840
	ds_read_b128 v[162:165], v213 offset:36864
	ds_read_b128 v[166:169], v213 offset:37888
	ds_read_b128 v[170:173], v213 offset:38912
	ds_read_b128 v[174:177], v213 offset:39936
	global_load_lds_dwordx4 v190, s[16:17]
	s_mov_b32 m0, s44
	s_nop 0
	global_load_lds_dwordx4 v192, s[16:17]
	s_waitcnt lgkmcnt(8)
	s_barrier
	s_waitcnt lgkmcnt(0)
	v_mfma_f32_16x16x32_bf16 v[126:129], v[130:133], v[146:149], v[126:129]
	v_mfma_f32_16x16x32_bf16 v[122:125], v[138:141], v[146:149], v[122:125]
	v_mfma_f32_16x16x32_bf16 v[110:113], v[130:133], v[154:157], v[110:113]
	v_mfma_f32_16x16x32_bf16 v[106:109], v[138:141], v[154:157], v[106:109]
	v_mfma_f32_16x16x32_bf16 v[94:97], v[130:133], v[162:165], v[94:97]
	v_mfma_f32_16x16x32_bf16 v[90:93], v[138:141], v[162:165], v[90:93]
	v_mfma_f32_16x16x32_bf16 v[78:81], v[130:133], v[170:173], v[78:81]
	v_mfma_f32_16x16x32_bf16 v[74:77], v[138:141], v[170:173], v[74:77]
	v_mfma_f32_16x16x32_bf16 v[126:129], v[134:137], v[150:153], v[126:129]
	v_mfma_f32_16x16x32_bf16 v[122:125], v[142:145], v[150:153], v[122:125]
	v_mfma_f32_16x16x32_bf16 v[110:113], v[134:137], v[158:161], v[110:113]
	v_mfma_f32_16x16x32_bf16 v[106:109], v[142:145], v[158:161], v[106:109]
	v_mfma_f32_16x16x32_bf16 v[94:97], v[134:137], v[166:169], v[94:97]
	v_mfma_f32_16x16x32_bf16 v[90:93], v[142:145], v[166:169], v[90:93]
	v_mfma_f32_16x16x32_bf16 v[78:81], v[134:137], v[174:177], v[78:81]
	v_mfma_f32_16x16x32_bf16 v[74:77], v[142:145], v[174:177], v[74:77]
	s_barrier
	s_add_i32 s88, 0, 0x1c000
	v_add_u32_e32 v204, s88, v212
	s_add_i32 m0, s38, 0x18000
	ds_read_b128 v[178:181], v204
	ds_read_b128 v[182:185], v204 offset:1024
	ds_read_b128 v[200:203], v204 offset:2048
	ds_read_b128 v[204:207], v204 offset:3072
	s_add_u32 s98, s86, s40
	s_addc_u32 s99, s87, s41
	global_load_lds_dwordx4 v0, s[98:99]
	s_add_i32 m0, s38, 0x1a000
	s_nop 0
	global_load_lds_dwordx4 v194, s[98:99]
	s_barrier
	s_waitcnt lgkmcnt(0)
	v_mfma_f32_16x16x32_bf16 v[118:121], v[178:181], v[146:149], v[118:121]
	v_mfma_f32_16x16x32_bf16 v[114:117], v[200:203], v[146:149], v[114:117]
	v_mfma_f32_16x16x32_bf16 v[102:105], v[178:181], v[154:157], v[102:105]
	v_mfma_f32_16x16x32_bf16 v[98:101], v[200:203], v[154:157], v[98:101]
	v_mfma_f32_16x16x32_bf16 v[86:89], v[178:181], v[162:165], v[86:89]
	v_mfma_f32_16x16x32_bf16 v[82:85], v[200:203], v[162:165], v[82:85]
	v_mfma_f32_16x16x32_bf16 v[70:73], v[178:181], v[170:173], v[70:73]
	v_mfma_f32_16x16x32_bf16 v[66:69], v[200:203], v[170:173], v[66:69]
	v_mfma_f32_16x16x32_bf16 v[118:121], v[182:185], v[150:153], v[118:121]
	v_mfma_f32_16x16x32_bf16 v[114:117], v[204:207], v[150:153], v[114:117]
	v_mfma_f32_16x16x32_bf16 v[102:105], v[182:185], v[158:161], v[102:105]
	v_mfma_f32_16x16x32_bf16 v[98:101], v[204:207], v[158:161], v[98:101]
	v_mfma_f32_16x16x32_bf16 v[86:89], v[182:185], v[166:169], v[86:89]
	v_mfma_f32_16x16x32_bf16 v[82:85], v[204:207], v[166:169], v[82:85]
	v_mfma_f32_16x16x32_bf16 v[70:73], v[182:185], v[174:177], v[70:73]
	v_mfma_f32_16x16x32_bf16 v[66:69], v[204:207], v[174:177], v[66:69]
	s_mov_b32 m0, s60
	s_barrier
	ds_read_b128 v[146:149], v213 offset:49152
	ds_read_b128 v[150:153], v213 offset:50176
	ds_read_b128 v[154:157], v213 offset:51200
	ds_read_b128 v[158:161], v213 offset:52224
	ds_read_b128 v[162:165], v213 offset:53248
	ds_read_b128 v[166:169], v213 offset:54272
	ds_read_b128 v[170:173], v213 offset:55296
	ds_read_b128 v[174:177], v213 offset:56320
	s_add_u32 s98, s100, s40
	s_addc_u32 s99, s101, s41
	global_load_lds_dwordx4 v190, s[98:99]
	s_mov_b32 m0, s61
	s_nop 0
	global_load_lds_dwordx4 v192, s[98:99]
	s_waitcnt vmcnt(10)
	s_barrier
	s_waitcnt lgkmcnt(0)
	v_mfma_f32_16x16x32_bf16 v[62:65], v[130:133], v[146:149], v[62:65]
	v_mfma_f32_16x16x32_bf16 v[58:61], v[138:141], v[146:149], v[58:61]
	v_mfma_f32_16x16x32_bf16 v[46:49], v[130:133], v[154:157], v[46:49]
	v_mfma_f32_16x16x32_bf16 v[42:45], v[138:141], v[154:157], v[42:45]
	v_mfma_f32_16x16x32_bf16 v[30:33], v[130:133], v[162:165], v[30:33]
	v_mfma_f32_16x16x32_bf16 v[26:29], v[138:141], v[162:165], v[26:29]
	v_mfma_f32_16x16x32_bf16 v[14:17], v[130:133], v[170:173], v[14:17]
	v_mfma_f32_16x16x32_bf16 v[10:13], v[138:141], v[170:173], v[10:13]
	v_mfma_f32_16x16x32_bf16 v[62:65], v[134:137], v[150:153], v[62:65]
	v_mfma_f32_16x16x32_bf16 v[58:61], v[142:145], v[150:153], v[58:61]
	v_mfma_f32_16x16x32_bf16 v[46:49], v[134:137], v[158:161], v[46:49]
	v_mfma_f32_16x16x32_bf16 v[42:45], v[142:145], v[158:161], v[42:45]
	v_mfma_f32_16x16x32_bf16 v[30:33], v[134:137], v[166:169], v[30:33]
	v_mfma_f32_16x16x32_bf16 v[26:29], v[142:145], v[166:169], v[26:29]
	v_mfma_f32_16x16x32_bf16 v[14:17], v[134:137], v[174:177], v[14:17]
	v_mfma_f32_16x16x32_bf16 v[10:13], v[142:145], v[174:177], v[10:13]
	s_barrier
	s_add_u32 s16, s86, 0xb0080
	s_addc_u32 s17, s87, 0
	s_add_i32 m0, s38, 0x1c000
	s_nop 0
	global_load_lds_dwordx4 v0, s[16:17]
	s_add_i32 m0, s38, 0x1e000
	s_nop 0
	global_load_lds_dwordx4 v194, s[16:17]
	ds_read_b128 v[130:133], v189
	ds_read_b128 v[134:137], v189 offset:1024
	ds_read_b128 v[138:141], v189 offset:2048
	ds_read_b128 v[142:145], v189 offset:3072
	s_waitcnt vmcnt(6)
	s_barrier
	v_mfma_f32_16x16x32_bf16 v[54:57], v[178:181], v[146:149], v[54:57]
	v_mfma_f32_16x16x32_bf16 v[50:53], v[200:203], v[146:149], v[50:53]
	v_mfma_f32_16x16x32_bf16 v[38:41], v[178:181], v[154:157], v[38:41]
	v_mfma_f32_16x16x32_bf16 v[34:37], v[200:203], v[154:157], v[34:37]
	v_mfma_f32_16x16x32_bf16 v[22:25], v[178:181], v[162:165], v[22:25]
	v_mfma_f32_16x16x32_bf16 v[18:21], v[200:203], v[162:165], v[18:21]
	v_mfma_f32_16x16x32_bf16 v[6:9], v[178:181], v[170:173], v[6:9]
	v_mfma_f32_16x16x32_bf16 v[2:5], v[200:203], v[170:173], v[2:5]
	v_mfma_f32_16x16x32_bf16 v[54:57], v[182:185], v[150:153], v[54:57]
	v_mfma_f32_16x16x32_bf16 v[50:53], v[204:207], v[150:153], v[50:53]
	v_mfma_f32_16x16x32_bf16 v[38:41], v[182:185], v[158:161], v[38:41]
	v_mfma_f32_16x16x32_bf16 v[34:37], v[204:207], v[158:161], v[34:37]
	v_mfma_f32_16x16x32_bf16 v[22:25], v[182:185], v[166:169], v[22:25]
	v_mfma_f32_16x16x32_bf16 v[18:21], v[204:207], v[166:169], v[18:21]
	v_mfma_f32_16x16x32_bf16 v[6:9], v[182:185], v[174:177], v[6:9]
	v_mfma_f32_16x16x32_bf16 v[2:5], v[204:207], v[174:177], v[2:5]
	s_add_i32 s79, s79, 2
	s_add_u32 s34, s34, 0x100
	s_addc_u32 s78, s78, 0
	s_mov_b64 s[16:17], s[84:85]
	s_add_u32 s84, s16, 0x100
	s_addc_u32 s85, s17, 0
	s_cmp_eq_u32 s79, 40
	s_cselect_b32 s89, s5, s85
	s_cselect_b32 s88, s4, s84
	s_cselect_b32 s87, s7, s78
	s_cselect_b32 s86, s6, s34
	s_cmp_gt_u32 s79, 41
	s_barrier
	s_cbranch_scc0 .LBB0_1090
	s_waitcnt lgkmcnt(0)
	s_lshl_b32 s16, s23, 8
	v_mov_b32_e32 v186, v252
	s_add_i32 s16, s16, s47
	s_nop 0
	v_and_or_b32 v202, v186, 15, s16
	s_lshl_b32 s16, s22, 8
	s_or_b32 s16, s16, s55
	v_lshrrev_b32_e32 v130, 1, v186
	v_and_or_b32 v200, v130, 24, s16
	v_ashrrev_i32_e32 v201, 31, v200
	v_ashrrev_i32_e32 v203, 31, v202
	v_lshl_add_u64 v[204:205], v[200:201], 2, s[12:13]
	v_lshlrev_b64 v[130:131], 12, v[202:203]
	v_lshl_add_u64 v[130:131], v[204:205], 0, v[130:131]
	global_load_dwordx4 v[216:219], v[130:131], off offset:16
	global_load_dwordx4 v[220:223], v[130:131], off
	global_load_dwordx4 v[178:181], v[130:131], off offset:528
	global_load_dwordx4 v[182:185], v[130:131], off offset:512
	v_or_b32_e32 v210, 16, v202
	v_ashrrev_i32_e32 v211, 31, v210
	v_lshlrev_b64 v[130:131], 12, v[210:211]
	v_or_b32_e32 v208, 32, v202
	v_lshl_add_u64 v[130:131], v[204:205], 0, v[130:131]
	v_ashrrev_i32_e32 v209, 31, v208
	global_load_dwordx4 v[170:173], v[130:131], off offset:16
	global_load_dwordx4 v[174:177], v[130:131], off
	global_load_dwordx4 v[162:165], v[130:131], off offset:528
	global_load_dwordx4 v[166:169], v[130:131], off offset:512
	v_lshlrev_b64 v[130:131], 12, v[208:209]
	v_or_b32_e32 v206, 48, v202
	v_lshl_add_u64 v[130:131], v[204:205], 0, v[130:131]
	v_ashrrev_i32_e32 v207, 31, v206
	global_load_dwordx4 v[154:157], v[130:131], off offset:16
	global_load_dwordx4 v[158:161], v[130:131], off
	global_load_dwordx4 v[138:141], v[130:131], off offset:528
	global_load_dwordx4 v[142:145], v[130:131], off offset:512
	v_lshlrev_b64 v[130:131], 12, v[206:207]
	v_lshl_add_u64 v[134:135], v[204:205], 0, v[130:131]
	global_load_dwordx4 v[146:149], v[134:135], off offset:16
	global_load_dwordx4 v[150:153], v[134:135], off
	global_load_dwordx4 v[130:133], v[134:135], off offset:528
	s_nop 0
	global_load_dwordx4 v[134:137], v[134:135], off offset:512
	v_and_b32_e32 v186, 63, v186
	v_lshlrev_b32_e32 v187, 2, v186
	v_xor_b32_e32 v215, 64, v187
	v_xor_b32_e32 v214, 0x80, v187
	v_cmp_gt_u32_e32 vcc, 16, v186
	v_lshlrev_b64 v[186:187], 10, v[202:203]
	v_lshl_add_u64 v[186:187], v[186:187], 0, v[200:201]
	s_lshl_b32 s16, s22, 2
	s_ashr_i32 s17, s16, 31
	s_waitcnt vmcnt(0)
	v_pk_add_f32 v[124:125], v[124:125], v[218:219]
	v_pk_add_f32 v[128:129], v[128:129], v[222:223]
	v_pk_add_f32 v[126:127], v[126:127], v[220:221]
	v_pk_mul_f32 v[218:219], v[128:129], v[128:129]
	v_pk_mul_f32 v[220:221], v[126:127], v[126:127]
	v_pk_add_f32 v[122:123], v[122:123], v[216:217]
	v_lshl_add_u64 v[216:217], v[186:187], 2, s[14:15]
	v_add_f32_e32 v220, v220, v221
	v_add_f32_e32 v218, v218, v219
	global_store_dwordx4 v[216:217], v[126:129], off
	global_store_dwordx4 v[216:217], v[122:125], off offset:16
	v_add_f32_e32 v222, v220, v218
	v_pk_mul_f32 v[220:221], v[122:123], v[122:123]
	v_cvt_pk_bf16_f32 v126, v126, v127
	v_cvt_pk_bf16_f32 v127, v128, v129
	v_cvt_pk_bf16_f32 v128, v122, v123
	v_cvt_pk_bf16_f32 v129, v124, v125
	v_lshl_add_u64 v[122:123], v[186:187], 1, s[80:81]
	v_pk_add_f32 v[120:121], v[120:121], v[184:185]
	v_pk_add_f32 v[118:119], v[118:119], v[182:183]
	v_pk_mul_f32 v[218:219], v[124:125], v[124:125]
	global_store_dwordx4 v[122:123], v[126:129], off
	v_pk_mul_f32 v[124:125], v[120:121], v[120:121]
	v_pk_add_f32 v[116:117], v[116:117], v[180:181]
	v_pk_mul_f32 v[126:127], v[118:119], v[118:119]
	v_pk_add_f32 v[114:115], v[114:115], v[178:179]
	v_add_f32_e32 v126, v126, v127
	v_add_f32_e32 v124, v124, v125
	v_add_f32_e32 v128, v126, v124
	v_pk_mul_f32 v[124:125], v[116:117], v[116:117]
	v_pk_mul_f32 v[126:127], v[114:115], v[114:115]
	v_add_f32_e32 v220, v220, v221
	v_add_f32_e32 v218, v218, v219
	v_add_f32_e32 v126, v126, v127
	v_add_f32_e32 v124, v124, v125
	v_add_f32_e32 v218, v220, v218
	v_add_f32_e32 v124, v126, v124
	v_add_f32_e32 v218, v222, v218
	v_add_f32_e32 v124, v128, v124
	v_add_f32_e32 v124, v218, v124
	global_store_dwordx4 v[216:217], v[118:121], off offset:512
	global_store_dwordx4 v[216:217], v[114:117], off offset:528
	s_nop 0
	v_cvt_pk_bf16_f32 v118, v118, v119
	v_cvt_pk_bf16_f32 v119, v120, v121
	v_cvt_pk_bf16_f32 v120, v114, v115
	ds_bpermute_b32 v114, v215, v124
	v_cvt_pk_bf16_f32 v121, v116, v117
	global_store_dwordx4 v[122:123], v[118:121], off offset:256
	s_waitcnt lgkmcnt(0)
	v_add_f32_e32 v114, v124, v114
	ds_bpermute_b32 v115, v214, v114
	s_and_saveexec_b64 s[22:23], vcc
	s_cbranch_execz .LBB0_1093
	v_lshlrev_b64 v[116:117], 6, v[202:203]
	v_lshl_add_u64 v[116:117], s[82:83], 0, v[116:117]
	v_lshl_add_u64 v[116:117], s[16:17], 2, v[116:117]
	s_lshl_b32 s34, s45, 2
	v_lshl_add_u64 v[116:117], v[116:117], 0, s[34:35]
	s_waitcnt lgkmcnt(0)
	v_add_f32_e32 v114, v114, v115
	global_store_dword v[116:117], v114, off

.LBB0_1208:
	s_ashr_i32 s13, s12, 31
	v_cmp_lt_i64_e32 vcc, s[14:15], v[230:231]
	s_lshl_b64 s[14:15], s[12:13], 19
	s_add_u32 s14, s80, s14
	s_addc_u32 s15, s81, s15
	s_and_b64 s[16:17], vcc, exec
	s_cselect_b32 s13, s15, s89
	s_cselect_b32 s22, s14, s88
	s_ashr_i32 s7, s6, 31
	s_lshl_b64 s[16:17], s[6:7], 19
	s_add_u32 s16, s36, s16
	s_addc_u32 s17, s37, s17
	s_and_b64 s[92:93], vcc, exec
	s_cselect_b32 s7, s17, s91
	s_cselect_b32 s23, s16, s90
	s_add_u32 s88, s88, 0x40080
	s_addc_u32 s89, s89, 0
	s_add_u32 s34, s90, 0x100
	s_addc_u32 s79, s91, 0
	s_mov_b32 s85, -2
	s_waitcnt lgkmcnt(0)
	s_add_i32 s94, 0, 0x10000
	v_add_u32_e32 v0, s94, v170
	v_add_u32_e32 v189, 0x10000, v170
	ds_read_b128 v[130:133], v0
	ds_read_b128 v[134:137], v0 offset:1024
	ds_read_b128 v[138:141], v0 offset:2048
	ds_read_b128 v[142:145], v0 offset:3072
	s_add_u32 s87, s88, 0xfffc0080
	s_addc_u32 s90, s89, -1
	s_cmp_eq_u32 s85, 12
	s_cselect_b32 s93, s13, s90
	s_cselect_b32 s92, s22, s87
	s_cselect_b32 s91, s7, s79
	s_cselect_b32 s90, s23, s34
	s_waitcnt lgkmcnt(0)
	s_add_i32 m0, s39, 0xc000
	ds_read_b128 v[158:161], v171
	ds_read_b128 v[162:165], v171 offset:1024
	ds_read_b128 v[166:169], v171 offset:2048
	ds_read_b128 v[172:175], v171 offset:3072
	ds_read_b128 v[176:179], v171 offset:4096
	ds_read_b128 v[180:183], v171 offset:5120
	ds_read_b128 v[184:187], v171 offset:6144
	ds_read_b128 v[190:193], v171 offset:7168
	global_load_lds_dwordx4 v154, s[88:89]
	s_add_i32 m0, s39, 0xe000
	s_nop 0
	global_load_lds_dwordx4 v156, s[88:89]
	s_waitcnt lgkmcnt(8)
	s_barrier
	s_waitcnt lgkmcnt(0)
	v_mfma_f32_16x16x32_bf16 v[126:129], v[130:133], v[158:161], 0
	v_mfma_f32_16x16x32_bf16 v[122:125], v[138:141], v[158:161], 0
	v_mfma_f32_16x16x32_bf16 v[110:113], v[130:133], v[166:169], 0
	v_mfma_f32_16x16x32_bf16 v[106:109], v[138:141], v[166:169], 0
	v_mfma_f32_16x16x32_bf16 v[94:97], v[130:133], v[176:179], 0
	v_mfma_f32_16x16x32_bf16 v[90:93], v[138:141], v[176:179], 0
	v_mfma_f32_16x16x32_bf16 v[78:81], v[130:133], v[184:187], 0
	v_mfma_f32_16x16x32_bf16 v[74:77], v[138:141], v[184:187], 0
	v_mfma_f32_16x16x32_bf16 v[126:129], v[134:137], v[162:165], v[126:129]
	v_mfma_f32_16x16x32_bf16 v[122:125], v[142:145], v[162:165], v[122:125]
	v_mfma_f32_16x16x32_bf16 v[110:113], v[134:137], v[172:175], v[110:113]
	v_mfma_f32_16x16x32_bf16 v[106:109], v[142:145], v[172:175], v[106:109]
	v_mfma_f32_16x16x32_bf16 v[94:97], v[134:137], v[180:183], v[94:97]
	v_mfma_f32_16x16x32_bf16 v[90:93], v[142:145], v[180:183], v[90:93]
	v_mfma_f32_16x16x32_bf16 v[78:81], v[134:137], v[190:193], v[78:81]
	v_mfma_f32_16x16x32_bf16 v[74:77], v[142:145], v[190:193], v[74:77]
	s_barrier
	s_add_i32 m0, s38, 0x10000
	ds_read_b128 v[194:197], v189 offset:16384
	ds_read_b128 v[198:201], v189 offset:17408
	ds_read_b128 v[202:205], v189 offset:18432
	ds_read_b128 v[206:209], v189 offset:19456
	global_load_lds_dwordx4 v148, s[90:91]
	s_add_i32 m0, s38, 0x12000
	s_nop 0
	global_load_lds_dwordx4 v152, s[90:91]
	s_barrier
	s_waitcnt lgkmcnt(0)
	v_mfma_f32_16x16x32_bf16 v[118:121], v[194:197], v[158:161], 0
	v_mfma_f32_16x16x32_bf16 v[114:117], v[202:205], v[158:161], 0
	v_mfma_f32_16x16x32_bf16 v[102:105], v[194:197], v[166:169], 0
	v_mfma_f32_16x16x32_bf16 v[98:101], v[202:205], v[166:169], 0
	v_mfma_f32_16x16x32_bf16 v[86:89], v[194:197], v[176:179], 0
	v_mfma_f32_16x16x32_bf16 v[82:85], v[202:205], v[176:179], 0
	v_mfma_f32_16x16x32_bf16 v[70:73], v[194:197], v[184:187], 0
	v_mfma_f32_16x16x32_bf16 v[66:69], v[202:205], v[184:187], 0
	v_mfma_f32_16x16x32_bf16 v[118:121], v[198:201], v[162:165], v[118:121]
	v_mfma_f32_16x16x32_bf16 v[114:117], v[206:209], v[162:165], v[114:117]
	v_mfma_f32_16x16x32_bf16 v[102:105], v[198:201], v[172:175], v[102:105]
	v_mfma_f32_16x16x32_bf16 v[98:101], v[206:209], v[172:175], v[98:101]
	v_mfma_f32_16x16x32_bf16 v[86:89], v[198:201], v[180:183], v[86:89]
	v_mfma_f32_16x16x32_bf16 v[82:85], v[206:209], v[180:183], v[82:85]
	v_mfma_f32_16x16x32_bf16 v[70:73], v[198:201], v[190:193], v[70:73]
	v_mfma_f32_16x16x32_bf16 v[66:69], v[206:209], v[190:193], v[66:69]
	s_mov_b32 m0, s39
	s_mov_b64 s[100:101], s[92:93]
	s_barrier
	ds_read_b128 v[158:161], v171 offset:16384
	ds_read_b128 v[162:165], v171 offset:17408
	ds_read_b128 v[166:169], v171 offset:18432
	ds_read_b128 v[172:175], v171 offset:19456
	ds_read_b128 v[176:179], v171 offset:20480
	ds_read_b128 v[180:183], v171 offset:21504
	ds_read_b128 v[184:187], v171 offset:22528
	ds_read_b128 v[190:193], v171 offset:23552
	global_load_lds_dwordx4 v146, s[100:101]
	s_mov_b32 m0, s42
	s_nop 0
	global_load_lds_dwordx4 v150, s[100:101]
	s_waitcnt vmcnt(10)
	s_barrier
	s_waitcnt lgkmcnt(0)
	v_mfma_f32_16x16x32_bf16 v[62:65], v[130:133], v[158:161], 0
	v_mfma_f32_16x16x32_bf16 v[58:61], v[138:141], v[158:161], 0
	v_mfma_f32_16x16x32_bf16 v[46:49], v[130:133], v[166:169], 0
	v_mfma_f32_16x16x32_bf16 v[42:45], v[138:141], v[166:169], 0
	v_mfma_f32_16x16x32_bf16 v[30:33], v[130:133], v[176:179], 0
	v_mfma_f32_16x16x32_bf16 v[26:29], v[138:141], v[176:179], 0
	v_mfma_f32_16x16x32_bf16 v[14:17], v[130:133], v[184:187], 0
	v_mfma_f32_16x16x32_bf16 v[10:13], v[138:141], v[184:187], 0
	v_mfma_f32_16x16x32_bf16 v[62:65], v[134:137], v[162:165], v[62:65]
	v_mfma_f32_16x16x32_bf16 v[58:61], v[142:145], v[162:165], v[58:61]
	v_mfma_f32_16x16x32_bf16 v[46:49], v[134:137], v[172:175], v[46:49]
	v_mfma_f32_16x16x32_bf16 v[42:45], v[142:145], v[172:175], v[42:45]
	v_mfma_f32_16x16x32_bf16 v[30:33], v[134:137], v[180:183], v[30:33]
	v_mfma_f32_16x16x32_bf16 v[26:29], v[142:145], v[180:183], v[26:29]
	v_mfma_f32_16x16x32_bf16 v[14:17], v[134:137], v[190:193], v[14:17]
	v_mfma_f32_16x16x32_bf16 v[10:13], v[142:145], v[190:193], v[10:13]
	s_barrier
	s_add_u32 s94, s90, 0x40000
	s_addc_u32 s95, s91, 0
	s_add_i32 m0, s38, 0x14000
	s_nop 0
	global_load_lds_dwordx4 v148, s[94:95]
	s_add_i32 m0, s38, 0x16000
	s_nop 0
	global_load_lds_dwordx4 v152, s[94:95]
	ds_read_b128 v[130:133], v189 offset:32768
	ds_read_b128 v[134:137], v189 offset:33792
	ds_read_b128 v[138:141], v189 offset:34816
	ds_read_b128 v[142:145], v189 offset:35840
	s_waitcnt vmcnt(6)
	s_barrier
	v_mfma_f32_16x16x32_bf16 v[54:57], v[194:197], v[158:161], 0
	v_mfma_f32_16x16x32_bf16 v[50:53], v[202:205], v[158:161], 0
	v_mfma_f32_16x16x32_bf16 v[38:41], v[194:197], v[166:169], 0
	v_mfma_f32_16x16x32_bf16 v[34:37], v[202:205], v[166:169], 0
	v_mfma_f32_16x16x32_bf16 v[22:25], v[194:197], v[176:179], 0
	v_mfma_f32_16x16x32_bf16 v[18:21], v[202:205], v[176:179], 0
	v_mfma_f32_16x16x32_bf16 v[6:9], v[194:197], v[184:187], 0
	v_mfma_f32_16x16x32_bf16 v[2:5], v[202:205], v[184:187], 0
	v_mfma_f32_16x16x32_bf16 v[54:57], v[198:201], v[162:165], v[54:57]
	v_mfma_f32_16x16x32_bf16 v[50:53], v[206:209], v[162:165], v[50:53]
	v_mfma_f32_16x16x32_bf16 v[38:41], v[198:201], v[172:175], v[38:41]
	v_mfma_f32_16x16x32_bf16 v[34:37], v[206:209], v[172:175], v[34:37]
	v_mfma_f32_16x16x32_bf16 v[22:25], v[198:201], v[180:183], v[22:25]
	v_mfma_f32_16x16x32_bf16 v[18:21], v[206:209], v[180:183], v[18:21]
	v_mfma_f32_16x16x32_bf16 v[6:9], v[198:201], v[190:193], v[6:9]
	v_mfma_f32_16x16x32_bf16 v[2:5], v[206:209], v[190:193], v[2:5]
	s_barrier
	s_add_u32 s92, s92, 0x40000
	s_addc_u32 s93, s93, 0
	s_mov_b32 m0, s43
	ds_read_b128 v[158:161], v171 offset:32768
	ds_read_b128 v[162:165], v171 offset:33792
	ds_read_b128 v[166:169], v171 offset:34816
	ds_read_b128 v[172:175], v171 offset:35840
	ds_read_b128 v[176:179], v171 offset:36864
	ds_read_b128 v[180:183], v171 offset:37888
	ds_read_b128 v[184:187], v171 offset:38912
	ds_read_b128 v[190:193], v171 offset:39936
	global_load_lds_dwordx4 v146, s[92:93]
	s_mov_b32 m0, s44
	s_nop 0
	global_load_lds_dwordx4 v150, s[92:93]
	s_waitcnt lgkmcnt(8)
	s_barrier
	s_waitcnt lgkmcnt(0)
	v_mfma_f32_16x16x32_bf16 v[126:129], v[130:133], v[158:161], v[126:129]
	v_mfma_f32_16x16x32_bf16 v[122:125], v[138:141], v[158:161], v[122:125]
	v_mfma_f32_16x16x32_bf16 v[110:113], v[130:133], v[166:169], v[110:113]
	v_mfma_f32_16x16x32_bf16 v[106:109], v[138:141], v[166:169], v[106:109]
	v_mfma_f32_16x16x32_bf16 v[94:97], v[130:133], v[176:179], v[94:97]
	v_mfma_f32_16x16x32_bf16 v[90:93], v[138:141], v[176:179], v[90:93]
	v_mfma_f32_16x16x32_bf16 v[78:81], v[130:133], v[184:187], v[78:81]
	v_mfma_f32_16x16x32_bf16 v[74:77], v[138:141], v[184:187], v[74:77]
	v_mfma_f32_16x16x32_bf16 v[126:129], v[134:137], v[162:165], v[126:129]
	v_mfma_f32_16x16x32_bf16 v[122:125], v[142:145], v[162:165], v[122:125]
	v_mfma_f32_16x16x32_bf16 v[110:113], v[134:137], v[172:175], v[110:113]
	v_mfma_f32_16x16x32_bf16 v[106:109], v[142:145], v[172:175], v[106:109]
	v_mfma_f32_16x16x32_bf16 v[94:97], v[134:137], v[180:183], v[94:97]
	v_mfma_f32_16x16x32_bf16 v[90:93], v[142:145], v[180:183], v[90:93]
	v_mfma_f32_16x16x32_bf16 v[78:81], v[134:137], v[190:193], v[78:81]
	v_mfma_f32_16x16x32_bf16 v[74:77], v[142:145], v[190:193], v[74:77]
	s_barrier
	s_add_i32 m0, s38, 0x18000
	ds_read_b128 v[194:197], v189 offset:49152
	ds_read_b128 v[198:201], v189 offset:50176
	ds_read_b128 v[202:205], v189 offset:51200
	ds_read_b128 v[206:209], v189 offset:52224
	s_add_u32 s98, s90, s40
	s_addc_u32 s99, s91, s41
	global_load_lds_dwordx4 v148, s[98:99]
	s_add_i32 m0, s38, 0x1a000
	s_nop 0
	global_load_lds_dwordx4 v152, s[98:99]
	s_barrier
	s_waitcnt lgkmcnt(0)
	v_mfma_f32_16x16x32_bf16 v[118:121], v[194:197], v[158:161], v[118:121]
	v_mfma_f32_16x16x32_bf16 v[114:117], v[202:205], v[158:161], v[114:117]
	v_mfma_f32_16x16x32_bf16 v[102:105], v[194:197], v[166:169], v[102:105]
	v_mfma_f32_16x16x32_bf16 v[98:101], v[202:205], v[166:169], v[98:101]
	v_mfma_f32_16x16x32_bf16 v[86:89], v[194:197], v[176:179], v[86:89]
	v_mfma_f32_16x16x32_bf16 v[82:85], v[202:205], v[176:179], v[82:85]
	v_mfma_f32_16x16x32_bf16 v[70:73], v[194:197], v[184:187], v[70:73]
	v_mfma_f32_16x16x32_bf16 v[66:69], v[202:205], v[184:187], v[66:69]
	v_mfma_f32_16x16x32_bf16 v[118:121], v[198:201], v[162:165], v[118:121]
	v_mfma_f32_16x16x32_bf16 v[114:117], v[206:209], v[162:165], v[114:117]
	v_mfma_f32_16x16x32_bf16 v[102:105], v[198:201], v[172:175], v[102:105]
	v_mfma_f32_16x16x32_bf16 v[98:101], v[206:209], v[172:175], v[98:101]
	v_mfma_f32_16x16x32_bf16 v[86:89], v[198:201], v[180:183], v[86:89]
	v_mfma_f32_16x16x32_bf16 v[82:85], v[206:209], v[180:183], v[82:85]
	v_mfma_f32_16x16x32_bf16 v[70:73], v[198:201], v[190:193], v[70:73]
	v_mfma_f32_16x16x32_bf16 v[66:69], v[206:209], v[190:193], v[66:69]
	s_mov_b32 m0, s60
	s_barrier
	ds_read_b128 v[158:161], v171 offset:49152
	ds_read_b128 v[162:165], v171 offset:50176
	ds_read_b128 v[166:169], v171 offset:51200
	ds_read_b128 v[172:175], v171 offset:52224
	ds_read_b128 v[176:179], v171 offset:53248
	ds_read_b128 v[180:183], v171 offset:54272
	ds_read_b128 v[184:187], v171 offset:55296
	ds_read_b128 v[190:193], v171 offset:56320
	s_add_u32 s98, s100, s40
	s_addc_u32 s99, s101, s41
	global_load_lds_dwordx4 v146, s[98:99]
	s_mov_b32 m0, s61
	s_nop 0
	global_load_lds_dwordx4 v150, s[98:99]
	s_waitcnt vmcnt(10)
	s_barrier
	s_waitcnt lgkmcnt(0)
	v_mfma_f32_16x16x32_bf16 v[62:65], v[130:133], v[158:161], v[62:65]
	v_mfma_f32_16x16x32_bf16 v[58:61], v[138:141], v[158:161], v[58:61]
	v_mfma_f32_16x16x32_bf16 v[46:49], v[130:133], v[166:169], v[46:49]
	v_mfma_f32_16x16x32_bf16 v[42:45], v[138:141], v[166:169], v[42:45]
	v_mfma_f32_16x16x32_bf16 v[30:33], v[130:133], v[176:179], v[30:33]
	v_mfma_f32_16x16x32_bf16 v[26:29], v[138:141], v[176:179], v[26:29]
	v_mfma_f32_16x16x32_bf16 v[14:17], v[130:133], v[184:187], v[14:17]
	v_mfma_f32_16x16x32_bf16 v[10:13], v[138:141], v[184:187], v[10:13]
	v_mfma_f32_16x16x32_bf16 v[62:65], v[134:137], v[162:165], v[62:65]
	v_mfma_f32_16x16x32_bf16 v[58:61], v[142:145], v[162:165], v[58:61]
	v_mfma_f32_16x16x32_bf16 v[46:49], v[134:137], v[172:175], v[46:49]
	v_mfma_f32_16x16x32_bf16 v[42:45], v[142:145], v[172:175], v[42:45]
	v_mfma_f32_16x16x32_bf16 v[30:33], v[134:137], v[180:183], v[30:33]
	v_mfma_f32_16x16x32_bf16 v[26:29], v[142:145], v[180:183], v[26:29]
	v_mfma_f32_16x16x32_bf16 v[14:17], v[134:137], v[190:193], v[14:17]
	v_mfma_f32_16x16x32_bf16 v[10:13], v[142:145], v[190:193], v[10:13]
	s_barrier
	s_add_u32 s90, s90, 0x40080
	s_addc_u32 s91, s91, 0
	s_add_i32 m0, s38, 0x1c000
	s_nop 0
	global_load_lds_dwordx4 v148, s[90:91]
	s_add_i32 m0, s38, 0x1e000
	s_nop 0
	global_load_lds_dwordx4 v152, s[90:91]
	ds_read_b128 v[130:133], v189
	ds_read_b128 v[134:137], v189 offset:1024
	ds_read_b128 v[138:141], v189 offset:2048
	ds_read_b128 v[142:145], v189 offset:3072
	s_waitcnt vmcnt(6)
	s_barrier
	v_mfma_f32_16x16x32_bf16 v[54:57], v[194:197], v[158:161], v[54:57]
	v_mfma_f32_16x16x32_bf16 v[50:53], v[202:205], v[158:161], v[50:53]
	v_mfma_f32_16x16x32_bf16 v[38:41], v[194:197], v[166:169], v[38:41]
	v_mfma_f32_16x16x32_bf16 v[34:37], v[202:205], v[166:169], v[34:37]
	v_mfma_f32_16x16x32_bf16 v[22:25], v[194:197], v[176:179], v[22:25]
	v_mfma_f32_16x16x32_bf16 v[18:21], v[202:205], v[176:179], v[18:21]
	v_mfma_f32_16x16x32_bf16 v[6:9], v[194:197], v[184:187], v[6:9]
	v_mfma_f32_16x16x32_bf16 v[2:5], v[202:205], v[184:187], v[2:5]
	v_mfma_f32_16x16x32_bf16 v[54:57], v[198:201], v[162:165], v[54:57]
	v_mfma_f32_16x16x32_bf16 v[50:53], v[206:209], v[162:165], v[50:53]
	v_mfma_f32_16x16x32_bf16 v[38:41], v[198:201], v[172:175], v[38:41]
	v_mfma_f32_16x16x32_bf16 v[34:37], v[206:209], v[172:175], v[34:37]
	v_mfma_f32_16x16x32_bf16 v[22:25], v[198:201], v[180:183], v[22:25]
	v_mfma_f32_16x16x32_bf16 v[18:21], v[206:209], v[180:183], v[18:21]
	v_mfma_f32_16x16x32_bf16 v[6:9], v[198:201], v[190:193], v[6:9]
	v_mfma_f32_16x16x32_bf16 v[2:5], v[206:209], v[190:193], v[2:5]
	s_add_i32 s85, s85, 2
	s_add_u32 s88, s88, 0x100
	s_addc_u32 s89, s89, 0
	s_add_u32 s34, s34, 0x100
	s_addc_u32 s79, s79, 0
	s_add_u32 s87, s88, 0xfffc0080
	s_addc_u32 s90, s89, -1
	s_cmp_eq_u32 s85, 12
	s_cselect_b32 s93, s13, s90
	s_cselect_b32 s92, s22, s87
	s_cselect_b32 s91, s7, s79
	s_cselect_b32 s90, s23, s34
	s_cmp_gt_u32 s85, 13
	s_barrier
.LBB0_1209:
	s_waitcnt lgkmcnt(0)
	s_add_i32 m0, s39, 0xc000
	ds_read_b128 v[158:161], v171
	ds_read_b128 v[162:165], v171 offset:1024
	ds_read_b128 v[166:169], v171 offset:2048
	ds_read_b128 v[172:175], v171 offset:3072
	ds_read_b128 v[176:179], v171 offset:4096
	ds_read_b128 v[180:183], v171 offset:5120
	ds_read_b128 v[184:187], v171 offset:6144
	ds_read_b128 v[190:193], v171 offset:7168
	global_load_lds_dwordx4 v154, s[88:89]
	s_add_i32 m0, s39, 0xe000
	s_nop 0
	global_load_lds_dwordx4 v156, s[88:89]
	s_waitcnt lgkmcnt(8)
	s_barrier
	s_waitcnt lgkmcnt(0)
	v_mfma_f32_16x16x32_bf16 v[126:129], v[130:133], v[158:161], v[126:129]
	v_mfma_f32_16x16x32_bf16 v[122:125], v[138:141], v[158:161], v[122:125]
	v_mfma_f32_16x16x32_bf16 v[110:113], v[130:133], v[166:169], v[110:113]
	v_mfma_f32_16x16x32_bf16 v[106:109], v[138:141], v[166:169], v[106:109]
	v_mfma_f32_16x16x32_bf16 v[94:97], v[130:133], v[176:179], v[94:97]
	v_mfma_f32_16x16x32_bf16 v[90:93], v[138:141], v[176:179], v[90:93]
	v_mfma_f32_16x16x32_bf16 v[78:81], v[130:133], v[184:187], v[78:81]
	v_mfma_f32_16x16x32_bf16 v[74:77], v[138:141], v[184:187], v[74:77]
	v_mfma_f32_16x16x32_bf16 v[126:129], v[134:137], v[162:165], v[126:129]
	v_mfma_f32_16x16x32_bf16 v[122:125], v[142:145], v[162:165], v[122:125]
	v_mfma_f32_16x16x32_bf16 v[110:113], v[134:137], v[172:175], v[110:113]
	v_mfma_f32_16x16x32_bf16 v[106:109], v[142:145], v[172:175], v[106:109]
	v_mfma_f32_16x16x32_bf16 v[94:97], v[134:137], v[180:183], v[94:97]
	v_mfma_f32_16x16x32_bf16 v[90:93], v[142:145], v[180:183], v[90:93]
	v_mfma_f32_16x16x32_bf16 v[78:81], v[134:137], v[190:193], v[78:81]
	v_mfma_f32_16x16x32_bf16 v[74:77], v[142:145], v[190:193], v[74:77]
	s_barrier
	s_add_i32 m0, s38, 0x10000
	ds_read_b128 v[194:197], v189 offset:16384
	ds_read_b128 v[198:201], v189 offset:17408
	ds_read_b128 v[202:205], v189 offset:18432
	ds_read_b128 v[206:209], v189 offset:19456
	global_load_lds_dwordx4 v148, s[90:91]
	s_add_i32 m0, s38, 0x12000
	s_nop 0
	global_load_lds_dwordx4 v152, s[90:91]
	s_barrier
	s_waitcnt lgkmcnt(0)
	v_mfma_f32_16x16x32_bf16 v[118:121], v[194:197], v[158:161], v[118:121]
	v_mfma_f32_16x16x32_bf16 v[114:117], v[202:205], v[158:161], v[114:117]
	v_mfma_f32_16x16x32_bf16 v[102:105], v[194:197], v[166:169], v[102:105]
	v_mfma_f32_16x16x32_bf16 v[98:101], v[202:205], v[166:169], v[98:101]
	v_mfma_f32_16x16x32_bf16 v[86:89], v[194:197], v[176:179], v[86:89]
	v_mfma_f32_16x16x32_bf16 v[82:85], v[202:205], v[176:179], v[82:85]
	v_mfma_f32_16x16x32_bf16 v[70:73], v[194:197], v[184:187], v[70:73]
	v_mfma_f32_16x16x32_bf16 v[66:69], v[202:205], v[184:187], v[66:69]
	v_mfma_f32_16x16x32_bf16 v[118:121], v[198:201], v[162:165], v[118:121]
	v_mfma_f32_16x16x32_bf16 v[114:117], v[206:209], v[162:165], v[114:117]
	v_mfma_f32_16x16x32_bf16 v[102:105], v[198:201], v[172:175], v[102:105]
	v_mfma_f32_16x16x32_bf16 v[98:101], v[206:209], v[172:175], v[98:101]
	v_mfma_f32_16x16x32_bf16 v[86:89], v[198:201], v[180:183], v[86:89]
	v_mfma_f32_16x16x32_bf16 v[82:85], v[206:209], v[180:183], v[82:85]
	v_mfma_f32_16x16x32_bf16 v[70:73], v[198:201], v[190:193], v[70:73]
	v_mfma_f32_16x16x32_bf16 v[66:69], v[206:209], v[190:193], v[66:69]
	s_mov_b32 m0, s39
	s_mov_b64 s[100:101], s[92:93]
	s_barrier
	ds_read_b128 v[158:161], v171 offset:16384
	ds_read_b128 v[162:165], v171 offset:17408
	ds_read_b128 v[166:169], v171 offset:18432
	ds_read_b128 v[172:175], v171 offset:19456
	ds_read_b128 v[176:179], v171 offset:20480
	ds_read_b128 v[180:183], v171 offset:21504
	ds_read_b128 v[184:187], v171 offset:22528
	ds_read_b128 v[190:193], v171 offset:23552
	global_load_lds_dwordx4 v146, s[100:101]
	s_mov_b32 m0, s42
	s_nop 0
	global_load_lds_dwordx4 v150, s[100:101]
	s_waitcnt vmcnt(10)
	s_barrier
	s_waitcnt lgkmcnt(0)
	v_mfma_f32_16x16x32_bf16 v[62:65], v[130:133], v[158:161], v[62:65]
	v_mfma_f32_16x16x32_bf16 v[58:61], v[138:141], v[158:161], v[58:61]
	v_mfma_f32_16x16x32_bf16 v[46:49], v[130:133], v[166:169], v[46:49]
	v_mfma_f32_16x16x32_bf16 v[42:45], v[138:141], v[166:169], v[42:45]
	v_mfma_f32_16x16x32_bf16 v[30:33], v[130:133], v[176:179], v[30:33]
	v_mfma_f32_16x16x32_bf16 v[26:29], v[138:141], v[176:179], v[26:29]
	v_mfma_f32_16x16x32_bf16 v[14:17], v[130:133], v[184:187], v[14:17]
	v_mfma_f32_16x16x32_bf16 v[10:13], v[138:141], v[184:187], v[10:13]
	v_mfma_f32_16x16x32_bf16 v[62:65], v[134:137], v[162:165], v[62:65]
	v_mfma_f32_16x16x32_bf16 v[58:61], v[142:145], v[162:165], v[58:61]
	v_mfma_f32_16x16x32_bf16 v[46:49], v[134:137], v[172:175], v[46:49]
	v_mfma_f32_16x16x32_bf16 v[42:45], v[142:145], v[172:175], v[42:45]
	v_mfma_f32_16x16x32_bf16 v[30:33], v[134:137], v[180:183], v[30:33]
	v_mfma_f32_16x16x32_bf16 v[26:29], v[142:145], v[180:183], v[26:29]
	v_mfma_f32_16x16x32_bf16 v[14:17], v[134:137], v[190:193], v[14:17]
	v_mfma_f32_16x16x32_bf16 v[10:13], v[142:145], v[190:193], v[10:13]
	s_barrier
	s_add_u32 s94, s90, 0x40000
	s_addc_u32 s95, s91, 0
	s_add_i32 m0, s38, 0x14000
	s_nop 0
	global_load_lds_dwordx4 v148, s[94:95]
	s_add_i32 m0, s38, 0x16000
	s_nop 0
	global_load_lds_dwordx4 v152, s[94:95]
	ds_read_b128 v[130:133], v189 offset:32768
	ds_read_b128 v[134:137], v189 offset:33792
	ds_read_b128 v[138:141], v189 offset:34816
	ds_read_b128 v[142:145], v189 offset:35840
	s_waitcnt vmcnt(6)
	s_barrier
	v_mfma_f32_16x16x32_bf16 v[54:57], v[194:197], v[158:161], v[54:57]
	v_mfma_f32_16x16x32_bf16 v[50:53], v[202:205], v[158:161], v[50:53]
	v_mfma_f32_16x16x32_bf16 v[38:41], v[194:197], v[166:169], v[38:41]
	v_mfma_f32_16x16x32_bf16 v[34:37], v[202:205], v[166:169], v[34:37]
	v_mfma_f32_16x16x32_bf16 v[22:25], v[194:197], v[176:179], v[22:25]
	v_mfma_f32_16x16x32_bf16 v[18:21], v[202:205], v[176:179], v[18:21]
	v_mfma_f32_16x16x32_bf16 v[6:9], v[194:197], v[184:187], v[6:9]
	v_mfma_f32_16x16x32_bf16 v[2:5], v[202:205], v[184:187], v[2:5]
	v_mfma_f32_16x16x32_bf16 v[54:57], v[198:201], v[162:165], v[54:57]
	v_mfma_f32_16x16x32_bf16 v[50:53], v[206:209], v[162:165], v[50:53]
	v_mfma_f32_16x16x32_bf16 v[38:41], v[198:201], v[172:175], v[38:41]
	v_mfma_f32_16x16x32_bf16 v[34:37], v[206:209], v[172:175], v[34:37]
	v_mfma_f32_16x16x32_bf16 v[22:25], v[198:201], v[180:183], v[22:25]
	v_mfma_f32_16x16x32_bf16 v[18:21], v[206:209], v[180:183], v[18:21]
	v_mfma_f32_16x16x32_bf16 v[6:9], v[198:201], v[190:193], v[6:9]
	v_mfma_f32_16x16x32_bf16 v[2:5], v[206:209], v[190:193], v[2:5]
	s_barrier
	s_add_u32 s92, s92, 0x40000
	s_addc_u32 s93, s93, 0
	s_mov_b32 m0, s43
	ds_read_b128 v[158:161], v171 offset:32768
	ds_read_b128 v[162:165], v171 offset:33792
	ds_read_b128 v[166:169], v171 offset:34816
	ds_read_b128 v[172:175], v171 offset:35840
	ds_read_b128 v[176:179], v171 offset:36864
	ds_read_b128 v[180:183], v171 offset:37888
	ds_read_b128 v[184:187], v171 offset:38912
	ds_read_b128 v[190:193], v171 offset:39936
	global_load_lds_dwordx4 v146, s[92:93]
	s_mov_b32 m0, s44
	s_nop 0
	global_load_lds_dwordx4 v150, s[92:93]
	s_waitcnt lgkmcnt(8)
	s_barrier
	s_waitcnt lgkmcnt(0)
	v_mfma_f32_16x16x32_bf16 v[126:129], v[130:133], v[158:161], v[126:129]
	v_mfma_f32_16x16x32_bf16 v[122:125], v[138:141], v[158:161], v[122:125]
	v_mfma_f32_16x16x32_bf16 v[110:113], v[130:133], v[166:169], v[110:113]
	v_mfma_f32_16x16x32_bf16 v[106:109], v[138:141], v[166:169], v[106:109]
	v_mfma_f32_16x16x32_bf16 v[94:97], v[130:133], v[176:179], v[94:97]
	v_mfma_f32_16x16x32_bf16 v[90:93], v[138:141], v[176:179], v[90:93]
	v_mfma_f32_16x16x32_bf16 v[78:81], v[130:133], v[184:187], v[78:81]
	v_mfma_f32_16x16x32_bf16 v[74:77], v[138:141], v[184:187], v[74:77]
	v_mfma_f32_16x16x32_bf16 v[126:129], v[134:137], v[162:165], v[126:129]
	v_mfma_f32_16x16x32_bf16 v[122:125], v[142:145], v[162:165], v[122:125]
	v_mfma_f32_16x16x32_bf16 v[110:113], v[134:137], v[172:175], v[110:113]
	v_mfma_f32_16x16x32_bf16 v[106:109], v[142:145], v[172:175], v[106:109]
	v_mfma_f32_16x16x32_bf16 v[94:97], v[134:137], v[180:183], v[94:97]
	v_mfma_f32_16x16x32_bf16 v[90:93], v[142:145], v[180:183], v[90:93]
	v_mfma_f32_16x16x32_bf16 v[78:81], v[134:137], v[190:193], v[78:81]
	v_mfma_f32_16x16x32_bf16 v[74:77], v[142:145], v[190:193], v[74:77]
	s_barrier
	s_add_i32 m0, s38, 0x18000
	ds_read_b128 v[194:197], v189 offset:49152
	ds_read_b128 v[198:201], v189 offset:50176
	ds_read_b128 v[202:205], v189 offset:51200
	ds_read_b128 v[206:209], v189 offset:52224
	s_add_u32 s98, s90, s40
	s_addc_u32 s99, s91, s41
	global_load_lds_dwordx4 v148, s[98:99]
	s_add_i32 m0, s38, 0x1a000
	s_nop 0
	global_load_lds_dwordx4 v152, s[98:99]
	s_barrier
	s_waitcnt lgkmcnt(0)
	v_mfma_f32_16x16x32_bf16 v[118:121], v[194:197], v[158:161], v[118:121]
	v_mfma_f32_16x16x32_bf16 v[114:117], v[202:205], v[158:161], v[114:117]
	v_mfma_f32_16x16x32_bf16 v[102:105], v[194:197], v[166:169], v[102:105]
	v_mfma_f32_16x16x32_bf16 v[98:101], v[202:205], v[166:169], v[98:101]
	v_mfma_f32_16x16x32_bf16 v[86:89], v[194:197], v[176:179], v[86:89]
	v_mfma_f32_16x16x32_bf16 v[82:85], v[202:205], v[176:179], v[82:85]
	v_mfma_f32_16x16x32_bf16 v[70:73], v[194:197], v[184:187], v[70:73]
	v_mfma_f32_16x16x32_bf16 v[66:69], v[202:205], v[184:187], v[66:69]
	v_mfma_f32_16x16x32_bf16 v[118:121], v[198:201], v[162:165], v[118:121]
	v_mfma_f32_16x16x32_bf16 v[114:117], v[206:209], v[162:165], v[114:117]
	v_mfma_f32_16x16x32_bf16 v[102:105], v[198:201], v[172:175], v[102:105]
	v_mfma_f32_16x16x32_bf16 v[98:101], v[206:209], v[172:175], v[98:101]
	v_mfma_f32_16x16x32_bf16 v[86:89], v[198:201], v[180:183], v[86:89]
	v_mfma_f32_16x16x32_bf16 v[82:85], v[206:209], v[180:183], v[82:85]
	v_mfma_f32_16x16x32_bf16 v[70:73], v[198:201], v[190:193], v[70:73]
	v_mfma_f32_16x16x32_bf16 v[66:69], v[206:209], v[190:193], v[66:69]
	s_mov_b32 m0, s60
	s_barrier
	ds_read_b128 v[158:161], v171 offset:49152
	ds_read_b128 v[162:165], v171 offset:50176
	ds_read_b128 v[166:169], v171 offset:51200
	ds_read_b128 v[172:175], v171 offset:52224
	ds_read_b128 v[176:179], v171 offset:53248
	ds_read_b128 v[180:183], v171 offset:54272
	ds_read_b128 v[184:187], v171 offset:55296
	ds_read_b128 v[190:193], v171 offset:56320
	s_add_u32 s98, s100, s40
	s_addc_u32 s99, s101, s41
	global_load_lds_dwordx4 v146, s[98:99]
	s_mov_b32 m0, s61
	s_nop 0
	global_load_lds_dwordx4 v150, s[98:99]
	s_waitcnt vmcnt(10)
	s_barrier
	s_waitcnt lgkmcnt(0)
	v_mfma_f32_16x16x32_bf16 v[62:65], v[130:133], v[158:161], v[62:65]
	v_mfma_f32_16x16x32_bf16 v[58:61], v[138:141], v[158:161], v[58:61]
	v_mfma_f32_16x16x32_bf16 v[46:49], v[130:133], v[166:169], v[46:49]
	v_mfma_f32_16x16x32_bf16 v[42:45], v[138:141], v[166:169], v[42:45]
	v_mfma_f32_16x16x32_bf16 v[30:33], v[130:133], v[176:179], v[30:33]
	v_mfma_f32_16x16x32_bf16 v[26:29], v[138:141], v[176:179], v[26:29]
	v_mfma_f32_16x16x32_bf16 v[14:17], v[130:133], v[184:187], v[14:17]
	v_mfma_f32_16x16x32_bf16 v[10:13], v[138:141], v[184:187], v[10:13]
	v_mfma_f32_16x16x32_bf16 v[62:65], v[134:137], v[162:165], v[62:65]
	v_mfma_f32_16x16x32_bf16 v[58:61], v[142:145], v[162:165], v[58:61]
	v_mfma_f32_16x16x32_bf16 v[46:49], v[134:137], v[172:175], v[46:49]
	v_mfma_f32_16x16x32_bf16 v[42:45], v[142:145], v[172:175], v[42:45]
	v_mfma_f32_16x16x32_bf16 v[30:33], v[134:137], v[180:183], v[30:33]
	v_mfma_f32_16x16x32_bf16 v[26:29], v[142:145], v[180:183], v[26:29]
	v_mfma_f32_16x16x32_bf16 v[14:17], v[134:137], v[190:193], v[14:17]
	v_mfma_f32_16x16x32_bf16 v[10:13], v[142:145], v[190:193], v[10:13]
	s_barrier
	s_add_u32 s90, s90, 0x40080
	s_addc_u32 s91, s91, 0
	s_add_i32 m0, s38, 0x1c000
	s_nop 0
	global_load_lds_dwordx4 v148, s[90:91]
	s_add_i32 m0, s38, 0x1e000
	s_nop 0
	global_load_lds_dwordx4 v152, s[90:91]
	ds_read_b128 v[130:133], v189
	ds_read_b128 v[134:137], v189 offset:1024
	ds_read_b128 v[138:141], v189 offset:2048
	ds_read_b128 v[142:145], v189 offset:3072
	s_waitcnt vmcnt(6)
	s_barrier
	v_mfma_f32_16x16x32_bf16 v[54:57], v[194:197], v[158:161], v[54:57]
	v_mfma_f32_16x16x32_bf16 v[50:53], v[202:205], v[158:161], v[50:53]
	v_mfma_f32_16x16x32_bf16 v[38:41], v[194:197], v[166:169], v[38:41]
	v_mfma_f32_16x16x32_bf16 v[34:37], v[202:205], v[166:169], v[34:37]
	v_mfma_f32_16x16x32_bf16 v[22:25], v[194:197], v[176:179], v[22:25]
	v_mfma_f32_16x16x32_bf16 v[18:21], v[202:205], v[176:179], v[18:21]
	v_mfma_f32_16x16x32_bf16 v[6:9], v[194:197], v[184:187], v[6:9]
	v_mfma_f32_16x16x32_bf16 v[2:5], v[202:205], v[184:187], v[2:5]
	v_mfma_f32_16x16x32_bf16 v[54:57], v[198:201], v[162:165], v[54:57]
	v_mfma_f32_16x16x32_bf16 v[50:53], v[206:209], v[162:165], v[50:53]
	v_mfma_f32_16x16x32_bf16 v[38:41], v[198:201], v[172:175], v[38:41]
	v_mfma_f32_16x16x32_bf16 v[34:37], v[206:209], v[172:175], v[34:37]
	v_mfma_f32_16x16x32_bf16 v[22:25], v[198:201], v[180:183], v[22:25]
	v_mfma_f32_16x16x32_bf16 v[18:21], v[206:209], v[180:183], v[18:21]
	v_mfma_f32_16x16x32_bf16 v[6:9], v[198:201], v[190:193], v[6:9]
	v_mfma_f32_16x16x32_bf16 v[2:5], v[206:209], v[190:193], v[2:5]
	s_add_i32 s85, s85, 2
	s_add_u32 s88, s88, 0x100
	s_addc_u32 s89, s89, 0
	s_add_u32 s34, s34, 0x100
	s_addc_u32 s79, s79, 0
	s_add_u32 s87, s88, 0xfffc0080
	s_addc_u32 s90, s89, -1
	s_cmp_eq_u32 s85, 12
	s_cselect_b32 s93, s13, s90
	s_cselect_b32 s92, s22, s87
	s_cselect_b32 s91, s7, s79
	s_cselect_b32 s90, s23, s34
	s_cmp_gt_u32 s85, 13
	s_barrier
	s_cbranch_scc0 .LBB0_1209
	s_waitcnt lgkmcnt(0)
	v_mov_b32_e32 v131, v252
	s_lshl_b32 s7, s86, 8
	v_and_b32_e32 v130, 63, v131
	v_or_b32_e32 v0, s72, v130
	v_lshrrev_b32_e32 v0, 1, v0
	v_and_or_b32 v132, v0, 63, s73
	v_add_u32_e32 v134, s7, v132
	v_ashrrev_i32_e32 v135, 31, v134
	v_and_b32_e32 v142, 1, v131
	v_lshlrev_b64 v[134:135], 6, v[134:135]
	v_lshl_add_u64 v[134:135], s[82:83], 0, v[134:135]
	v_lshlrev_b32_e32 v0, 5, v142
	v_lshl_add_u64 v[138:139], v[134:135], 0, v[0:1]
	global_load_dwordx4 v[134:137], v[138:139], off
	s_nop 0
	global_load_dwordx4 v[138:141], v[138:139], off offset:16
	v_lshlrev_b32_e32 v0, 2, v130
	v_cmp_eq_u32_e32 vcc, 0, v142
	s_waitcnt vmcnt(0)
	v_add_f32_e32 v133, v134, v135
	v_add_f32_e32 v134, v136, v137
	v_add_f32_e32 v135, v138, v139
	v_add_f32_e32 v136, v140, v141
	v_add_f32_e32 v133, v133, v134
	v_add_f32_e32 v134, v135, v136
	v_add_f32_e32 v133, v133, v134
	v_xor_b32_e32 v134, 4, v0
	ds_bpermute_b32 v134, v134, v133
	s_and_saveexec_b64 s[22:23], vcc
	s_cbranch_execz .LBB0_1212
	s_waitcnt lgkmcnt(0)
	v_add_f32_e32 v133, v133, v134
	v_fmamk_f32 v133, v133, 0x3a800000, v224
	s_mov_b32 s13, 0x800000
	v_mul_f32_e32 v134, 0x4b800000, v133
	v_cmp_gt_f32_e32 vcc, s13, v133
	v_lshl_add_u32 v132, v132, 2, 0
	v_add_u32_e32 v132, 0x20000, v132
	v_cndmask_b32_e32 v133, v133, v134, vcc
	v_rsq_f32_e32 v133, v133
	s_nop 0
	v_mul_f32_e32 v134, 0x45800000, v133
	v_cndmask_b32_e32 v133, v133, v134, vcc
	ds_write_b32 v132, v133
